# converted bf16 weights stored with default cache policy instead of nt (stay in L2/MALL for the GEMM that reads them)
# speedup vs baseline: 1.0195x; 1.0043x over previous
.LBB0_22:
	v_lshl_add_u64 v[40:41], v[24:25], 0, s[10:11]
	global_load_dword v64, v[40:41], off nt
	v_lshl_add_u64 v[42:43], v[22:23], 0, s[10:11]
	global_load_dword v65, v[42:43], off nt
	v_lshl_add_u64 v[40:41], v[20:21], 0, s[10:11]
	global_load_dword v66, v[40:41], off nt
	v_lshl_add_u64 v[42:43], v[18:19], 0, s[10:11]
	global_load_dword v67, v[42:43], off nt
	v_lshl_add_u64 v[40:41], v[16:17], 0, s[10:11]
	global_load_dword v100, v[40:41], off nt
	v_lshl_add_u64 v[42:43], v[14:15], 0, s[10:11]
	global_load_dword v101, v[42:43], off nt
	v_lshl_add_u64 v[40:41], v[12:13], 0, s[10:11]
	global_load_dword v102, v[40:41], off nt
	v_lshl_add_u64 v[42:43], v[10:11], 0, s[10:11]
	global_load_dword v103, v[42:43], off nt
	s_add_u32 s10, s10, 0x20000
	s_addc_u32 s11, s11, 0
	v_lshl_add_u64 v[40:41], v[24:25], 0, s[10:11]
	global_load_dword v104, v[40:41], off nt
	v_lshl_add_u64 v[42:43], v[22:23], 0, s[10:11]
	global_load_dword v105, v[42:43], off nt
	v_lshl_add_u64 v[40:41], v[20:21], 0, s[10:11]
	global_load_dword v106, v[40:41], off nt
	v_lshl_add_u64 v[42:43], v[18:19], 0, s[10:11]
	global_load_dword v107, v[42:43], off nt
	v_lshl_add_u64 v[40:41], v[16:17], 0, s[10:11]
	global_load_dword v108, v[40:41], off nt
	v_lshl_add_u64 v[42:43], v[14:15], 0, s[10:11]
	global_load_dword v109, v[42:43], off nt
	v_lshl_add_u64 v[40:41], v[12:13], 0, s[10:11]
	global_load_dword v110, v[40:41], off nt
	v_lshl_add_u64 v[42:43], v[10:11], 0, s[10:11]
	global_load_dword v111, v[42:43], off nt
	s_add_u32 s10, s10, 0x20000
	s_addc_u32 s11, s11, 0
	v_lshl_add_u64 v[40:41], v[24:25], 0, s[10:11]
	global_load_dword v112, v[40:41], off nt
	v_lshl_add_u64 v[42:43], v[22:23], 0, s[10:11]
	global_load_dword v113, v[42:43], off nt
	v_lshl_add_u64 v[40:41], v[20:21], 0, s[10:11]
	global_load_dword v114, v[40:41], off nt
	v_lshl_add_u64 v[42:43], v[18:19], 0, s[10:11]
	global_load_dword v115, v[42:43], off nt
	v_lshl_add_u64 v[40:41], v[16:17], 0, s[10:11]
	global_load_dword v116, v[40:41], off nt
	v_lshl_add_u64 v[42:43], v[14:15], 0, s[10:11]
	global_load_dword v117, v[42:43], off nt
	v_lshl_add_u64 v[40:41], v[12:13], 0, s[10:11]
	global_load_dword v118, v[40:41], off nt
	v_lshl_add_u64 v[42:43], v[10:11], 0, s[10:11]
	global_load_dword v119, v[42:43], off nt
	s_add_u32 s10, s10, 0x20000
	s_addc_u32 s11, s11, 0
	v_lshl_add_u64 v[40:41], v[24:25], 0, s[10:11]
	global_load_dword v120, v[40:41], off nt
	v_lshl_add_u64 v[42:43], v[22:23], 0, s[10:11]
	global_load_dword v121, v[42:43], off nt
	v_lshl_add_u64 v[40:41], v[20:21], 0, s[10:11]
	global_load_dword v122, v[40:41], off nt
	v_lshl_add_u64 v[42:43], v[18:19], 0, s[10:11]
	global_load_dword v123, v[42:43], off nt
	v_lshl_add_u64 v[40:41], v[16:17], 0, s[10:11]
	global_load_dword v124, v[40:41], off nt
	v_lshl_add_u64 v[42:43], v[14:15], 0, s[10:11]
	global_load_dword v125, v[42:43], off nt
	v_lshl_add_u64 v[40:41], v[12:13], 0, s[10:11]
	global_load_dword v126, v[40:41], off nt
	v_lshl_add_u64 v[42:43], v[10:11], 0, s[10:11]
	global_load_dword v127, v[42:43], off nt
	s_add_u32 s10, s10, 0x20000
	s_addc_u32 s11, s11, 0
	v_add_u32_e32 v40, 0x400, v2
	s_waitcnt vmcnt(30)
	ds_write2_b32 v2, v64, v65 offset1:66
	s_waitcnt vmcnt(28)
	ds_write2_b32 v2, v66, v67 offset0:132 offset1:198
	s_waitcnt vmcnt(26)
	ds_write2_b32 v40, v100, v101 offset0:8 offset1:74
	s_waitcnt vmcnt(24)
	ds_write2_b32 v40, v102, v103 offset0:140 offset1:206
	v_add_u32_e32 v2, 0x840, v2
	v_add_u32_e32 v40, 0x400, v2
	s_waitcnt vmcnt(22)
	ds_write2_b32 v2, v104, v105 offset1:66
	s_waitcnt vmcnt(20)
	ds_write2_b32 v2, v106, v107 offset0:132 offset1:198
	s_waitcnt vmcnt(18)
	ds_write2_b32 v40, v108, v109 offset0:8 offset1:74
	s_waitcnt vmcnt(16)
	ds_write2_b32 v40, v110, v111 offset0:140 offset1:206
	v_add_u32_e32 v2, 0x840, v2
	v_add_u32_e32 v40, 0x400, v2
	s_waitcnt vmcnt(14)
	ds_write2_b32 v2, v112, v113 offset1:66
	s_waitcnt vmcnt(12)
	ds_write2_b32 v2, v114, v115 offset0:132 offset1:198
	s_waitcnt vmcnt(10)
	ds_write2_b32 v40, v116, v117 offset0:8 offset1:74
	s_waitcnt vmcnt(8)
	ds_write2_b32 v40, v118, v119 offset0:140 offset1:206
	v_add_u32_e32 v2, 0x840, v2
	v_add_u32_e32 v40, 0x400, v2
	s_waitcnt vmcnt(6)
	ds_write2_b32 v2, v120, v121 offset1:66
	s_waitcnt vmcnt(4)
	ds_write2_b32 v2, v122, v123 offset0:132 offset1:198
	s_waitcnt vmcnt(2)
	ds_write2_b32 v40, v124, v125 offset0:8 offset1:74
	s_waitcnt vmcnt(0)
	ds_write2_b32 v40, v126, v127 offset0:140 offset1:206
	v_add_u32_e32 v2, 0x840, v2
	s_waitcnt lgkmcnt(0)
	s_add_i32 s8, s17, 0xe800
	s_lshl_b32 s10, s17, 5
	ds_read2_b32 v[14:15], v28 offset0:33 offset1:41
	ds_read2_b32 v[16:17], v28 offset1:8
	ds_read2_b32 v[18:19], v28 offset0:66 offset1:74
	ds_read2_b32 v[20:21], v28 offset0:99 offset1:107
	ds_read2_b32 v[22:23], v28 offset0:132 offset1:140
	ds_read2_b32 v[24:25], v28 offset0:165 offset1:173
	ds_read2_b32 v[40:41], v28 offset0:198 offset1:206
	ds_read2_b32 v[42:43], v28 offset0:231 offset1:239
	s_and_b32 s8, s8, 0xffc0
	s_and_b32 s10, s10, 0x7e0
	s_lshl_b32 s8, s8, 1
	v_or_b32_e32 v2, s10, v27
	v_lshl_add_u64 v[44:45], v[6:7], 0, s[8:9]
	v_lshlrev_b32_e32 v2, 12, v2
	v_lshl_add_u64 v[46:47], v[44:45], 0, v[2:3]
	s_waitcnt lgkmcnt(6)
	v_cvt_pk_bf16_f32 v10, v16, v14
	s_waitcnt lgkmcnt(4)
	v_cvt_pk_bf16_f32 v11, v18, v20
	s_waitcnt lgkmcnt(2)
	v_cvt_pk_bf16_f32 v12, v22, v24
	s_waitcnt lgkmcnt(0)
	v_cvt_pk_bf16_f32 v13, v40, v42
	global_store_dwordx4 v[46:47], v[10:13], off
	v_or_b32_e32 v2, s10, v29
	v_lshlrev_b32_e32 v2, 12, v2
	v_cvt_pk_bf16_f32 v10, v17, v15
	v_cvt_pk_bf16_f32 v11, v19, v21
	v_cvt_pk_bf16_f32 v12, v23, v25
	v_cvt_pk_bf16_f32 v13, v41, v43
	ds_read2_b32 v[16:17], v28 offset0:16 offset1:24
	ds_read2_b32 v[18:19], v28 offset0:49 offset1:57
	ds_read2_b32 v[20:21], v28 offset0:82 offset1:90
	ds_read2_b32 v[22:23], v28 offset0:115 offset1:123
	ds_read2_b32 v[24:25], v28 offset0:148 offset1:156
	ds_read2_b32 v[40:41], v28 offset0:181 offset1:189
	ds_read2_b32 v[42:43], v28 offset0:214 offset1:222
	ds_read2_b32 v[46:47], v28 offset0:247 offset1:255
	v_lshl_add_u64 v[14:15], v[44:45], 0, v[2:3]
	v_or_b32_e32 v2, s10, v30
	v_lshlrev_b32_e32 v2, 12, v2
	global_store_dwordx4 v[14:15], v[10:13], off
	v_lshl_add_u64 v[14:15], v[44:45], 0, v[2:3]
	v_or_b32_e32 v2, s10, v31
	v_lshlrev_b32_e32 v2, 12, v2
	s_waitcnt lgkmcnt(6)
	v_cvt_pk_bf16_f32 v10, v16, v18
	s_waitcnt lgkmcnt(4)
	v_cvt_pk_bf16_f32 v11, v20, v22
	s_waitcnt lgkmcnt(2)
	v_cvt_pk_bf16_f32 v12, v24, v40
	s_waitcnt lgkmcnt(0)
	v_cvt_pk_bf16_f32 v13, v42, v46
	global_store_dwordx4 v[14:15], v[10:13], off
	v_lshl_add_u64 v[14:15], v[44:45], 0, v[2:3]
	s_mov_b64 s[10:11], 0
	v_cvt_pk_bf16_f32 v10, v17, v19
	v_cvt_pk_bf16_f32 v11, v21, v23
	v_cvt_pk_bf16_f32 v12, v25, v41
	v_cvt_pk_bf16_f32 v13, v43, v47
	global_store_dwordx4 v[14:15], v[10:13], off
	s_waitcnt lgkmcnt(0)

.LBB0_30:
	v_lshl_add_u64 v[40:41], v[24:25], 0, s[12:13]
	global_load_dword v64, v[40:41], off nt
	v_lshl_add_u64 v[42:43], v[22:23], 0, s[12:13]
	global_load_dword v65, v[42:43], off nt
	v_lshl_add_u64 v[40:41], v[20:21], 0, s[12:13]
	global_load_dword v66, v[40:41], off nt
	v_lshl_add_u64 v[42:43], v[18:19], 0, s[12:13]
	global_load_dword v67, v[42:43], off nt
	v_lshl_add_u64 v[40:41], v[16:17], 0, s[12:13]
	global_load_dword v100, v[40:41], off nt
	v_lshl_add_u64 v[42:43], v[14:15], 0, s[12:13]
	global_load_dword v101, v[42:43], off nt
	v_lshl_add_u64 v[40:41], v[12:13], 0, s[12:13]
	global_load_dword v102, v[40:41], off nt
	v_lshl_add_u64 v[42:43], v[10:11], 0, s[12:13]
	global_load_dword v103, v[42:43], off nt
	s_add_u32 s12, s12, 0x60000
	s_addc_u32 s13, s13, 0
	v_lshl_add_u64 v[40:41], v[24:25], 0, s[12:13]
	global_load_dword v104, v[40:41], off nt
	v_lshl_add_u64 v[42:43], v[22:23], 0, s[12:13]
	global_load_dword v105, v[42:43], off nt
	v_lshl_add_u64 v[40:41], v[20:21], 0, s[12:13]
	global_load_dword v106, v[40:41], off nt
	v_lshl_add_u64 v[42:43], v[18:19], 0, s[12:13]
	global_load_dword v107, v[42:43], off nt
	v_lshl_add_u64 v[40:41], v[16:17], 0, s[12:13]
	global_load_dword v108, v[40:41], off nt
	v_lshl_add_u64 v[42:43], v[14:15], 0, s[12:13]
	global_load_dword v109, v[42:43], off nt
	v_lshl_add_u64 v[40:41], v[12:13], 0, s[12:13]
	global_load_dword v110, v[40:41], off nt
	v_lshl_add_u64 v[42:43], v[10:11], 0, s[12:13]
	global_load_dword v111, v[42:43], off nt
	s_add_u32 s12, s12, 0x60000
	s_addc_u32 s13, s13, 0
	v_lshl_add_u64 v[40:41], v[24:25], 0, s[12:13]
	global_load_dword v112, v[40:41], off nt
	v_lshl_add_u64 v[42:43], v[22:23], 0, s[12:13]
	global_load_dword v113, v[42:43], off nt
	v_lshl_add_u64 v[40:41], v[20:21], 0, s[12:13]
	global_load_dword v114, v[40:41], off nt
	v_lshl_add_u64 v[42:43], v[18:19], 0, s[12:13]
	global_load_dword v115, v[42:43], off nt
	v_lshl_add_u64 v[40:41], v[16:17], 0, s[12:13]
	global_load_dword v116, v[40:41], off nt
	v_lshl_add_u64 v[42:43], v[14:15], 0, s[12:13]
	global_load_dword v117, v[42:43], off nt
	v_lshl_add_u64 v[40:41], v[12:13], 0, s[12:13]
	global_load_dword v118, v[40:41], off nt
	v_lshl_add_u64 v[42:43], v[10:11], 0, s[12:13]
	global_load_dword v119, v[42:43], off nt
	s_add_u32 s12, s12, 0x60000
	s_addc_u32 s13, s13, 0
	v_lshl_add_u64 v[40:41], v[24:25], 0, s[12:13]
	global_load_dword v120, v[40:41], off nt
	v_lshl_add_u64 v[42:43], v[22:23], 0, s[12:13]
	global_load_dword v121, v[42:43], off nt
	v_lshl_add_u64 v[40:41], v[20:21], 0, s[12:13]
	global_load_dword v122, v[40:41], off nt
	v_lshl_add_u64 v[42:43], v[18:19], 0, s[12:13]
	global_load_dword v123, v[42:43], off nt
	v_lshl_add_u64 v[40:41], v[16:17], 0, s[12:13]
	global_load_dword v124, v[40:41], off nt
	v_lshl_add_u64 v[42:43], v[14:15], 0, s[12:13]
	global_load_dword v125, v[42:43], off nt
	v_lshl_add_u64 v[40:41], v[12:13], 0, s[12:13]
	global_load_dword v126, v[40:41], off nt
	v_lshl_add_u64 v[42:43], v[10:11], 0, s[12:13]
	global_load_dword v127, v[42:43], off nt
	s_add_u32 s12, s12, 0x60000
	s_addc_u32 s13, s13, 0
	v_add_u32_e32 v40, 0x400, v2
	s_waitcnt vmcnt(30)
	ds_write2_b32 v2, v64, v65 offset1:66
	s_waitcnt vmcnt(28)
	ds_write2_b32 v2, v66, v67 offset0:132 offset1:198
	s_waitcnt vmcnt(26)
	ds_write2_b32 v40, v100, v101 offset0:8 offset1:74
	s_waitcnt vmcnt(24)
	ds_write2_b32 v40, v102, v103 offset0:140 offset1:206
	v_add_u32_e32 v2, 0x840, v2
	v_add_u32_e32 v40, 0x400, v2
	s_waitcnt vmcnt(22)
	ds_write2_b32 v2, v104, v105 offset1:66
	s_waitcnt vmcnt(20)
	ds_write2_b32 v2, v106, v107 offset0:132 offset1:198
	s_waitcnt vmcnt(18)
	ds_write2_b32 v40, v108, v109 offset0:8 offset1:74
	s_waitcnt vmcnt(16)
	ds_write2_b32 v40, v110, v111 offset0:140 offset1:206
	v_add_u32_e32 v2, 0x840, v2
	v_add_u32_e32 v40, 0x400, v2
	s_waitcnt vmcnt(14)
	ds_write2_b32 v2, v112, v113 offset1:66
	s_waitcnt vmcnt(12)
	ds_write2_b32 v2, v114, v115 offset0:132 offset1:198
	s_waitcnt vmcnt(10)
	ds_write2_b32 v40, v116, v117 offset0:8 offset1:74
	s_waitcnt vmcnt(8)
	ds_write2_b32 v40, v118, v119 offset0:140 offset1:206
	v_add_u32_e32 v2, 0x840, v2
	v_add_u32_e32 v40, 0x400, v2
	s_waitcnt vmcnt(6)
	ds_write2_b32 v2, v120, v121 offset1:66
	s_waitcnt vmcnt(4)
	ds_write2_b32 v2, v122, v123 offset0:132 offset1:198
	s_waitcnt vmcnt(2)
	ds_write2_b32 v40, v124, v125 offset0:8 offset1:74
	s_waitcnt vmcnt(0)
	ds_write2_b32 v40, v126, v127 offset0:140 offset1:206
	v_add_u32_e32 v2, 0x840, v2
	s_waitcnt lgkmcnt(0)
	ds_read2_b32 v[14:15], v28 offset0:33 offset1:41
	ds_read2_b32 v[16:17], v28 offset1:8
	ds_read2_b32 v[18:19], v28 offset0:66 offset1:74
	ds_read2_b32 v[20:21], v28 offset0:99 offset1:107
	ds_read2_b32 v[22:23], v28 offset0:132 offset1:140
	ds_read2_b32 v[24:25], v28 offset0:165 offset1:173
	ds_read2_b32 v[40:41], v28 offset0:198 offset1:206
	ds_read2_b32 v[42:43], v28 offset0:231 offset1:239
	v_add_u32_e32 v46, s8, v27
	s_ashr_i32 s11, s10, 31
	v_ashrrev_i32_e32 v47, 31, v46
	v_lshl_add_u64 v[44:45], s[10:11], 1, v[4:5]
	v_lshlrev_b64 v[46:47], 12, v[46:47]
	s_waitcnt lgkmcnt(6)
	v_cvt_pk_bf16_f32 v10, v16, v14
	v_lshl_add_u64 v[46:47], v[44:45], 0, v[46:47]
	v_add_u32_e32 v14, s8, v29
	s_waitcnt lgkmcnt(4)
	v_cvt_pk_bf16_f32 v11, v18, v20
	s_waitcnt lgkmcnt(2)
	v_cvt_pk_bf16_f32 v12, v22, v24
	s_waitcnt lgkmcnt(0)
	v_cvt_pk_bf16_f32 v13, v40, v42
	global_store_dwordx4 v[46:47], v[10:13], off
	s_nop 1
	v_cvt_pk_bf16_f32 v10, v17, v15
	v_ashrrev_i32_e32 v15, 31, v14
	v_lshlrev_b64 v[14:15], 12, v[14:15]
	v_cvt_pk_bf16_f32 v11, v19, v21
	v_cvt_pk_bf16_f32 v12, v23, v25
	v_cvt_pk_bf16_f32 v13, v41, v43
	v_lshl_add_u64 v[14:15], v[44:45], 0, v[14:15]
	ds_read2_b32 v[16:17], v28 offset0:16 offset1:24
	ds_read2_b32 v[18:19], v28 offset0:49 offset1:57
	ds_read2_b32 v[20:21], v28 offset0:82 offset1:90
	ds_read2_b32 v[22:23], v28 offset0:115 offset1:123
	ds_read2_b32 v[24:25], v28 offset0:148 offset1:156
	ds_read2_b32 v[40:41], v28 offset0:181 offset1:189
	ds_read2_b32 v[42:43], v28 offset0:214 offset1:222
	ds_read2_b32 v[46:47], v28 offset0:247 offset1:255
	global_store_dwordx4 v[14:15], v[10:13], off
	v_add_u32_e32 v14, s8, v30
	v_ashrrev_i32_e32 v15, 31, v14
	v_lshlrev_b64 v[14:15], 12, v[14:15]
	v_lshl_add_u64 v[14:15], v[44:45], 0, v[14:15]
	s_waitcnt lgkmcnt(6)
	v_cvt_pk_bf16_f32 v10, v16, v18
	s_waitcnt lgkmcnt(4)
	v_cvt_pk_bf16_f32 v11, v20, v22
	s_waitcnt lgkmcnt(2)
	v_cvt_pk_bf16_f32 v12, v24, v40
	s_waitcnt lgkmcnt(0)
	v_cvt_pk_bf16_f32 v13, v42, v46
	global_store_dwordx4 v[14:15], v[10:13], off
	v_add_u32_e32 v14, s8, v31
	v_ashrrev_i32_e32 v15, 31, v14
	v_lshlrev_b64 v[14:15], 12, v[14:15]
	v_lshl_add_u64 v[14:15], v[44:45], 0, v[14:15]
	v_cvt_pk_bf16_f32 v10, v17, v19
	v_cvt_pk_bf16_f32 v11, v21, v23
	v_cvt_pk_bf16_f32 v12, v25, v41
	v_cvt_pk_bf16_f32 v13, v43, v47
	global_store_dwordx4 v[14:15], v[10:13], off
	s_waitcnt lgkmcnt(0)
	s_branch .LBB0_19

.LBB0_167:
	v_lshl_add_u64 v[48:49], v[30:31], 0, s[0:1]
	global_load_dword v64, v[48:49], off nt
	v_lshl_add_u64 v[48:49], v[28:29], 0, s[0:1]
	global_load_dword v65, v[48:49], off nt
	v_lshl_add_u64 v[48:49], v[26:27], 0, s[0:1]
	global_load_dword v66, v[48:49], off nt
	v_lshl_add_u64 v[48:49], v[24:25], 0, s[0:1]
	global_load_dword v67, v[48:49], off nt
	v_lshl_add_u64 v[48:49], v[22:23], 0, s[0:1]
	global_load_dword v100, v[48:49], off nt
	v_lshl_add_u64 v[48:49], v[20:21], 0, s[0:1]
	global_load_dword v101, v[48:49], off nt
	v_lshl_add_u64 v[48:49], v[18:19], 0, s[0:1]
	global_load_dword v102, v[48:49], off nt
	v_lshl_add_u64 v[48:49], v[16:17], 0, s[0:1]
	global_load_dword v103, v[48:49], off nt
	s_add_u32 s0, s0, 0x58000
	s_addc_u32 s1, s1, 0
	v_lshl_add_u64 v[48:49], v[30:31], 0, s[0:1]
	global_load_dword v104, v[48:49], off nt
	v_lshl_add_u64 v[48:49], v[28:29], 0, s[0:1]
	global_load_dword v105, v[48:49], off nt
	v_lshl_add_u64 v[48:49], v[26:27], 0, s[0:1]
	global_load_dword v106, v[48:49], off nt
	v_lshl_add_u64 v[48:49], v[24:25], 0, s[0:1]
	global_load_dword v107, v[48:49], off nt
	v_lshl_add_u64 v[48:49], v[22:23], 0, s[0:1]
	global_load_dword v108, v[48:49], off nt
	v_lshl_add_u64 v[48:49], v[20:21], 0, s[0:1]
	global_load_dword v109, v[48:49], off nt
	v_lshl_add_u64 v[48:49], v[18:19], 0, s[0:1]
	global_load_dword v110, v[48:49], off nt
	v_lshl_add_u64 v[48:49], v[16:17], 0, s[0:1]
	global_load_dword v111, v[48:49], off nt
	s_add_u32 s0, s0, 0x58000
	s_addc_u32 s1, s1, 0
	v_lshl_add_u64 v[48:49], v[30:31], 0, s[0:1]
	global_load_dword v112, v[48:49], off nt
	v_lshl_add_u64 v[48:49], v[28:29], 0, s[0:1]
	global_load_dword v113, v[48:49], off nt
	v_lshl_add_u64 v[48:49], v[26:27], 0, s[0:1]
	global_load_dword v114, v[48:49], off nt
	v_lshl_add_u64 v[48:49], v[24:25], 0, s[0:1]
	global_load_dword v115, v[48:49], off nt
	v_lshl_add_u64 v[48:49], v[22:23], 0, s[0:1]
	global_load_dword v116, v[48:49], off nt
	v_lshl_add_u64 v[48:49], v[20:21], 0, s[0:1]
	global_load_dword v117, v[48:49], off nt
	v_lshl_add_u64 v[48:49], v[18:19], 0, s[0:1]
	global_load_dword v118, v[48:49], off nt
	v_lshl_add_u64 v[48:49], v[16:17], 0, s[0:1]
	global_load_dword v119, v[48:49], off nt
	s_add_u32 s0, s0, 0x58000
	s_addc_u32 s1, s1, 0
	v_lshl_add_u64 v[48:49], v[30:31], 0, s[0:1]
	global_load_dword v120, v[48:49], off nt
	v_lshl_add_u64 v[48:49], v[28:29], 0, s[0:1]
	global_load_dword v121, v[48:49], off nt
	v_lshl_add_u64 v[48:49], v[26:27], 0, s[0:1]
	global_load_dword v122, v[48:49], off nt
	v_lshl_add_u64 v[48:49], v[24:25], 0, s[0:1]
	global_load_dword v123, v[48:49], off nt
	v_lshl_add_u64 v[48:49], v[22:23], 0, s[0:1]
	global_load_dword v124, v[48:49], off nt
	v_lshl_add_u64 v[48:49], v[20:21], 0, s[0:1]
	global_load_dword v125, v[48:49], off nt
	v_lshl_add_u64 v[48:49], v[18:19], 0, s[0:1]
	global_load_dword v126, v[48:49], off nt
	v_lshl_add_u64 v[48:49], v[16:17], 0, s[0:1]
	global_load_dword v127, v[48:49], off nt
	s_add_u32 s0, s0, 0x58000
	s_addc_u32 s1, s1, 0
	v_add_u32_e32 v50, 0x400, v46
	s_waitcnt vmcnt(30)
	ds_write2_b32 v46, v64, v65 offset1:66
	s_waitcnt vmcnt(28)
	ds_write2_b32 v46, v66, v67 offset0:132 offset1:198
	s_waitcnt vmcnt(26)
	ds_write2_b32 v50, v100, v101 offset0:8 offset1:74
	s_waitcnt vmcnt(24)
	ds_write2_b32 v50, v102, v103 offset0:140 offset1:206
	v_add_u32_e32 v46, 0x840, v46
	v_add_u32_e32 v50, 0x400, v46
	s_waitcnt vmcnt(22)
	ds_write2_b32 v46, v104, v105 offset1:66
	s_waitcnt vmcnt(20)
	ds_write2_b32 v46, v106, v107 offset0:132 offset1:198
	s_waitcnt vmcnt(18)
	ds_write2_b32 v50, v108, v109 offset0:8 offset1:74
	s_waitcnt vmcnt(16)
	ds_write2_b32 v50, v110, v111 offset0:140 offset1:206
	v_add_u32_e32 v46, 0x840, v46
	v_add_u32_e32 v50, 0x400, v46
	s_waitcnt vmcnt(14)
	ds_write2_b32 v46, v112, v113 offset1:66
	s_waitcnt vmcnt(12)
	ds_write2_b32 v46, v114, v115 offset0:132 offset1:198
	s_waitcnt vmcnt(10)
	ds_write2_b32 v50, v116, v117 offset0:8 offset1:74
	s_waitcnt vmcnt(8)
	ds_write2_b32 v50, v118, v119 offset0:140 offset1:206
	v_add_u32_e32 v46, 0x840, v46
	v_add_u32_e32 v50, 0x400, v46
	s_waitcnt vmcnt(6)
	ds_write2_b32 v46, v120, v121 offset1:66
	s_waitcnt vmcnt(4)
	ds_write2_b32 v46, v122, v123 offset0:132 offset1:198
	s_waitcnt vmcnt(2)
	ds_write2_b32 v50, v124, v125 offset0:8 offset1:74
	s_waitcnt vmcnt(0)
	ds_write2_b32 v50, v126, v127 offset0:140 offset1:206
	v_add_u32_e32 v46, 0x840, v46
	s_waitcnt lgkmcnt(0)
	ds_read2_b32 v[22:23], v34 offset0:33 offset1:41
	ds_read2_b32 v[24:25], v34 offset1:8
	s_lshl_b32 s0, s12, 6
	s_and_b32 s0, s0, 0x3f00
	s_and_b32 s1, s13, 0x60
	s_or_b32 s0, s0, s1
	ds_read2_b32 v[26:27], v34 offset0:66 offset1:74
	ds_read2_b32 v[28:29], v34 offset0:99 offset1:107
	ds_read2_b32 v[30:31], v34 offset0:132 offset1:140
	ds_read2_b32 v[46:47], v34 offset0:165 offset1:173
	ds_read2_b32 v[48:49], v34 offset0:198 offset1:206
	ds_read2_b32 v[50:51], v34 offset0:231 offset1:239
	s_bitset1_b32 s0, 7
	s_and_b32 s1, 0xffff, s5
	s_lshl_b32 s76, s1, 1
	s_waitcnt lgkmcnt(6)
	v_cvt_pk_bf16_f32 v16, v24, v22
	v_or_b32_e32 v22, s0, v33
	v_lshl_add_u64 v[20:21], v[2:3], 0, s[76:77]
	v_lshlrev_b32_e32 v144, 12, v22
	v_or_b32_e32 v22, s0, v35
	v_lshl_add_u64 v[52:53], v[20:21], 0, v[144:145]
	v_lshlrev_b32_e32 v144, 12, v22
	s_waitcnt lgkmcnt(4)
	v_cvt_pk_bf16_f32 v17, v26, v28
	s_waitcnt lgkmcnt(2)
	v_cvt_pk_bf16_f32 v18, v30, v46
	s_waitcnt lgkmcnt(0)
	v_cvt_pk_bf16_f32 v19, v48, v50
	global_store_dwordx4 v[52:53], v[16:19], off
	s_nop 1
	v_cvt_pk_bf16_f32 v16, v25, v23
	v_lshl_add_u64 v[22:23], v[20:21], 0, v[144:145]
	v_cvt_pk_bf16_f32 v17, v27, v29
	v_cvt_pk_bf16_f32 v18, v31, v47
	v_cvt_pk_bf16_f32 v19, v49, v51
	global_store_dwordx4 v[22:23], v[16:19], off
	ds_read2_b32 v[22:23], v34 offset0:16 offset1:24
	ds_read2_b32 v[24:25], v34 offset0:49 offset1:57
	ds_read2_b32 v[26:27], v34 offset0:82 offset1:90
	ds_read2_b32 v[28:29], v34 offset0:115 offset1:123
	ds_read2_b32 v[30:31], v34 offset0:148 offset1:156
	ds_read2_b32 v[46:47], v34 offset0:181 offset1:189
	ds_read2_b32 v[48:49], v34 offset0:214 offset1:222
	ds_read2_b32 v[50:51], v34 offset0:247 offset1:255
	s_waitcnt lgkmcnt(6)
	v_cvt_pk_bf16_f32 v16, v22, v24
	v_or_b32_e32 v22, s0, v36
	v_lshlrev_b32_e32 v144, 12, v22
	v_or_b32_e32 v22, s0, v37
	v_lshl_add_u64 v[52:53], v[20:21], 0, v[144:145]
	v_lshlrev_b32_e32 v144, 12, v22
	s_waitcnt lgkmcnt(4)
	v_cvt_pk_bf16_f32 v17, v26, v28
	s_waitcnt lgkmcnt(2)
	v_cvt_pk_bf16_f32 v18, v30, v46
	s_waitcnt lgkmcnt(0)
	v_cvt_pk_bf16_f32 v19, v48, v50
	v_lshl_add_u64 v[20:21], v[20:21], 0, v[144:145]
	global_store_dwordx4 v[52:53], v[16:19], off
	s_mov_b64 s[0:1], 0
	s_nop 0
	v_cvt_pk_bf16_f32 v16, v23, v25
	v_cvt_pk_bf16_f32 v17, v27, v29
	v_cvt_pk_bf16_f32 v18, v31, v47
	v_cvt_pk_bf16_f32 v19, v49, v51
	global_store_dwordx4 v[20:21], v[16:19], off
	s_waitcnt lgkmcnt(0)

.LBB0_171:
	v_lshl_add_u64 v[48:49], v[30:31], 0, s[0:1]
	global_load_dword v64, v[48:49], off nt
	v_lshl_add_u64 v[48:49], v[28:29], 0, s[0:1]
	global_load_dword v65, v[48:49], off nt
	v_lshl_add_u64 v[48:49], v[26:27], 0, s[0:1]
	global_load_dword v66, v[48:49], off nt
	v_lshl_add_u64 v[48:49], v[24:25], 0, s[0:1]
	global_load_dword v67, v[48:49], off nt
	v_lshl_add_u64 v[48:49], v[22:23], 0, s[0:1]
	global_load_dword v100, v[48:49], off nt
	v_lshl_add_u64 v[48:49], v[20:21], 0, s[0:1]
	global_load_dword v101, v[48:49], off nt
	v_lshl_add_u64 v[48:49], v[18:19], 0, s[0:1]
	global_load_dword v102, v[48:49], off nt
	v_lshl_add_u64 v[48:49], v[16:17], 0, s[0:1]
	global_load_dword v103, v[48:49], off nt
	s_add_u32 s0, s0, 0x58000
	s_addc_u32 s1, s1, 0
	v_lshl_add_u64 v[48:49], v[30:31], 0, s[0:1]
	global_load_dword v104, v[48:49], off nt
	v_lshl_add_u64 v[48:49], v[28:29], 0, s[0:1]
	global_load_dword v105, v[48:49], off nt
	v_lshl_add_u64 v[48:49], v[26:27], 0, s[0:1]
	global_load_dword v106, v[48:49], off nt
	v_lshl_add_u64 v[48:49], v[24:25], 0, s[0:1]
	global_load_dword v107, v[48:49], off nt
	v_lshl_add_u64 v[48:49], v[22:23], 0, s[0:1]
	global_load_dword v108, v[48:49], off nt
	v_lshl_add_u64 v[48:49], v[20:21], 0, s[0:1]
	global_load_dword v109, v[48:49], off nt
	v_lshl_add_u64 v[48:49], v[18:19], 0, s[0:1]
	global_load_dword v110, v[48:49], off nt
	v_lshl_add_u64 v[48:49], v[16:17], 0, s[0:1]
	global_load_dword v111, v[48:49], off nt
	s_add_u32 s0, s0, 0x58000
	s_addc_u32 s1, s1, 0
	v_lshl_add_u64 v[48:49], v[30:31], 0, s[0:1]
	global_load_dword v112, v[48:49], off nt
	v_lshl_add_u64 v[48:49], v[28:29], 0, s[0:1]
	global_load_dword v113, v[48:49], off nt
	v_lshl_add_u64 v[48:49], v[26:27], 0, s[0:1]
	global_load_dword v114, v[48:49], off nt
	v_lshl_add_u64 v[48:49], v[24:25], 0, s[0:1]
	global_load_dword v115, v[48:49], off nt
	v_lshl_add_u64 v[48:49], v[22:23], 0, s[0:1]
	global_load_dword v116, v[48:49], off nt
	v_lshl_add_u64 v[48:49], v[20:21], 0, s[0:1]
	global_load_dword v117, v[48:49], off nt
	v_lshl_add_u64 v[48:49], v[18:19], 0, s[0:1]
	global_load_dword v118, v[48:49], off nt
	v_lshl_add_u64 v[48:49], v[16:17], 0, s[0:1]
	global_load_dword v119, v[48:49], off nt
	s_add_u32 s0, s0, 0x58000
	s_addc_u32 s1, s1, 0
	v_lshl_add_u64 v[48:49], v[30:31], 0, s[0:1]
	global_load_dword v120, v[48:49], off nt
	v_lshl_add_u64 v[48:49], v[28:29], 0, s[0:1]
	global_load_dword v121, v[48:49], off nt
	v_lshl_add_u64 v[48:49], v[26:27], 0, s[0:1]
	global_load_dword v122, v[48:49], off nt
	v_lshl_add_u64 v[48:49], v[24:25], 0, s[0:1]
	global_load_dword v123, v[48:49], off nt
	v_lshl_add_u64 v[48:49], v[22:23], 0, s[0:1]
	global_load_dword v124, v[48:49], off nt
	v_lshl_add_u64 v[48:49], v[20:21], 0, s[0:1]
	global_load_dword v125, v[48:49], off nt
	v_lshl_add_u64 v[48:49], v[18:19], 0, s[0:1]
	global_load_dword v126, v[48:49], off nt
	v_lshl_add_u64 v[48:49], v[16:17], 0, s[0:1]
	global_load_dword v127, v[48:49], off nt
	s_add_u32 s0, s0, 0x58000
	s_addc_u32 s1, s1, 0
	v_add_u32_e32 v50, 0x400, v46
	s_waitcnt vmcnt(30)
	ds_write2_b32 v46, v64, v65 offset1:66
	s_waitcnt vmcnt(28)
	ds_write2_b32 v46, v66, v67 offset0:132 offset1:198
	s_waitcnt vmcnt(26)
	ds_write2_b32 v50, v100, v101 offset0:8 offset1:74
	s_waitcnt vmcnt(24)
	ds_write2_b32 v50, v102, v103 offset0:140 offset1:206
	v_add_u32_e32 v46, 0x840, v46
	v_add_u32_e32 v50, 0x400, v46
	s_waitcnt vmcnt(22)
	ds_write2_b32 v46, v104, v105 offset1:66
	s_waitcnt vmcnt(20)
	ds_write2_b32 v46, v106, v107 offset0:132 offset1:198
	s_waitcnt vmcnt(18)
	ds_write2_b32 v50, v108, v109 offset0:8 offset1:74
	s_waitcnt vmcnt(16)
	ds_write2_b32 v50, v110, v111 offset0:140 offset1:206
	v_add_u32_e32 v46, 0x840, v46
	v_add_u32_e32 v50, 0x400, v46
	s_waitcnt vmcnt(14)
	ds_write2_b32 v46, v112, v113 offset1:66
	s_waitcnt vmcnt(12)
	ds_write2_b32 v46, v114, v115 offset0:132 offset1:198
	s_waitcnt vmcnt(10)
	ds_write2_b32 v50, v116, v117 offset0:8 offset1:74
	s_waitcnt vmcnt(8)
	ds_write2_b32 v50, v118, v119 offset0:140 offset1:206
	v_add_u32_e32 v46, 0x840, v46
	v_add_u32_e32 v50, 0x400, v46
	s_waitcnt vmcnt(6)
	ds_write2_b32 v46, v120, v121 offset1:66
	s_waitcnt vmcnt(4)
	ds_write2_b32 v46, v122, v123 offset0:132 offset1:198
	s_waitcnt vmcnt(2)
	ds_write2_b32 v50, v124, v125 offset0:8 offset1:74
	s_waitcnt vmcnt(0)
	ds_write2_b32 v50, v126, v127 offset0:140 offset1:206
	v_add_u32_e32 v46, 0x840, v46
	s_waitcnt lgkmcnt(0)
	ds_read2_b32 v[22:23], v34 offset0:33 offset1:41
	ds_read2_b32 v[24:25], v34 offset1:8
	s_lshl_b32 s0, s12, 6
	s_and_b32 s1, s13, 0x60
	s_and_b32 s0, s0, 0x3f00
	ds_read2_b32 v[26:27], v34 offset0:66 offset1:74
	ds_read2_b32 v[28:29], v34 offset0:99 offset1:107
	ds_read2_b32 v[30:31], v34 offset0:132 offset1:140
	ds_read2_b32 v[46:47], v34 offset0:165 offset1:173
	ds_read2_b32 v[48:49], v34 offset0:198 offset1:206
	ds_read2_b32 v[50:51], v34 offset0:231 offset1:239
	s_or_b32 s0, s0, s1
	s_and_b32 s1, 0xffff, s5
	s_lshl_b32 s76, s1, 1
	s_waitcnt lgkmcnt(6)
	v_cvt_pk_bf16_f32 v16, v24, v22
	v_or_b32_e32 v22, s0, v33
	v_lshl_add_u64 v[20:21], v[2:3], 0, s[76:77]
	v_lshlrev_b32_e32 v144, 12, v22
	v_or_b32_e32 v22, s0, v35
	v_lshl_add_u64 v[52:53], v[20:21], 0, v[144:145]
	v_lshlrev_b32_e32 v144, 12, v22
	s_waitcnt lgkmcnt(4)
	v_cvt_pk_bf16_f32 v17, v26, v28
	s_waitcnt lgkmcnt(2)
	v_cvt_pk_bf16_f32 v18, v30, v46
	s_waitcnt lgkmcnt(0)
	v_cvt_pk_bf16_f32 v19, v48, v50
	global_store_dwordx4 v[52:53], v[16:19], off
	s_nop 1
	v_cvt_pk_bf16_f32 v16, v25, v23
	v_lshl_add_u64 v[22:23], v[20:21], 0, v[144:145]
	v_cvt_pk_bf16_f32 v17, v27, v29
	v_cvt_pk_bf16_f32 v18, v31, v47
	v_cvt_pk_bf16_f32 v19, v49, v51
	global_store_dwordx4 v[22:23], v[16:19], off
	ds_read2_b32 v[22:23], v34 offset0:16 offset1:24
	ds_read2_b32 v[24:25], v34 offset0:49 offset1:57
	ds_read2_b32 v[26:27], v34 offset0:82 offset1:90
	ds_read2_b32 v[28:29], v34 offset0:115 offset1:123
	ds_read2_b32 v[30:31], v34 offset0:148 offset1:156
	ds_read2_b32 v[46:47], v34 offset0:181 offset1:189
	ds_read2_b32 v[48:49], v34 offset0:214 offset1:222
	ds_read2_b32 v[50:51], v34 offset0:247 offset1:255
	s_waitcnt lgkmcnt(6)
	v_cvt_pk_bf16_f32 v16, v22, v24
	v_or_b32_e32 v22, s0, v36
	v_lshlrev_b32_e32 v144, 12, v22
	v_or_b32_e32 v22, s0, v37
	v_lshl_add_u64 v[52:53], v[20:21], 0, v[144:145]
	v_lshlrev_b32_e32 v144, 12, v22
	s_waitcnt lgkmcnt(4)
	v_cvt_pk_bf16_f32 v17, v26, v28
	s_waitcnt lgkmcnt(2)
	v_cvt_pk_bf16_f32 v18, v30, v46
	s_waitcnt lgkmcnt(0)
	v_cvt_pk_bf16_f32 v19, v48, v50
	v_lshl_add_u64 v[20:21], v[20:21], 0, v[144:145]
	global_store_dwordx4 v[52:53], v[16:19], off
	s_nop 1
	v_cvt_pk_bf16_f32 v16, v23, v25
	v_cvt_pk_bf16_f32 v17, v27, v29
	v_cvt_pk_bf16_f32 v18, v31, v47
	v_cvt_pk_bf16_f32 v19, v49, v51
	global_store_dwordx4 v[20:21], v[16:19], off
	s_waitcnt lgkmcnt(0)

.LBB0_176:
	v_lshl_add_u64 v[48:49], v[30:31], 0, s[0:1]
	global_load_dword v64, v[48:49], off nt
	v_lshl_add_u64 v[48:49], v[28:29], 0, s[0:1]
	global_load_dword v65, v[48:49], off nt
	v_lshl_add_u64 v[48:49], v[26:27], 0, s[0:1]
	global_load_dword v66, v[48:49], off nt
	v_lshl_add_u64 v[48:49], v[24:25], 0, s[0:1]
	global_load_dword v67, v[48:49], off nt
	v_lshl_add_u64 v[48:49], v[22:23], 0, s[0:1]
	global_load_dword v100, v[48:49], off nt
	v_lshl_add_u64 v[48:49], v[20:21], 0, s[0:1]
	global_load_dword v101, v[48:49], off nt
	v_lshl_add_u64 v[48:49], v[18:19], 0, s[0:1]
	global_load_dword v102, v[48:49], off nt
	v_lshl_add_u64 v[48:49], v[16:17], 0, s[0:1]
	global_load_dword v103, v[48:49], off nt
	s_add_u32 s0, s0, 0x20000
	s_addc_u32 s1, s1, 0
	v_lshl_add_u64 v[48:49], v[30:31], 0, s[0:1]
	global_load_dword v104, v[48:49], off nt
	v_lshl_add_u64 v[48:49], v[28:29], 0, s[0:1]
	global_load_dword v105, v[48:49], off nt
	v_lshl_add_u64 v[48:49], v[26:27], 0, s[0:1]
	global_load_dword v106, v[48:49], off nt
	v_lshl_add_u64 v[48:49], v[24:25], 0, s[0:1]
	global_load_dword v107, v[48:49], off nt
	v_lshl_add_u64 v[48:49], v[22:23], 0, s[0:1]
	global_load_dword v108, v[48:49], off nt
	v_lshl_add_u64 v[48:49], v[20:21], 0, s[0:1]
	global_load_dword v109, v[48:49], off nt
	v_lshl_add_u64 v[48:49], v[18:19], 0, s[0:1]
	global_load_dword v110, v[48:49], off nt
	v_lshl_add_u64 v[48:49], v[16:17], 0, s[0:1]
	global_load_dword v111, v[48:49], off nt
	s_add_u32 s0, s0, 0x20000
	s_addc_u32 s1, s1, 0
	v_lshl_add_u64 v[48:49], v[30:31], 0, s[0:1]
	global_load_dword v112, v[48:49], off nt
	v_lshl_add_u64 v[48:49], v[28:29], 0, s[0:1]
	global_load_dword v113, v[48:49], off nt
	v_lshl_add_u64 v[48:49], v[26:27], 0, s[0:1]
	global_load_dword v114, v[48:49], off nt
	v_lshl_add_u64 v[48:49], v[24:25], 0, s[0:1]
	global_load_dword v115, v[48:49], off nt
	v_lshl_add_u64 v[48:49], v[22:23], 0, s[0:1]
	global_load_dword v116, v[48:49], off nt
	v_lshl_add_u64 v[48:49], v[20:21], 0, s[0:1]
	global_load_dword v117, v[48:49], off nt
	v_lshl_add_u64 v[48:49], v[18:19], 0, s[0:1]
	global_load_dword v118, v[48:49], off nt
	v_lshl_add_u64 v[48:49], v[16:17], 0, s[0:1]
	global_load_dword v119, v[48:49], off nt
	s_add_u32 s0, s0, 0x20000
	s_addc_u32 s1, s1, 0
	v_lshl_add_u64 v[48:49], v[30:31], 0, s[0:1]
	global_load_dword v120, v[48:49], off nt
	v_lshl_add_u64 v[48:49], v[28:29], 0, s[0:1]
	global_load_dword v121, v[48:49], off nt
	v_lshl_add_u64 v[48:49], v[26:27], 0, s[0:1]
	global_load_dword v122, v[48:49], off nt
	v_lshl_add_u64 v[48:49], v[24:25], 0, s[0:1]
	global_load_dword v123, v[48:49], off nt
	v_lshl_add_u64 v[48:49], v[22:23], 0, s[0:1]
	global_load_dword v124, v[48:49], off nt
	v_lshl_add_u64 v[48:49], v[20:21], 0, s[0:1]
	global_load_dword v125, v[48:49], off nt
	v_lshl_add_u64 v[48:49], v[18:19], 0, s[0:1]
	global_load_dword v126, v[48:49], off nt
	v_lshl_add_u64 v[48:49], v[16:17], 0, s[0:1]
	global_load_dword v127, v[48:49], off nt
	s_add_u32 s0, s0, 0x20000
	s_addc_u32 s1, s1, 0
	v_add_u32_e32 v50, 0x400, v46
	s_waitcnt vmcnt(30)
	ds_write2_b32 v46, v64, v65 offset1:66
	s_waitcnt vmcnt(28)
	ds_write2_b32 v46, v66, v67 offset0:132 offset1:198
	s_waitcnt vmcnt(26)
	ds_write2_b32 v50, v100, v101 offset0:8 offset1:74
	s_waitcnt vmcnt(24)
	ds_write2_b32 v50, v102, v103 offset0:140 offset1:206
	v_add_u32_e32 v46, 0x840, v46
	v_add_u32_e32 v50, 0x400, v46
	s_waitcnt vmcnt(22)
	ds_write2_b32 v46, v104, v105 offset1:66
	s_waitcnt vmcnt(20)
	ds_write2_b32 v46, v106, v107 offset0:132 offset1:198
	s_waitcnt vmcnt(18)
	ds_write2_b32 v50, v108, v109 offset0:8 offset1:74
	s_waitcnt vmcnt(16)
	ds_write2_b32 v50, v110, v111 offset0:140 offset1:206
	v_add_u32_e32 v46, 0x840, v46
	v_add_u32_e32 v50, 0x400, v46
	s_waitcnt vmcnt(14)
	ds_write2_b32 v46, v112, v113 offset1:66
	s_waitcnt vmcnt(12)
	ds_write2_b32 v46, v114, v115 offset0:132 offset1:198
	s_waitcnt vmcnt(10)
	ds_write2_b32 v50, v116, v117 offset0:8 offset1:74
	s_waitcnt vmcnt(8)
	ds_write2_b32 v50, v118, v119 offset0:140 offset1:206
	v_add_u32_e32 v46, 0x840, v46
	v_add_u32_e32 v50, 0x400, v46
	s_waitcnt vmcnt(6)
	ds_write2_b32 v46, v120, v121 offset1:66
	s_waitcnt vmcnt(4)
	ds_write2_b32 v46, v122, v123 offset0:132 offset1:198
	s_waitcnt vmcnt(2)
	ds_write2_b32 v50, v124, v125 offset0:8 offset1:74
	s_waitcnt vmcnt(0)
	ds_write2_b32 v50, v126, v127 offset0:140 offset1:206
	v_add_u32_e32 v46, 0x840, v46
	s_waitcnt lgkmcnt(0)
	ds_read2_b32 v[22:23], v34 offset0:33 offset1:41
	ds_read2_b32 v[24:25], v34 offset1:8
	s_add_i32 s0, s6, 0x8e00
	s_lshl_b32 s1, s6, 5
	ds_read2_b32 v[26:27], v34 offset0:66 offset1:74
	ds_read2_b32 v[28:29], v34 offset0:99 offset1:107
	ds_read2_b32 v[30:31], v34 offset0:132 offset1:140
	ds_read2_b32 v[46:47], v34 offset0:165 offset1:173
	ds_read2_b32 v[48:49], v34 offset0:198 offset1:206
	ds_read2_b32 v[50:51], v34 offset0:231 offset1:239
	s_and_b32 s0, s0, 0xffc0
	s_and_b32 s1, s1, 0x7e0
	s_lshl_b32 s76, s0, 1
	s_waitcnt lgkmcnt(6)
	v_cvt_pk_bf16_f32 v16, v24, v22
	v_or_b32_e32 v22, s1, v33
	v_lshl_add_u64 v[20:21], v[4:5], 0, s[76:77]
	v_lshlrev_b32_e32 v144, 12, v22
	v_or_b32_e32 v22, s1, v35
	v_lshl_add_u64 v[52:53], v[20:21], 0, v[144:145]
	v_lshlrev_b32_e32 v144, 12, v22
	s_waitcnt lgkmcnt(4)
	v_cvt_pk_bf16_f32 v17, v26, v28
	s_waitcnt lgkmcnt(2)
	v_cvt_pk_bf16_f32 v18, v30, v46
	s_waitcnt lgkmcnt(0)
	v_cvt_pk_bf16_f32 v19, v48, v50
	global_store_dwordx4 v[52:53], v[16:19], off
	s_nop 1
	v_cvt_pk_bf16_f32 v16, v25, v23
	v_lshl_add_u64 v[22:23], v[20:21], 0, v[144:145]
	v_cvt_pk_bf16_f32 v17, v27, v29
	v_cvt_pk_bf16_f32 v18, v31, v47
	v_cvt_pk_bf16_f32 v19, v49, v51
	global_store_dwordx4 v[22:23], v[16:19], off
	ds_read2_b32 v[22:23], v34 offset0:16 offset1:24
	ds_read2_b32 v[24:25], v34 offset0:49 offset1:57
	ds_read2_b32 v[26:27], v34 offset0:82 offset1:90
	ds_read2_b32 v[28:29], v34 offset0:115 offset1:123
	ds_read2_b32 v[30:31], v34 offset0:148 offset1:156
	ds_read2_b32 v[46:47], v34 offset0:181 offset1:189
	ds_read2_b32 v[48:49], v34 offset0:214 offset1:222
	ds_read2_b32 v[50:51], v34 offset0:247 offset1:255
	s_waitcnt lgkmcnt(6)
	v_cvt_pk_bf16_f32 v16, v22, v24
	v_or_b32_e32 v22, s1, v36
	v_lshlrev_b32_e32 v144, 12, v22
	v_or_b32_e32 v22, s1, v37
	v_lshl_add_u64 v[52:53], v[20:21], 0, v[144:145]
	v_lshlrev_b32_e32 v144, 12, v22
	s_waitcnt lgkmcnt(4)
	v_cvt_pk_bf16_f32 v17, v26, v28
	s_waitcnt lgkmcnt(2)
	v_cvt_pk_bf16_f32 v18, v30, v46
	s_waitcnt lgkmcnt(0)
	v_cvt_pk_bf16_f32 v19, v48, v50
	v_lshl_add_u64 v[20:21], v[20:21], 0, v[144:145]
	global_store_dwordx4 v[52:53], v[16:19], off
	s_nop 1
	v_cvt_pk_bf16_f32 v16, v23, v25
	v_cvt_pk_bf16_f32 v17, v27, v29
	v_cvt_pk_bf16_f32 v18, v31, v47
	v_cvt_pk_bf16_f32 v19, v49, v51
	global_store_dwordx4 v[20:21], v[16:19], off
	s_waitcnt lgkmcnt(0)

.LBB0_181:
	v_lshl_add_u64 v[48:49], v[30:31], 0, s[0:1]
	global_load_dword v64, v[48:49], off nt
	v_lshl_add_u64 v[48:49], v[28:29], 0, s[0:1]
	global_load_dword v65, v[48:49], off nt
	v_lshl_add_u64 v[48:49], v[26:27], 0, s[0:1]
	global_load_dword v66, v[48:49], off nt
	v_lshl_add_u64 v[48:49], v[24:25], 0, s[0:1]
	global_load_dword v67, v[48:49], off nt
	v_lshl_add_u64 v[48:49], v[22:23], 0, s[0:1]
	global_load_dword v100, v[48:49], off nt
	v_lshl_add_u64 v[48:49], v[20:21], 0, s[0:1]
	global_load_dword v101, v[48:49], off nt
	v_lshl_add_u64 v[48:49], v[18:19], 0, s[0:1]
	global_load_dword v102, v[48:49], off nt
	v_lshl_add_u64 v[48:49], v[16:17], 0, s[0:1]
	global_load_dword v103, v[48:49], off nt
	s_add_u32 s0, s0, 0x40000
	s_addc_u32 s1, s1, 0
	v_lshl_add_u64 v[48:49], v[30:31], 0, s[0:1]
	global_load_dword v104, v[48:49], off nt
	v_lshl_add_u64 v[48:49], v[28:29], 0, s[0:1]
	global_load_dword v105, v[48:49], off nt
	v_lshl_add_u64 v[48:49], v[26:27], 0, s[0:1]
	global_load_dword v106, v[48:49], off nt
	v_lshl_add_u64 v[48:49], v[24:25], 0, s[0:1]
	global_load_dword v107, v[48:49], off nt
	v_lshl_add_u64 v[48:49], v[22:23], 0, s[0:1]
	global_load_dword v108, v[48:49], off nt
	v_lshl_add_u64 v[48:49], v[20:21], 0, s[0:1]
	global_load_dword v109, v[48:49], off nt
	v_lshl_add_u64 v[48:49], v[18:19], 0, s[0:1]
	global_load_dword v110, v[48:49], off nt
	v_lshl_add_u64 v[48:49], v[16:17], 0, s[0:1]
	global_load_dword v111, v[48:49], off nt
	s_add_u32 s0, s0, 0x40000
	s_addc_u32 s1, s1, 0
	v_lshl_add_u64 v[48:49], v[30:31], 0, s[0:1]
	global_load_dword v112, v[48:49], off nt
	v_lshl_add_u64 v[48:49], v[28:29], 0, s[0:1]
	global_load_dword v113, v[48:49], off nt
	v_lshl_add_u64 v[48:49], v[26:27], 0, s[0:1]
	global_load_dword v114, v[48:49], off nt
	v_lshl_add_u64 v[48:49], v[24:25], 0, s[0:1]
	global_load_dword v115, v[48:49], off nt
	v_lshl_add_u64 v[48:49], v[22:23], 0, s[0:1]
	global_load_dword v116, v[48:49], off nt
	v_lshl_add_u64 v[48:49], v[20:21], 0, s[0:1]
	global_load_dword v117, v[48:49], off nt
	v_lshl_add_u64 v[48:49], v[18:19], 0, s[0:1]
	global_load_dword v118, v[48:49], off nt
	v_lshl_add_u64 v[48:49], v[16:17], 0, s[0:1]
	global_load_dword v119, v[48:49], off nt
	s_add_u32 s0, s0, 0x40000
	s_addc_u32 s1, s1, 0
	v_lshl_add_u64 v[48:49], v[30:31], 0, s[0:1]
	global_load_dword v120, v[48:49], off nt
	v_lshl_add_u64 v[48:49], v[28:29], 0, s[0:1]
	global_load_dword v121, v[48:49], off nt
	v_lshl_add_u64 v[48:49], v[26:27], 0, s[0:1]
	global_load_dword v122, v[48:49], off nt
	v_lshl_add_u64 v[48:49], v[24:25], 0, s[0:1]
	global_load_dword v123, v[48:49], off nt
	v_lshl_add_u64 v[48:49], v[22:23], 0, s[0:1]
	global_load_dword v124, v[48:49], off nt
	v_lshl_add_u64 v[48:49], v[20:21], 0, s[0:1]
	global_load_dword v125, v[48:49], off nt
	v_lshl_add_u64 v[48:49], v[18:19], 0, s[0:1]
	global_load_dword v126, v[48:49], off nt
	v_lshl_add_u64 v[48:49], v[16:17], 0, s[0:1]
	global_load_dword v127, v[48:49], off nt
	s_add_u32 s0, s0, 0x40000
	s_addc_u32 s1, s1, 0
	v_add_u32_e32 v50, 0x400, v46
	s_waitcnt vmcnt(30)
	ds_write2_b32 v46, v64, v65 offset1:66
	s_waitcnt vmcnt(28)
	ds_write2_b32 v46, v66, v67 offset0:132 offset1:198
	s_waitcnt vmcnt(26)
	ds_write2_b32 v50, v100, v101 offset0:8 offset1:74
	s_waitcnt vmcnt(24)
	ds_write2_b32 v50, v102, v103 offset0:140 offset1:206
	v_add_u32_e32 v46, 0x840, v46
	v_add_u32_e32 v50, 0x400, v46
	s_waitcnt vmcnt(22)
	ds_write2_b32 v46, v104, v105 offset1:66
	s_waitcnt vmcnt(20)
	ds_write2_b32 v46, v106, v107 offset0:132 offset1:198
	s_waitcnt vmcnt(18)
	ds_write2_b32 v50, v108, v109 offset0:8 offset1:74
	s_waitcnt vmcnt(16)
	ds_write2_b32 v50, v110, v111 offset0:140 offset1:206
	v_add_u32_e32 v46, 0x840, v46
	v_add_u32_e32 v50, 0x400, v46
	s_waitcnt vmcnt(14)
	ds_write2_b32 v46, v112, v113 offset1:66
	s_waitcnt vmcnt(12)
	ds_write2_b32 v46, v114, v115 offset0:132 offset1:198
	s_waitcnt vmcnt(10)
	ds_write2_b32 v50, v116, v117 offset0:8 offset1:74
	s_waitcnt vmcnt(8)
	ds_write2_b32 v50, v118, v119 offset0:140 offset1:206
	v_add_u32_e32 v46, 0x840, v46
	v_add_u32_e32 v50, 0x400, v46
	s_waitcnt vmcnt(6)
	ds_write2_b32 v46, v120, v121 offset1:66
	s_waitcnt vmcnt(4)
	ds_write2_b32 v46, v122, v123 offset0:132 offset1:198
	s_waitcnt vmcnt(2)
	ds_write2_b32 v50, v124, v125 offset0:8 offset1:74
	s_waitcnt vmcnt(0)
	ds_write2_b32 v50, v126, v127 offset0:140 offset1:206
	v_add_u32_e32 v46, 0x840, v46
	s_waitcnt lgkmcnt(0)
	ds_read2_b32 v[22:23], v34 offset0:33 offset1:41
	ds_read2_b32 v[24:25], v34 offset1:8
	s_lshl_b32 s1, s6, 5
	ds_read2_b32 v[26:27], v34 offset0:66 offset1:74
	ds_read2_b32 v[28:29], v34 offset0:99 offset1:107
	ds_read2_b32 v[30:31], v34 offset0:132 offset1:140
	ds_read2_b32 v[46:47], v34 offset0:165 offset1:173
	ds_read2_b32 v[48:49], v34 offset0:198 offset1:206
	ds_read2_b32 v[50:51], v34 offset0:231 offset1:239
	s_add_i32 s0, s6, 0x9e00
	s_and_b32 s1, s1, 0xfe0
	s_and_b32 s76, s0, 0xff80
	s_waitcnt lgkmcnt(6)
	v_cvt_pk_bf16_f32 v16, v24, v22
	v_or_b32_e32 v22, s1, v33
	v_lshl_add_u64 v[20:21], v[6:7], 0, s[76:77]
	v_lshlrev_b32_e32 v144, 12, v22
	v_or_b32_e32 v22, s1, v35
	v_lshl_add_u64 v[52:53], v[20:21], 0, v[144:145]
	v_lshlrev_b32_e32 v144, 12, v22
	s_waitcnt lgkmcnt(4)
	v_cvt_pk_bf16_f32 v17, v26, v28
	s_waitcnt lgkmcnt(2)
	v_cvt_pk_bf16_f32 v18, v30, v46
	s_waitcnt lgkmcnt(0)
	v_cvt_pk_bf16_f32 v19, v48, v50
	global_store_dwordx4 v[52:53], v[16:19], off
	s_nop 1
	v_cvt_pk_bf16_f32 v16, v25, v23
	v_lshl_add_u64 v[22:23], v[20:21], 0, v[144:145]
	v_cvt_pk_bf16_f32 v17, v27, v29
	v_cvt_pk_bf16_f32 v18, v31, v47
	v_cvt_pk_bf16_f32 v19, v49, v51
	global_store_dwordx4 v[22:23], v[16:19], off
	ds_read2_b32 v[22:23], v34 offset0:16 offset1:24
	ds_read2_b32 v[24:25], v34 offset0:49 offset1:57
	ds_read2_b32 v[26:27], v34 offset0:82 offset1:90
	ds_read2_b32 v[28:29], v34 offset0:115 offset1:123
	ds_read2_b32 v[30:31], v34 offset0:148 offset1:156
	ds_read2_b32 v[46:47], v34 offset0:181 offset1:189
	ds_read2_b32 v[48:49], v34 offset0:214 offset1:222
	ds_read2_b32 v[50:51], v34 offset0:247 offset1:255
	s_waitcnt lgkmcnt(6)
	v_cvt_pk_bf16_f32 v16, v22, v24
	v_or_b32_e32 v22, s1, v36
	v_lshlrev_b32_e32 v144, 12, v22
	v_or_b32_e32 v22, s1, v37
	v_lshl_add_u64 v[52:53], v[20:21], 0, v[144:145]
	v_lshlrev_b32_e32 v144, 12, v22
	s_waitcnt lgkmcnt(4)
	v_cvt_pk_bf16_f32 v17, v26, v28
	s_waitcnt lgkmcnt(2)
	v_cvt_pk_bf16_f32 v18, v30, v46
	s_waitcnt lgkmcnt(0)
	v_cvt_pk_bf16_f32 v19, v48, v50
	v_lshl_add_u64 v[20:21], v[20:21], 0, v[144:145]
	global_store_dwordx4 v[52:53], v[16:19], off
	s_nop 1
	v_cvt_pk_bf16_f32 v16, v23, v25
	v_cvt_pk_bf16_f32 v17, v27, v29
	v_cvt_pk_bf16_f32 v18, v31, v47
	v_cvt_pk_bf16_f32 v19, v49, v51
	global_store_dwordx4 v[20:21], v[16:19], off
	s_waitcnt lgkmcnt(0)

.LBB0_186:
	v_lshl_add_u64 v[48:49], v[30:31], 0, s[0:1]
	global_load_dword v64, v[48:49], off nt
	v_lshl_add_u64 v[48:49], v[28:29], 0, s[0:1]
	global_load_dword v65, v[48:49], off nt
	v_lshl_add_u64 v[48:49], v[26:27], 0, s[0:1]
	global_load_dword v66, v[48:49], off nt
	v_lshl_add_u64 v[48:49], v[24:25], 0, s[0:1]
	global_load_dword v67, v[48:49], off nt
	v_lshl_add_u64 v[48:49], v[22:23], 0, s[0:1]
	global_load_dword v100, v[48:49], off nt
	v_lshl_add_u64 v[48:49], v[20:21], 0, s[0:1]
	global_load_dword v101, v[48:49], off nt
	v_lshl_add_u64 v[48:49], v[18:19], 0, s[0:1]
	global_load_dword v102, v[48:49], off nt
	v_lshl_add_u64 v[48:49], v[16:17], 0, s[0:1]
	global_load_dword v103, v[48:49], off nt
	s_add_u32 s0, s0, 0x20000
	s_addc_u32 s1, s1, 0
	v_lshl_add_u64 v[48:49], v[30:31], 0, s[0:1]
	global_load_dword v104, v[48:49], off nt
	v_lshl_add_u64 v[48:49], v[28:29], 0, s[0:1]
	global_load_dword v105, v[48:49], off nt
	v_lshl_add_u64 v[48:49], v[26:27], 0, s[0:1]
	global_load_dword v106, v[48:49], off nt
	v_lshl_add_u64 v[48:49], v[24:25], 0, s[0:1]
	global_load_dword v107, v[48:49], off nt
	v_lshl_add_u64 v[48:49], v[22:23], 0, s[0:1]
	global_load_dword v108, v[48:49], off nt
	v_lshl_add_u64 v[48:49], v[20:21], 0, s[0:1]
	global_load_dword v109, v[48:49], off nt
	v_lshl_add_u64 v[48:49], v[18:19], 0, s[0:1]
	global_load_dword v110, v[48:49], off nt
	v_lshl_add_u64 v[48:49], v[16:17], 0, s[0:1]
	global_load_dword v111, v[48:49], off nt
	s_add_u32 s0, s0, 0x20000
	s_addc_u32 s1, s1, 0
	v_lshl_add_u64 v[48:49], v[30:31], 0, s[0:1]
	global_load_dword v112, v[48:49], off nt
	v_lshl_add_u64 v[48:49], v[28:29], 0, s[0:1]
	global_load_dword v113, v[48:49], off nt
	v_lshl_add_u64 v[48:49], v[26:27], 0, s[0:1]
	global_load_dword v114, v[48:49], off nt
	v_lshl_add_u64 v[48:49], v[24:25], 0, s[0:1]
	global_load_dword v115, v[48:49], off nt
	v_lshl_add_u64 v[48:49], v[22:23], 0, s[0:1]
	global_load_dword v116, v[48:49], off nt
	v_lshl_add_u64 v[48:49], v[20:21], 0, s[0:1]
	global_load_dword v117, v[48:49], off nt
	v_lshl_add_u64 v[48:49], v[18:19], 0, s[0:1]
	global_load_dword v118, v[48:49], off nt
	v_lshl_add_u64 v[48:49], v[16:17], 0, s[0:1]
	global_load_dword v119, v[48:49], off nt
	s_add_u32 s0, s0, 0x20000
	s_addc_u32 s1, s1, 0
	v_lshl_add_u64 v[48:49], v[30:31], 0, s[0:1]
	global_load_dword v120, v[48:49], off nt
	v_lshl_add_u64 v[48:49], v[28:29], 0, s[0:1]
	global_load_dword v121, v[48:49], off nt
	v_lshl_add_u64 v[48:49], v[26:27], 0, s[0:1]
	global_load_dword v122, v[48:49], off nt
	v_lshl_add_u64 v[48:49], v[24:25], 0, s[0:1]
	global_load_dword v123, v[48:49], off nt
	v_lshl_add_u64 v[48:49], v[22:23], 0, s[0:1]
	global_load_dword v124, v[48:49], off nt
	v_lshl_add_u64 v[48:49], v[20:21], 0, s[0:1]
	global_load_dword v125, v[48:49], off nt
	v_lshl_add_u64 v[48:49], v[18:19], 0, s[0:1]
	global_load_dword v126, v[48:49], off nt
	v_lshl_add_u64 v[48:49], v[16:17], 0, s[0:1]
	global_load_dword v127, v[48:49], off nt
	s_add_u32 s0, s0, 0x20000
	s_addc_u32 s1, s1, 0
	v_add_u32_e32 v50, 0x400, v46
	s_waitcnt vmcnt(30)
	ds_write2_b32 v46, v64, v65 offset1:66
	s_waitcnt vmcnt(28)
	ds_write2_b32 v46, v66, v67 offset0:132 offset1:198
	s_waitcnt vmcnt(26)
	ds_write2_b32 v50, v100, v101 offset0:8 offset1:74
	s_waitcnt vmcnt(24)
	ds_write2_b32 v50, v102, v103 offset0:140 offset1:206
	v_add_u32_e32 v46, 0x840, v46
	v_add_u32_e32 v50, 0x400, v46
	s_waitcnt vmcnt(22)
	ds_write2_b32 v46, v104, v105 offset1:66
	s_waitcnt vmcnt(20)
	ds_write2_b32 v46, v106, v107 offset0:132 offset1:198
	s_waitcnt vmcnt(18)
	ds_write2_b32 v50, v108, v109 offset0:8 offset1:74
	s_waitcnt vmcnt(16)
	ds_write2_b32 v50, v110, v111 offset0:140 offset1:206
	v_add_u32_e32 v46, 0x840, v46
	v_add_u32_e32 v50, 0x400, v46
	s_waitcnt vmcnt(14)
	ds_write2_b32 v46, v112, v113 offset1:66
	s_waitcnt vmcnt(12)
	ds_write2_b32 v46, v114, v115 offset0:132 offset1:198
	s_waitcnt vmcnt(10)
	ds_write2_b32 v50, v116, v117 offset0:8 offset1:74
	s_waitcnt vmcnt(8)
	ds_write2_b32 v50, v118, v119 offset0:140 offset1:206
	v_add_u32_e32 v46, 0x840, v46
	v_add_u32_e32 v50, 0x400, v46
	s_waitcnt vmcnt(6)
	ds_write2_b32 v46, v120, v121 offset1:66
	s_waitcnt vmcnt(4)
	ds_write2_b32 v46, v122, v123 offset0:132 offset1:198
	s_waitcnt vmcnt(2)
	ds_write2_b32 v50, v124, v125 offset0:8 offset1:74
	s_waitcnt vmcnt(0)
	ds_write2_b32 v50, v126, v127 offset0:140 offset1:206
	v_add_u32_e32 v46, 0x840, v46
	s_waitcnt lgkmcnt(0)
	ds_read2_b32 v[22:23], v34 offset0:33 offset1:41
	ds_read2_b32 v[24:25], v34 offset1:8
	s_lshl_b32 s1, s6, 5
	s_and_b32 s1, s1, 0x7e0
	s_add_i32 s0, s6, 0xb400
	ds_read2_b32 v[26:27], v34 offset0:66 offset1:74
	ds_read2_b32 v[28:29], v34 offset0:99 offset1:107
	s_waitcnt lgkmcnt(2)
	v_cvt_pk_bf16_f32 v16, v24, v22
	ds_read2_b32 v[30:31], v34 offset0:132 offset1:140
	ds_read2_b32 v[46:47], v34 offset0:165 offset1:173
	ds_read2_b32 v[48:49], v34 offset0:198 offset1:206
	ds_read2_b32 v[50:51], v34 offset0:231 offset1:239
	v_or_b32_e32 v22, s1, v33
	s_and_b32 s0, s0, 0xffc0
	v_mul_u32_u24_e32 v22, 0x1600, v22
	s_lshl_b32 s76, s0, 1
	v_lshlrev_b32_e32 v144, 1, v22
	v_or_b32_e32 v22, s1, v35
	v_lshl_add_u64 v[20:21], v[8:9], 0, s[76:77]
	v_mul_u32_u24_e32 v22, 0x1600, v22
	v_lshl_add_u64 v[52:53], v[20:21], 0, v[144:145]
	v_lshlrev_b32_e32 v144, 1, v22
	s_waitcnt lgkmcnt(4)
	v_cvt_pk_bf16_f32 v17, v26, v28
	s_waitcnt lgkmcnt(2)
	v_cvt_pk_bf16_f32 v18, v30, v46
	s_waitcnt lgkmcnt(0)
	v_cvt_pk_bf16_f32 v19, v48, v50
	global_store_dwordx4 v[52:53], v[16:19], off
	s_nop 1
	v_cvt_pk_bf16_f32 v16, v25, v23
	v_lshl_add_u64 v[22:23], v[20:21], 0, v[144:145]
	v_cvt_pk_bf16_f32 v17, v27, v29
	v_cvt_pk_bf16_f32 v18, v31, v47
	v_cvt_pk_bf16_f32 v19, v49, v51
	global_store_dwordx4 v[22:23], v[16:19], off
	ds_read2_b32 v[22:23], v34 offset0:16 offset1:24
	ds_read2_b32 v[24:25], v34 offset0:49 offset1:57
	s_waitcnt lgkmcnt(0)
	v_cvt_pk_bf16_f32 v16, v22, v24
	ds_read2_b32 v[26:27], v34 offset0:82 offset1:90
	ds_read2_b32 v[28:29], v34 offset0:115 offset1:123
	ds_read2_b32 v[30:31], v34 offset0:148 offset1:156
	ds_read2_b32 v[46:47], v34 offset0:181 offset1:189
	ds_read2_b32 v[48:49], v34 offset0:214 offset1:222
	ds_read2_b32 v[50:51], v34 offset0:247 offset1:255
	v_or_b32_e32 v22, s1, v36
	v_mul_u32_u24_e32 v22, 0x1600, v22
	v_lshlrev_b32_e32 v144, 1, v22
	v_or_b32_e32 v22, s1, v37
	v_mul_u32_u24_e32 v22, 0x1600, v22
	v_lshl_add_u64 v[52:53], v[20:21], 0, v[144:145]
	v_lshlrev_b32_e32 v144, 1, v22
	s_waitcnt lgkmcnt(4)
	v_cvt_pk_bf16_f32 v17, v26, v28
	s_waitcnt lgkmcnt(2)
	v_cvt_pk_bf16_f32 v18, v30, v46
	s_waitcnt lgkmcnt(0)
	v_cvt_pk_bf16_f32 v19, v48, v50
	v_lshl_add_u64 v[20:21], v[20:21], 0, v[144:145]
	global_store_dwordx4 v[52:53], v[16:19], off
	s_nop 1
	v_cvt_pk_bf16_f32 v16, v23, v25
	v_cvt_pk_bf16_f32 v17, v27, v29
	v_cvt_pk_bf16_f32 v18, v31, v47
	v_cvt_pk_bf16_f32 v19, v49, v51
	global_store_dwordx4 v[20:21], v[16:19], off
	s_waitcnt lgkmcnt(0)

.LBB0_191:
	v_lshl_add_u64 v[48:49], v[30:31], 0, s[0:1]
	global_load_dword v64, v[48:49], off nt
	v_lshl_add_u64 v[48:49], v[28:29], 0, s[0:1]
	global_load_dword v65, v[48:49], off nt
	v_lshl_add_u64 v[48:49], v[26:27], 0, s[0:1]
	global_load_dword v66, v[48:49], off nt
	v_lshl_add_u64 v[48:49], v[24:25], 0, s[0:1]
	global_load_dword v67, v[48:49], off nt
	v_lshl_add_u64 v[48:49], v[22:23], 0, s[0:1]
	global_load_dword v100, v[48:49], off nt
	v_lshl_add_u64 v[48:49], v[20:21], 0, s[0:1]
	global_load_dword v101, v[48:49], off nt
	v_lshl_add_u64 v[48:49], v[18:19], 0, s[0:1]
	global_load_dword v102, v[48:49], off nt
	v_lshl_add_u64 v[48:49], v[16:17], 0, s[0:1]
	global_load_dword v103, v[48:49], off nt
	s_add_u32 s0, s0, 0x58000
	s_addc_u32 s1, s1, 0
	v_lshl_add_u64 v[48:49], v[30:31], 0, s[0:1]
	global_load_dword v104, v[48:49], off nt
	v_lshl_add_u64 v[48:49], v[28:29], 0, s[0:1]
	global_load_dword v105, v[48:49], off nt
	v_lshl_add_u64 v[48:49], v[26:27], 0, s[0:1]
	global_load_dword v106, v[48:49], off nt
	v_lshl_add_u64 v[48:49], v[24:25], 0, s[0:1]
	global_load_dword v107, v[48:49], off nt
	v_lshl_add_u64 v[48:49], v[22:23], 0, s[0:1]
	global_load_dword v108, v[48:49], off nt
	v_lshl_add_u64 v[48:49], v[20:21], 0, s[0:1]
	global_load_dword v109, v[48:49], off nt
	v_lshl_add_u64 v[48:49], v[18:19], 0, s[0:1]
	global_load_dword v110, v[48:49], off nt
	v_lshl_add_u64 v[48:49], v[16:17], 0, s[0:1]
	global_load_dword v111, v[48:49], off nt
	s_add_u32 s0, s0, 0x58000
	s_addc_u32 s1, s1, 0
	v_lshl_add_u64 v[48:49], v[30:31], 0, s[0:1]
	global_load_dword v112, v[48:49], off nt
	v_lshl_add_u64 v[48:49], v[28:29], 0, s[0:1]
	global_load_dword v113, v[48:49], off nt
	v_lshl_add_u64 v[48:49], v[26:27], 0, s[0:1]
	global_load_dword v114, v[48:49], off nt
	v_lshl_add_u64 v[48:49], v[24:25], 0, s[0:1]
	global_load_dword v115, v[48:49], off nt
	v_lshl_add_u64 v[48:49], v[22:23], 0, s[0:1]
	global_load_dword v116, v[48:49], off nt
	v_lshl_add_u64 v[48:49], v[20:21], 0, s[0:1]
	global_load_dword v117, v[48:49], off nt
	v_lshl_add_u64 v[48:49], v[18:19], 0, s[0:1]
	global_load_dword v118, v[48:49], off nt
	v_lshl_add_u64 v[48:49], v[16:17], 0, s[0:1]
	global_load_dword v119, v[48:49], off nt
	s_add_u32 s0, s0, 0x58000
	s_addc_u32 s1, s1, 0
	v_lshl_add_u64 v[48:49], v[30:31], 0, s[0:1]
	global_load_dword v120, v[48:49], off nt
	v_lshl_add_u64 v[48:49], v[28:29], 0, s[0:1]
	global_load_dword v121, v[48:49], off nt
	v_lshl_add_u64 v[48:49], v[26:27], 0, s[0:1]
	global_load_dword v122, v[48:49], off nt
	v_lshl_add_u64 v[48:49], v[24:25], 0, s[0:1]
	global_load_dword v123, v[48:49], off nt
	v_lshl_add_u64 v[48:49], v[22:23], 0, s[0:1]
	global_load_dword v124, v[48:49], off nt
	v_lshl_add_u64 v[48:49], v[20:21], 0, s[0:1]
	global_load_dword v125, v[48:49], off nt
	v_lshl_add_u64 v[48:49], v[18:19], 0, s[0:1]
	global_load_dword v126, v[48:49], off nt
	v_lshl_add_u64 v[48:49], v[16:17], 0, s[0:1]
	global_load_dword v127, v[48:49], off nt
	s_add_u32 s0, s0, 0x58000
	s_addc_u32 s1, s1, 0
	v_add_u32_e32 v50, 0x400, v46
	s_waitcnt vmcnt(30)
	ds_write2_b32 v46, v64, v65 offset1:66
	s_waitcnt vmcnt(28)
	ds_write2_b32 v46, v66, v67 offset0:132 offset1:198
	s_waitcnt vmcnt(26)
	ds_write2_b32 v50, v100, v101 offset0:8 offset1:74
	s_waitcnt vmcnt(24)
	ds_write2_b32 v50, v102, v103 offset0:140 offset1:206
	v_add_u32_e32 v46, 0x840, v46
	v_add_u32_e32 v50, 0x400, v46
	s_waitcnt vmcnt(22)
	ds_write2_b32 v46, v104, v105 offset1:66
	s_waitcnt vmcnt(20)
	ds_write2_b32 v46, v106, v107 offset0:132 offset1:198
	s_waitcnt vmcnt(18)
	ds_write2_b32 v50, v108, v109 offset0:8 offset1:74
	s_waitcnt vmcnt(16)
	ds_write2_b32 v50, v110, v111 offset0:140 offset1:206
	v_add_u32_e32 v46, 0x840, v46
	v_add_u32_e32 v50, 0x400, v46
	s_waitcnt vmcnt(14)
	ds_write2_b32 v46, v112, v113 offset1:66
	s_waitcnt vmcnt(12)
	ds_write2_b32 v46, v114, v115 offset0:132 offset1:198
	s_waitcnt vmcnt(10)
	ds_write2_b32 v50, v116, v117 offset0:8 offset1:74
	s_waitcnt vmcnt(8)
	ds_write2_b32 v50, v118, v119 offset0:140 offset1:206
	v_add_u32_e32 v46, 0x840, v46
	v_add_u32_e32 v50, 0x400, v46
	s_waitcnt vmcnt(6)
	ds_write2_b32 v46, v120, v121 offset1:66
	s_waitcnt vmcnt(4)
	ds_write2_b32 v46, v122, v123 offset0:132 offset1:198
	s_waitcnt vmcnt(2)
	ds_write2_b32 v50, v124, v125 offset0:8 offset1:74
	s_waitcnt vmcnt(0)
	ds_write2_b32 v50, v126, v127 offset0:140 offset1:206
	v_add_u32_e32 v46, 0x840, v46
	s_waitcnt lgkmcnt(0)
	ds_read2_b32 v[22:23], v34 offset0:33 offset1:41
	ds_read2_b32 v[24:25], v34 offset1:8
	s_lshl_b32 s0, s12, 6
	s_and_b32 s0, s0, 0x3f00
	s_and_b32 s1, s13, 0x60
	s_or_b32 s0, s0, s1
	ds_read2_b32 v[26:27], v34 offset0:66 offset1:74
	ds_read2_b32 v[28:29], v34 offset0:99 offset1:107
	ds_read2_b32 v[30:31], v34 offset0:132 offset1:140
	ds_read2_b32 v[46:47], v34 offset0:165 offset1:173
	ds_read2_b32 v[48:49], v34 offset0:198 offset1:206
	ds_read2_b32 v[50:51], v34 offset0:231 offset1:239
	s_bitset1_b32 s0, 7
	s_and_b32 s1, 0xffff, s5
	s_lshl_b32 s76, s1, 1
	s_waitcnt lgkmcnt(6)
	v_cvt_pk_bf16_f32 v16, v24, v22
	v_or_b32_e32 v22, s0, v33
	v_lshl_add_u64 v[20:21], v[10:11], 0, s[76:77]
	v_lshlrev_b32_e32 v144, 12, v22
	v_or_b32_e32 v22, s0, v35
	v_lshl_add_u64 v[52:53], v[20:21], 0, v[144:145]
	v_lshlrev_b32_e32 v144, 12, v22
	s_waitcnt lgkmcnt(4)
	v_cvt_pk_bf16_f32 v17, v26, v28
	s_waitcnt lgkmcnt(2)
	v_cvt_pk_bf16_f32 v18, v30, v46
	s_waitcnt lgkmcnt(0)
	v_cvt_pk_bf16_f32 v19, v48, v50
	global_store_dwordx4 v[52:53], v[16:19], off
	s_nop 1
	v_cvt_pk_bf16_f32 v16, v25, v23
	v_lshl_add_u64 v[22:23], v[20:21], 0, v[144:145]
	v_cvt_pk_bf16_f32 v17, v27, v29
	v_cvt_pk_bf16_f32 v18, v31, v47
	v_cvt_pk_bf16_f32 v19, v49, v51
	global_store_dwordx4 v[22:23], v[16:19], off
	ds_read2_b32 v[22:23], v34 offset0:16 offset1:24
	ds_read2_b32 v[24:25], v34 offset0:49 offset1:57
	ds_read2_b32 v[26:27], v34 offset0:82 offset1:90
	ds_read2_b32 v[28:29], v34 offset0:115 offset1:123
	ds_read2_b32 v[30:31], v34 offset0:148 offset1:156
	ds_read2_b32 v[46:47], v34 offset0:181 offset1:189
	ds_read2_b32 v[48:49], v34 offset0:214 offset1:222
	ds_read2_b32 v[50:51], v34 offset0:247 offset1:255
	s_waitcnt lgkmcnt(6)
	v_cvt_pk_bf16_f32 v16, v22, v24
	v_or_b32_e32 v22, s0, v36
	v_lshlrev_b32_e32 v144, 12, v22
	v_or_b32_e32 v22, s0, v37
	v_lshl_add_u64 v[52:53], v[20:21], 0, v[144:145]
	v_lshlrev_b32_e32 v144, 12, v22
	s_waitcnt lgkmcnt(4)
	v_cvt_pk_bf16_f32 v17, v26, v28
	s_waitcnt lgkmcnt(2)
	v_cvt_pk_bf16_f32 v18, v30, v46
	s_waitcnt lgkmcnt(0)
	v_cvt_pk_bf16_f32 v19, v48, v50
	v_lshl_add_u64 v[20:21], v[20:21], 0, v[144:145]
	global_store_dwordx4 v[52:53], v[16:19], off
	s_nop 1
	v_cvt_pk_bf16_f32 v16, v23, v25
	v_cvt_pk_bf16_f32 v17, v27, v29
	v_cvt_pk_bf16_f32 v18, v31, v47
	v_cvt_pk_bf16_f32 v19, v49, v51
	global_store_dwordx4 v[20:21], v[16:19], off
	s_waitcnt lgkmcnt(0)

.LBB0_196:
	v_lshl_add_u64 v[48:49], v[30:31], 0, s[0:1]
	global_load_dword v64, v[48:49], off nt
	v_lshl_add_u64 v[48:49], v[28:29], 0, s[0:1]
	global_load_dword v65, v[48:49], off nt
	v_lshl_add_u64 v[48:49], v[26:27], 0, s[0:1]
	global_load_dword v66, v[48:49], off nt
	v_lshl_add_u64 v[48:49], v[24:25], 0, s[0:1]
	global_load_dword v67, v[48:49], off nt
	v_lshl_add_u64 v[48:49], v[22:23], 0, s[0:1]
	global_load_dword v100, v[48:49], off nt
	v_lshl_add_u64 v[48:49], v[20:21], 0, s[0:1]
	global_load_dword v101, v[48:49], off nt
	v_lshl_add_u64 v[48:49], v[18:19], 0, s[0:1]
	global_load_dword v102, v[48:49], off nt
	v_lshl_add_u64 v[48:49], v[16:17], 0, s[0:1]
	global_load_dword v103, v[48:49], off nt
	s_add_u32 s0, s0, 0x58000
	s_addc_u32 s1, s1, 0
	v_lshl_add_u64 v[48:49], v[30:31], 0, s[0:1]
	global_load_dword v104, v[48:49], off nt
	v_lshl_add_u64 v[48:49], v[28:29], 0, s[0:1]
	global_load_dword v105, v[48:49], off nt
	v_lshl_add_u64 v[48:49], v[26:27], 0, s[0:1]
	global_load_dword v106, v[48:49], off nt
	v_lshl_add_u64 v[48:49], v[24:25], 0, s[0:1]
	global_load_dword v107, v[48:49], off nt
	v_lshl_add_u64 v[48:49], v[22:23], 0, s[0:1]
	global_load_dword v108, v[48:49], off nt
	v_lshl_add_u64 v[48:49], v[20:21], 0, s[0:1]
	global_load_dword v109, v[48:49], off nt
	v_lshl_add_u64 v[48:49], v[18:19], 0, s[0:1]
	global_load_dword v110, v[48:49], off nt
	v_lshl_add_u64 v[48:49], v[16:17], 0, s[0:1]
	global_load_dword v111, v[48:49], off nt
	s_add_u32 s0, s0, 0x58000
	s_addc_u32 s1, s1, 0
	v_lshl_add_u64 v[48:49], v[30:31], 0, s[0:1]
	global_load_dword v112, v[48:49], off nt
	v_lshl_add_u64 v[48:49], v[28:29], 0, s[0:1]
	global_load_dword v113, v[48:49], off nt
	v_lshl_add_u64 v[48:49], v[26:27], 0, s[0:1]
	global_load_dword v114, v[48:49], off nt
	v_lshl_add_u64 v[48:49], v[24:25], 0, s[0:1]
	global_load_dword v115, v[48:49], off nt
	v_lshl_add_u64 v[48:49], v[22:23], 0, s[0:1]
	global_load_dword v116, v[48:49], off nt
	v_lshl_add_u64 v[48:49], v[20:21], 0, s[0:1]
	global_load_dword v117, v[48:49], off nt
	v_lshl_add_u64 v[48:49], v[18:19], 0, s[0:1]
	global_load_dword v118, v[48:49], off nt
	v_lshl_add_u64 v[48:49], v[16:17], 0, s[0:1]
	global_load_dword v119, v[48:49], off nt
	s_add_u32 s0, s0, 0x58000
	s_addc_u32 s1, s1, 0
	v_lshl_add_u64 v[48:49], v[30:31], 0, s[0:1]
	global_load_dword v120, v[48:49], off nt
	v_lshl_add_u64 v[48:49], v[28:29], 0, s[0:1]
	global_load_dword v121, v[48:49], off nt
	v_lshl_add_u64 v[48:49], v[26:27], 0, s[0:1]
	global_load_dword v122, v[48:49], off nt
	v_lshl_add_u64 v[48:49], v[24:25], 0, s[0:1]
	global_load_dword v123, v[48:49], off nt
	v_lshl_add_u64 v[48:49], v[22:23], 0, s[0:1]
	global_load_dword v124, v[48:49], off nt
	v_lshl_add_u64 v[48:49], v[20:21], 0, s[0:1]
	global_load_dword v125, v[48:49], off nt
	v_lshl_add_u64 v[48:49], v[18:19], 0, s[0:1]
	global_load_dword v126, v[48:49], off nt
	v_lshl_add_u64 v[48:49], v[16:17], 0, s[0:1]
	global_load_dword v127, v[48:49], off nt
	s_add_u32 s0, s0, 0x58000
	s_addc_u32 s1, s1, 0
	v_add_u32_e32 v50, 0x400, v46
	s_waitcnt vmcnt(30)
	ds_write2_b32 v46, v64, v65 offset1:66
	s_waitcnt vmcnt(28)
	ds_write2_b32 v46, v66, v67 offset0:132 offset1:198
	s_waitcnt vmcnt(26)
	ds_write2_b32 v50, v100, v101 offset0:8 offset1:74
	s_waitcnt vmcnt(24)
	ds_write2_b32 v50, v102, v103 offset0:140 offset1:206
	v_add_u32_e32 v46, 0x840, v46
	v_add_u32_e32 v50, 0x400, v46
	s_waitcnt vmcnt(22)
	ds_write2_b32 v46, v104, v105 offset1:66
	s_waitcnt vmcnt(20)
	ds_write2_b32 v46, v106, v107 offset0:132 offset1:198
	s_waitcnt vmcnt(18)
	ds_write2_b32 v50, v108, v109 offset0:8 offset1:74
	s_waitcnt vmcnt(16)
	ds_write2_b32 v50, v110, v111 offset0:140 offset1:206
	v_add_u32_e32 v46, 0x840, v46
	v_add_u32_e32 v50, 0x400, v46
	s_waitcnt vmcnt(14)
	ds_write2_b32 v46, v112, v113 offset1:66
	s_waitcnt vmcnt(12)
	ds_write2_b32 v46, v114, v115 offset0:132 offset1:198
	s_waitcnt vmcnt(10)
	ds_write2_b32 v50, v116, v117 offset0:8 offset1:74
	s_waitcnt vmcnt(8)
	ds_write2_b32 v50, v118, v119 offset0:140 offset1:206
	v_add_u32_e32 v46, 0x840, v46
	v_add_u32_e32 v50, 0x400, v46
	s_waitcnt vmcnt(6)
	ds_write2_b32 v46, v120, v121 offset1:66
	s_waitcnt vmcnt(4)
	ds_write2_b32 v46, v122, v123 offset0:132 offset1:198
	s_waitcnt vmcnt(2)
	ds_write2_b32 v50, v124, v125 offset0:8 offset1:74
	s_waitcnt vmcnt(0)
	ds_write2_b32 v50, v126, v127 offset0:140 offset1:206
	v_add_u32_e32 v46, 0x840, v46
	s_waitcnt lgkmcnt(0)
	ds_read2_b32 v[22:23], v34 offset0:33 offset1:41
	ds_read2_b32 v[24:25], v34 offset1:8
	s_lshl_b32 s0, s12, 6
	s_and_b32 s1, s13, 0x60
	s_and_b32 s0, s0, 0x3f00
	ds_read2_b32 v[26:27], v34 offset0:66 offset1:74
	ds_read2_b32 v[28:29], v34 offset0:99 offset1:107
	ds_read2_b32 v[30:31], v34 offset0:132 offset1:140
	ds_read2_b32 v[46:47], v34 offset0:165 offset1:173
	ds_read2_b32 v[48:49], v34 offset0:198 offset1:206
	ds_read2_b32 v[50:51], v34 offset0:231 offset1:239
	s_or_b32 s0, s0, s1
	s_and_b32 s1, 0xffff, s5
	s_lshl_b32 s76, s1, 1
	s_waitcnt lgkmcnt(6)
	v_cvt_pk_bf16_f32 v16, v24, v22
	v_or_b32_e32 v22, s0, v33
	v_lshl_add_u64 v[20:21], v[10:11], 0, s[76:77]
	v_lshlrev_b32_e32 v144, 12, v22
	v_or_b32_e32 v22, s0, v35
	v_lshl_add_u64 v[52:53], v[20:21], 0, v[144:145]
	v_lshlrev_b32_e32 v144, 12, v22
	s_waitcnt lgkmcnt(4)
	v_cvt_pk_bf16_f32 v17, v26, v28
	s_waitcnt lgkmcnt(2)
	v_cvt_pk_bf16_f32 v18, v30, v46
	s_waitcnt lgkmcnt(0)
	v_cvt_pk_bf16_f32 v19, v48, v50
	global_store_dwordx4 v[52:53], v[16:19], off
	s_nop 1
	v_cvt_pk_bf16_f32 v16, v25, v23
	v_lshl_add_u64 v[22:23], v[20:21], 0, v[144:145]
	v_cvt_pk_bf16_f32 v17, v27, v29
	v_cvt_pk_bf16_f32 v18, v31, v47
	v_cvt_pk_bf16_f32 v19, v49, v51
	global_store_dwordx4 v[22:23], v[16:19], off
	ds_read2_b32 v[22:23], v34 offset0:16 offset1:24
	ds_read2_b32 v[24:25], v34 offset0:49 offset1:57
	ds_read2_b32 v[26:27], v34 offset0:82 offset1:90
	ds_read2_b32 v[28:29], v34 offset0:115 offset1:123
	ds_read2_b32 v[30:31], v34 offset0:148 offset1:156
	ds_read2_b32 v[46:47], v34 offset0:181 offset1:189
	ds_read2_b32 v[48:49], v34 offset0:214 offset1:222
	ds_read2_b32 v[50:51], v34 offset0:247 offset1:255
	s_waitcnt lgkmcnt(6)
	v_cvt_pk_bf16_f32 v16, v22, v24
	v_or_b32_e32 v22, s0, v36
	v_lshlrev_b32_e32 v144, 12, v22
	v_or_b32_e32 v22, s0, v37
	v_lshl_add_u64 v[52:53], v[20:21], 0, v[144:145]
	v_lshlrev_b32_e32 v144, 12, v22
	s_waitcnt lgkmcnt(4)
	v_cvt_pk_bf16_f32 v17, v26, v28
	s_waitcnt lgkmcnt(2)
	v_cvt_pk_bf16_f32 v18, v30, v46
	s_waitcnt lgkmcnt(0)
	v_cvt_pk_bf16_f32 v19, v48, v50
	v_lshl_add_u64 v[20:21], v[20:21], 0, v[144:145]
	global_store_dwordx4 v[52:53], v[16:19], off
	s_nop 1
	v_cvt_pk_bf16_f32 v16, v23, v25
	v_cvt_pk_bf16_f32 v17, v27, v29
	v_cvt_pk_bf16_f32 v18, v31, v47
	v_cvt_pk_bf16_f32 v19, v49, v51
	global_store_dwordx4 v[20:21], v[16:19], off
	s_waitcnt lgkmcnt(0)

.LBB0_201:
	v_lshl_add_u64 v[48:49], v[30:31], 0, s[0:1]
	global_load_dword v64, v[48:49], off nt
	v_lshl_add_u64 v[48:49], v[28:29], 0, s[0:1]
	global_load_dword v65, v[48:49], off nt
	v_lshl_add_u64 v[48:49], v[26:27], 0, s[0:1]
	global_load_dword v66, v[48:49], off nt
	v_lshl_add_u64 v[48:49], v[24:25], 0, s[0:1]
	global_load_dword v67, v[48:49], off nt
	v_lshl_add_u64 v[48:49], v[22:23], 0, s[0:1]
	global_load_dword v100, v[48:49], off nt
	v_lshl_add_u64 v[48:49], v[20:21], 0, s[0:1]
	global_load_dword v101, v[48:49], off nt
	v_lshl_add_u64 v[48:49], v[18:19], 0, s[0:1]
	global_load_dword v102, v[48:49], off nt
	v_lshl_add_u64 v[48:49], v[16:17], 0, s[0:1]
	global_load_dword v103, v[48:49], off nt
	s_add_u32 s0, s0, 0x20000
	s_addc_u32 s1, s1, 0
	v_lshl_add_u64 v[48:49], v[30:31], 0, s[0:1]
	global_load_dword v104, v[48:49], off nt
	v_lshl_add_u64 v[48:49], v[28:29], 0, s[0:1]
	global_load_dword v105, v[48:49], off nt
	v_lshl_add_u64 v[48:49], v[26:27], 0, s[0:1]
	global_load_dword v106, v[48:49], off nt
	v_lshl_add_u64 v[48:49], v[24:25], 0, s[0:1]
	global_load_dword v107, v[48:49], off nt
	v_lshl_add_u64 v[48:49], v[22:23], 0, s[0:1]
	global_load_dword v108, v[48:49], off nt
	v_lshl_add_u64 v[48:49], v[20:21], 0, s[0:1]
	global_load_dword v109, v[48:49], off nt
	v_lshl_add_u64 v[48:49], v[18:19], 0, s[0:1]
	global_load_dword v110, v[48:49], off nt
	v_lshl_add_u64 v[48:49], v[16:17], 0, s[0:1]
	global_load_dword v111, v[48:49], off nt
	s_add_u32 s0, s0, 0x20000
	s_addc_u32 s1, s1, 0
	v_lshl_add_u64 v[48:49], v[30:31], 0, s[0:1]
	global_load_dword v112, v[48:49], off nt
	v_lshl_add_u64 v[48:49], v[28:29], 0, s[0:1]
	global_load_dword v113, v[48:49], off nt
	v_lshl_add_u64 v[48:49], v[26:27], 0, s[0:1]
	global_load_dword v114, v[48:49], off nt
	v_lshl_add_u64 v[48:49], v[24:25], 0, s[0:1]
	global_load_dword v115, v[48:49], off nt
	v_lshl_add_u64 v[48:49], v[22:23], 0, s[0:1]
	global_load_dword v116, v[48:49], off nt
	v_lshl_add_u64 v[48:49], v[20:21], 0, s[0:1]
	global_load_dword v117, v[48:49], off nt
	v_lshl_add_u64 v[48:49], v[18:19], 0, s[0:1]
	global_load_dword v118, v[48:49], off nt
	v_lshl_add_u64 v[48:49], v[16:17], 0, s[0:1]
	global_load_dword v119, v[48:49], off nt
	s_add_u32 s0, s0, 0x20000
	s_addc_u32 s1, s1, 0
	v_lshl_add_u64 v[48:49], v[30:31], 0, s[0:1]
	global_load_dword v120, v[48:49], off nt
	v_lshl_add_u64 v[48:49], v[28:29], 0, s[0:1]
	global_load_dword v121, v[48:49], off nt
	v_lshl_add_u64 v[48:49], v[26:27], 0, s[0:1]
	global_load_dword v122, v[48:49], off nt
	v_lshl_add_u64 v[48:49], v[24:25], 0, s[0:1]
	global_load_dword v123, v[48:49], off nt
	v_lshl_add_u64 v[48:49], v[22:23], 0, s[0:1]
	global_load_dword v124, v[48:49], off nt
	v_lshl_add_u64 v[48:49], v[20:21], 0, s[0:1]
	global_load_dword v125, v[48:49], off nt
	v_lshl_add_u64 v[48:49], v[18:19], 0, s[0:1]
	global_load_dword v126, v[48:49], off nt
	v_lshl_add_u64 v[48:49], v[16:17], 0, s[0:1]
	global_load_dword v127, v[48:49], off nt
	s_add_u32 s0, s0, 0x20000
	s_addc_u32 s1, s1, 0
	v_add_u32_e32 v50, 0x400, v46
	s_waitcnt vmcnt(30)
	ds_write2_b32 v46, v64, v65 offset1:66
	s_waitcnt vmcnt(28)
	ds_write2_b32 v46, v66, v67 offset0:132 offset1:198
	s_waitcnt vmcnt(26)
	ds_write2_b32 v50, v100, v101 offset0:8 offset1:74
	s_waitcnt vmcnt(24)
	ds_write2_b32 v50, v102, v103 offset0:140 offset1:206
	v_add_u32_e32 v46, 0x840, v46
	v_add_u32_e32 v50, 0x400, v46
	s_waitcnt vmcnt(22)
	ds_write2_b32 v46, v104, v105 offset1:66
	s_waitcnt vmcnt(20)
	ds_write2_b32 v46, v106, v107 offset0:132 offset1:198
	s_waitcnt vmcnt(18)
	ds_write2_b32 v50, v108, v109 offset0:8 offset1:74
	s_waitcnt vmcnt(16)
	ds_write2_b32 v50, v110, v111 offset0:140 offset1:206
	v_add_u32_e32 v46, 0x840, v46
	v_add_u32_e32 v50, 0x400, v46
	s_waitcnt vmcnt(14)
	ds_write2_b32 v46, v112, v113 offset1:66
	s_waitcnt vmcnt(12)
	ds_write2_b32 v46, v114, v115 offset0:132 offset1:198
	s_waitcnt vmcnt(10)
	ds_write2_b32 v50, v116, v117 offset0:8 offset1:74
	s_waitcnt vmcnt(8)
	ds_write2_b32 v50, v118, v119 offset0:140 offset1:206
	v_add_u32_e32 v46, 0x840, v46
	v_add_u32_e32 v50, 0x400, v46
	s_waitcnt vmcnt(6)
	ds_write2_b32 v46, v120, v121 offset1:66
	s_waitcnt vmcnt(4)
	ds_write2_b32 v46, v122, v123 offset0:132 offset1:198
	s_waitcnt vmcnt(2)
	ds_write2_b32 v50, v124, v125 offset0:8 offset1:74
	s_waitcnt vmcnt(0)
	ds_write2_b32 v50, v126, v127 offset0:140 offset1:206
	v_add_u32_e32 v46, 0x840, v46
	s_waitcnt lgkmcnt(0)
	ds_read2_b32 v[22:23], v34 offset0:33 offset1:41
	ds_read2_b32 v[24:25], v34 offset1:8
	s_add_i32 s0, s6, 0xe800
	s_lshl_b32 s1, s6, 5
	ds_read2_b32 v[26:27], v34 offset0:66 offset1:74
	ds_read2_b32 v[28:29], v34 offset0:99 offset1:107
	ds_read2_b32 v[30:31], v34 offset0:132 offset1:140
	ds_read2_b32 v[46:47], v34 offset0:165 offset1:173
	ds_read2_b32 v[48:49], v34 offset0:198 offset1:206
	ds_read2_b32 v[50:51], v34 offset0:231 offset1:239
	s_and_b32 s0, s0, 0xffc0
	s_and_b32 s1, s1, 0x7e0
	s_lshl_b32 s76, s0, 1
	s_waitcnt lgkmcnt(6)
	v_cvt_pk_bf16_f32 v16, v24, v22
	v_or_b32_e32 v22, s1, v33
	v_lshl_add_u64 v[20:21], v[12:13], 0, s[76:77]
	v_lshlrev_b32_e32 v144, 12, v22
	v_or_b32_e32 v22, s1, v35
	v_lshl_add_u64 v[52:53], v[20:21], 0, v[144:145]
	v_lshlrev_b32_e32 v144, 12, v22
	s_waitcnt lgkmcnt(4)
	v_cvt_pk_bf16_f32 v17, v26, v28
	s_waitcnt lgkmcnt(2)
	v_cvt_pk_bf16_f32 v18, v30, v46
	s_waitcnt lgkmcnt(0)
	v_cvt_pk_bf16_f32 v19, v48, v50
	global_store_dwordx4 v[52:53], v[16:19], off
	s_nop 1
	v_cvt_pk_bf16_f32 v16, v25, v23
	v_lshl_add_u64 v[22:23], v[20:21], 0, v[144:145]
	v_cvt_pk_bf16_f32 v17, v27, v29
	v_cvt_pk_bf16_f32 v18, v31, v47
	v_cvt_pk_bf16_f32 v19, v49, v51
	global_store_dwordx4 v[22:23], v[16:19], off
	ds_read2_b32 v[22:23], v34 offset0:16 offset1:24
	ds_read2_b32 v[24:25], v34 offset0:49 offset1:57
	ds_read2_b32 v[26:27], v34 offset0:82 offset1:90
	ds_read2_b32 v[28:29], v34 offset0:115 offset1:123
	ds_read2_b32 v[30:31], v34 offset0:148 offset1:156
	ds_read2_b32 v[46:47], v34 offset0:181 offset1:189
	ds_read2_b32 v[48:49], v34 offset0:214 offset1:222
	ds_read2_b32 v[50:51], v34 offset0:247 offset1:255
	s_waitcnt lgkmcnt(6)
	v_cvt_pk_bf16_f32 v16, v22, v24
	v_or_b32_e32 v22, s1, v36
	v_lshlrev_b32_e32 v144, 12, v22
	v_or_b32_e32 v22, s1, v37
	v_lshl_add_u64 v[52:53], v[20:21], 0, v[144:145]
	v_lshlrev_b32_e32 v144, 12, v22
	s_waitcnt lgkmcnt(4)
	v_cvt_pk_bf16_f32 v17, v26, v28
	s_waitcnt lgkmcnt(2)
	v_cvt_pk_bf16_f32 v18, v30, v46
	s_waitcnt lgkmcnt(0)
	v_cvt_pk_bf16_f32 v19, v48, v50
	v_lshl_add_u64 v[20:21], v[20:21], 0, v[144:145]
	global_store_dwordx4 v[52:53], v[16:19], off
	s_nop 1
	v_cvt_pk_bf16_f32 v16, v23, v25
	v_cvt_pk_bf16_f32 v17, v27, v29
	v_cvt_pk_bf16_f32 v18, v31, v47
	v_cvt_pk_bf16_f32 v19, v49, v51
	global_store_dwordx4 v[20:21], v[16:19], off
	s_waitcnt lgkmcnt(0)

.LBB0_210:
	v_lshl_add_u64 v[48:49], v[30:31], 0, s[4:5]
	global_load_dword v64, v[48:49], off nt
	v_lshl_add_u64 v[48:49], v[28:29], 0, s[4:5]
	global_load_dword v65, v[48:49], off nt
	v_lshl_add_u64 v[48:49], v[26:27], 0, s[4:5]
	global_load_dword v66, v[48:49], off nt
	v_lshl_add_u64 v[48:49], v[24:25], 0, s[4:5]
	global_load_dword v67, v[48:49], off nt
	v_lshl_add_u64 v[48:49], v[22:23], 0, s[4:5]
	global_load_dword v100, v[48:49], off nt
	v_lshl_add_u64 v[48:49], v[20:21], 0, s[4:5]
	global_load_dword v101, v[48:49], off nt
	v_lshl_add_u64 v[48:49], v[18:19], 0, s[4:5]
	global_load_dword v102, v[48:49], off nt
	v_lshl_add_u64 v[48:49], v[16:17], 0, s[4:5]
	global_load_dword v103, v[48:49], off nt
	s_add_u32 s4, s4, 0x60000
	s_addc_u32 s5, s5, 0
	v_lshl_add_u64 v[48:49], v[30:31], 0, s[4:5]
	global_load_dword v104, v[48:49], off nt
	v_lshl_add_u64 v[48:49], v[28:29], 0, s[4:5]
	global_load_dword v105, v[48:49], off nt
	v_lshl_add_u64 v[48:49], v[26:27], 0, s[4:5]
	global_load_dword v106, v[48:49], off nt
	v_lshl_add_u64 v[48:49], v[24:25], 0, s[4:5]
	global_load_dword v107, v[48:49], off nt
	v_lshl_add_u64 v[48:49], v[22:23], 0, s[4:5]
	global_load_dword v108, v[48:49], off nt
	v_lshl_add_u64 v[48:49], v[20:21], 0, s[4:5]
	global_load_dword v109, v[48:49], off nt
	v_lshl_add_u64 v[48:49], v[18:19], 0, s[4:5]
	global_load_dword v110, v[48:49], off nt
	v_lshl_add_u64 v[48:49], v[16:17], 0, s[4:5]
	global_load_dword v111, v[48:49], off nt
	s_add_u32 s4, s4, 0x60000
	s_addc_u32 s5, s5, 0
	v_lshl_add_u64 v[48:49], v[30:31], 0, s[4:5]
	global_load_dword v112, v[48:49], off nt
	v_lshl_add_u64 v[48:49], v[28:29], 0, s[4:5]
	global_load_dword v113, v[48:49], off nt
	v_lshl_add_u64 v[48:49], v[26:27], 0, s[4:5]
	global_load_dword v114, v[48:49], off nt
	v_lshl_add_u64 v[48:49], v[24:25], 0, s[4:5]
	global_load_dword v115, v[48:49], off nt
	v_lshl_add_u64 v[48:49], v[22:23], 0, s[4:5]
	global_load_dword v116, v[48:49], off nt
	v_lshl_add_u64 v[48:49], v[20:21], 0, s[4:5]
	global_load_dword v117, v[48:49], off nt
	v_lshl_add_u64 v[48:49], v[18:19], 0, s[4:5]
	global_load_dword v118, v[48:49], off nt
	v_lshl_add_u64 v[48:49], v[16:17], 0, s[4:5]
	global_load_dword v119, v[48:49], off nt
	s_add_u32 s4, s4, 0x60000
	s_addc_u32 s5, s5, 0
	v_lshl_add_u64 v[48:49], v[30:31], 0, s[4:5]
	global_load_dword v120, v[48:49], off nt
	v_lshl_add_u64 v[48:49], v[28:29], 0, s[4:5]
	global_load_dword v121, v[48:49], off nt
	v_lshl_add_u64 v[48:49], v[26:27], 0, s[4:5]
	global_load_dword v122, v[48:49], off nt
	v_lshl_add_u64 v[48:49], v[24:25], 0, s[4:5]
	global_load_dword v123, v[48:49], off nt
	v_lshl_add_u64 v[48:49], v[22:23], 0, s[4:5]
	global_load_dword v124, v[48:49], off nt
	v_lshl_add_u64 v[48:49], v[20:21], 0, s[4:5]
	global_load_dword v125, v[48:49], off nt
	v_lshl_add_u64 v[48:49], v[18:19], 0, s[4:5]
	global_load_dword v126, v[48:49], off nt
	v_lshl_add_u64 v[48:49], v[16:17], 0, s[4:5]
	global_load_dword v127, v[48:49], off nt
	s_add_u32 s4, s4, 0x60000
	s_addc_u32 s5, s5, 0
	v_add_u32_e32 v50, 0x400, v46
	s_waitcnt vmcnt(30)
	ds_write2_b32 v46, v64, v65 offset1:66
	s_waitcnt vmcnt(28)
	ds_write2_b32 v46, v66, v67 offset0:132 offset1:198
	s_waitcnt vmcnt(26)
	ds_write2_b32 v50, v100, v101 offset0:8 offset1:74
	s_waitcnt vmcnt(24)
	ds_write2_b32 v50, v102, v103 offset0:140 offset1:206
	v_add_u32_e32 v46, 0x840, v46
	v_add_u32_e32 v50, 0x400, v46
	s_waitcnt vmcnt(22)
	ds_write2_b32 v46, v104, v105 offset1:66
	s_waitcnt vmcnt(20)
	ds_write2_b32 v46, v106, v107 offset0:132 offset1:198
	s_waitcnt vmcnt(18)
	ds_write2_b32 v50, v108, v109 offset0:8 offset1:74
	s_waitcnt vmcnt(16)
	ds_write2_b32 v50, v110, v111 offset0:140 offset1:206
	v_add_u32_e32 v46, 0x840, v46
	v_add_u32_e32 v50, 0x400, v46
	s_waitcnt vmcnt(14)
	ds_write2_b32 v46, v112, v113 offset1:66
	s_waitcnt vmcnt(12)
	ds_write2_b32 v46, v114, v115 offset0:132 offset1:198
	s_waitcnt vmcnt(10)
	ds_write2_b32 v50, v116, v117 offset0:8 offset1:74
	s_waitcnt vmcnt(8)
	ds_write2_b32 v50, v118, v119 offset0:140 offset1:206
	v_add_u32_e32 v46, 0x840, v46
	v_add_u32_e32 v50, 0x400, v46
	s_waitcnt vmcnt(6)
	ds_write2_b32 v46, v120, v121 offset1:66
	s_waitcnt vmcnt(4)
	ds_write2_b32 v46, v122, v123 offset0:132 offset1:198
	s_waitcnt vmcnt(2)
	ds_write2_b32 v50, v124, v125 offset0:8 offset1:74
	s_waitcnt vmcnt(0)
	ds_write2_b32 v50, v126, v127 offset0:140 offset1:206
	v_add_u32_e32 v46, 0x840, v46
	s_waitcnt lgkmcnt(0)
	ds_read2_b32 v[22:23], v34 offset0:33 offset1:41
	ds_read2_b32 v[24:25], v34 offset1:8
	ds_read2_b32 v[26:27], v34 offset0:66 offset1:74
	ds_read2_b32 v[28:29], v34 offset0:99 offset1:107
	ds_read2_b32 v[30:31], v34 offset0:132 offset1:140
	ds_read2_b32 v[46:47], v34 offset0:165 offset1:173
	ds_read2_b32 v[48:49], v34 offset0:198 offset1:206
	ds_read2_b32 v[50:51], v34 offset0:231 offset1:239
	v_add_u32_e32 v52, s12, v33
	s_ashr_i32 s1, s0, 31
	v_ashrrev_i32_e32 v53, 31, v52
	v_lshl_add_u64 v[20:21], s[0:1], 1, v[0:1]
	v_lshlrev_b64 v[52:53], 12, v[52:53]
	s_waitcnt lgkmcnt(6)
	v_cvt_pk_bf16_f32 v16, v24, v22
	v_lshl_add_u64 v[52:53], v[20:21], 0, v[52:53]
	v_add_u32_e32 v22, s12, v35
	s_waitcnt lgkmcnt(4)
	v_cvt_pk_bf16_f32 v17, v26, v28
	s_waitcnt lgkmcnt(2)
	v_cvt_pk_bf16_f32 v18, v30, v46
	s_waitcnt lgkmcnt(0)
	v_cvt_pk_bf16_f32 v19, v48, v50
	global_store_dwordx4 v[52:53], v[16:19], off
	v_add_u32_e32 v52, s12, v36
	v_ashrrev_i32_e32 v53, 31, v52
	v_cvt_pk_bf16_f32 v16, v25, v23
	v_ashrrev_i32_e32 v23, 31, v22
	v_lshlrev_b64 v[22:23], 12, v[22:23]
	v_lshl_add_u64 v[22:23], v[20:21], 0, v[22:23]
	v_cvt_pk_bf16_f32 v17, v27, v29
	v_cvt_pk_bf16_f32 v18, v31, v47
	v_cvt_pk_bf16_f32 v19, v49, v51
	global_store_dwordx4 v[22:23], v[16:19], off
	ds_read2_b32 v[22:23], v34 offset0:16 offset1:24
	ds_read2_b32 v[24:25], v34 offset0:49 offset1:57
	ds_read2_b32 v[26:27], v34 offset0:82 offset1:90
	ds_read2_b32 v[28:29], v34 offset0:115 offset1:123
	ds_read2_b32 v[30:31], v34 offset0:148 offset1:156
	ds_read2_b32 v[46:47], v34 offset0:181 offset1:189
	ds_read2_b32 v[48:49], v34 offset0:214 offset1:222
	ds_read2_b32 v[50:51], v34 offset0:247 offset1:255
	v_lshlrev_b64 v[52:53], 12, v[52:53]
	s_waitcnt lgkmcnt(6)
	v_cvt_pk_bf16_f32 v16, v22, v24
	v_lshl_add_u64 v[52:53], v[20:21], 0, v[52:53]
	v_add_u32_e32 v22, s12, v37
	s_waitcnt lgkmcnt(4)
	v_cvt_pk_bf16_f32 v17, v26, v28
	s_waitcnt lgkmcnt(2)
	v_cvt_pk_bf16_f32 v18, v30, v46
	s_waitcnt lgkmcnt(0)
	v_cvt_pk_bf16_f32 v19, v48, v50
	global_store_dwordx4 v[52:53], v[16:19], off
	s_nop 1
	v_cvt_pk_bf16_f32 v16, v23, v25
	v_ashrrev_i32_e32 v23, 31, v22
	v_lshlrev_b64 v[22:23], 12, v[22:23]
	v_lshl_add_u64 v[20:21], v[20:21], 0, v[22:23]
	v_cvt_pk_bf16_f32 v17, v27, v29
	v_cvt_pk_bf16_f32 v18, v31, v47
	v_cvt_pk_bf16_f32 v19, v49, v51
	global_store_dwordx4 v[20:21], v[16:19], off
	s_waitcnt lgkmcnt(0)
	s_branch .LBB0_157

.LBB0_387:
	v_lshl_add_u64 v[40:41], v[22:23], 0, s[0:1]
	global_load_dword v64, v[40:41], off nt
	v_lshl_add_u64 v[42:43], v[20:21], 0, s[0:1]
	global_load_dword v65, v[42:43], off nt
	v_lshl_add_u64 v[40:41], v[18:19], 0, s[0:1]
	global_load_dword v66, v[40:41], off nt
	v_lshl_add_u64 v[42:43], v[16:17], 0, s[0:1]
	global_load_dword v67, v[42:43], off nt
	v_lshl_add_u64 v[40:41], v[14:15], 0, s[0:1]
	global_load_dword v100, v[40:41], off nt
	v_lshl_add_u64 v[42:43], v[12:13], 0, s[0:1]
	global_load_dword v101, v[42:43], off nt
	v_lshl_add_u64 v[40:41], v[10:11], 0, s[0:1]
	global_load_dword v102, v[40:41], off nt
	v_lshl_add_u64 v[42:43], v[8:9], 0, s[0:1]
	global_load_dword v103, v[42:43], off nt
	s_add_u32 s0, s0, 0x58000
	s_addc_u32 s1, s1, 0
	v_lshl_add_u64 v[40:41], v[22:23], 0, s[0:1]
	global_load_dword v104, v[40:41], off nt
	v_lshl_add_u64 v[42:43], v[20:21], 0, s[0:1]
	global_load_dword v105, v[42:43], off nt
	v_lshl_add_u64 v[40:41], v[18:19], 0, s[0:1]
	global_load_dword v106, v[40:41], off nt
	v_lshl_add_u64 v[42:43], v[16:17], 0, s[0:1]
	global_load_dword v107, v[42:43], off nt
	v_lshl_add_u64 v[40:41], v[14:15], 0, s[0:1]
	global_load_dword v108, v[40:41], off nt
	v_lshl_add_u64 v[42:43], v[12:13], 0, s[0:1]
	global_load_dword v109, v[42:43], off nt
	v_lshl_add_u64 v[40:41], v[10:11], 0, s[0:1]
	global_load_dword v110, v[40:41], off nt
	v_lshl_add_u64 v[42:43], v[8:9], 0, s[0:1]
	global_load_dword v111, v[42:43], off nt
	s_add_u32 s0, s0, 0x58000
	s_addc_u32 s1, s1, 0
	v_lshl_add_u64 v[40:41], v[22:23], 0, s[0:1]
	global_load_dword v112, v[40:41], off nt
	v_lshl_add_u64 v[42:43], v[20:21], 0, s[0:1]
	global_load_dword v113, v[42:43], off nt
	v_lshl_add_u64 v[40:41], v[18:19], 0, s[0:1]
	global_load_dword v114, v[40:41], off nt
	v_lshl_add_u64 v[42:43], v[16:17], 0, s[0:1]
	global_load_dword v115, v[42:43], off nt
	v_lshl_add_u64 v[40:41], v[14:15], 0, s[0:1]
	global_load_dword v116, v[40:41], off nt
	v_lshl_add_u64 v[42:43], v[12:13], 0, s[0:1]
	global_load_dword v117, v[42:43], off nt
	v_lshl_add_u64 v[40:41], v[10:11], 0, s[0:1]
	global_load_dword v118, v[40:41], off nt
	v_lshl_add_u64 v[42:43], v[8:9], 0, s[0:1]
	global_load_dword v119, v[42:43], off nt
	s_add_u32 s0, s0, 0x58000
	s_addc_u32 s1, s1, 0
	v_lshl_add_u64 v[40:41], v[22:23], 0, s[0:1]
	global_load_dword v120, v[40:41], off nt
	v_lshl_add_u64 v[42:43], v[20:21], 0, s[0:1]
	global_load_dword v121, v[42:43], off nt
	v_lshl_add_u64 v[40:41], v[18:19], 0, s[0:1]
	global_load_dword v122, v[40:41], off nt
	v_lshl_add_u64 v[42:43], v[16:17], 0, s[0:1]
	global_load_dword v123, v[42:43], off nt
	v_lshl_add_u64 v[40:41], v[14:15], 0, s[0:1]
	global_load_dword v124, v[40:41], off nt
	v_lshl_add_u64 v[42:43], v[12:13], 0, s[0:1]
	global_load_dword v125, v[42:43], off nt
	v_lshl_add_u64 v[40:41], v[10:11], 0, s[0:1]
	global_load_dword v126, v[40:41], off nt
	v_lshl_add_u64 v[42:43], v[8:9], 0, s[0:1]
	global_load_dword v127, v[42:43], off nt
	s_add_u32 s0, s0, 0x58000
	s_addc_u32 s1, s1, 0
	v_add_u32_e32 v47, 0x400, v38
	s_waitcnt vmcnt(30)
	ds_write2_b32 v38, v64, v65 offset1:66
	s_waitcnt vmcnt(28)
	ds_write2_b32 v38, v66, v67 offset0:132 offset1:198
	s_waitcnt vmcnt(26)
	ds_write2_b32 v47, v100, v101 offset0:8 offset1:74
	s_waitcnt vmcnt(24)
	ds_write2_b32 v47, v102, v103 offset0:140 offset1:206
	v_add_u32_e32 v38, 0x840, v38
	v_add_u32_e32 v47, 0x400, v38
	s_waitcnt vmcnt(22)
	ds_write2_b32 v38, v104, v105 offset1:66
	s_waitcnt vmcnt(20)
	ds_write2_b32 v38, v106, v107 offset0:132 offset1:198
	s_waitcnt vmcnt(18)
	ds_write2_b32 v47, v108, v109 offset0:8 offset1:74
	s_waitcnt vmcnt(16)
	ds_write2_b32 v47, v110, v111 offset0:140 offset1:206
	v_add_u32_e32 v38, 0x840, v38
	v_add_u32_e32 v47, 0x400, v38
	s_waitcnt vmcnt(14)
	ds_write2_b32 v38, v112, v113 offset1:66
	s_waitcnt vmcnt(12)
	ds_write2_b32 v38, v114, v115 offset0:132 offset1:198
	s_waitcnt vmcnt(10)
	ds_write2_b32 v47, v116, v117 offset0:8 offset1:74
	s_waitcnt vmcnt(8)
	ds_write2_b32 v47, v118, v119 offset0:140 offset1:206
	v_add_u32_e32 v38, 0x840, v38
	v_add_u32_e32 v47, 0x400, v38
	s_waitcnt vmcnt(6)
	ds_write2_b32 v38, v120, v121 offset1:66
	s_waitcnt vmcnt(4)
	ds_write2_b32 v38, v122, v123 offset0:132 offset1:198
	s_waitcnt vmcnt(2)
	ds_write2_b32 v47, v124, v125 offset0:8 offset1:74
	s_waitcnt vmcnt(0)
	ds_write2_b32 v47, v126, v127 offset0:140 offset1:206
	v_add_u32_e32 v38, 0x840, v38
	s_lshl_b32 s0, s5, 6
	s_and_b32 s0, s0, 0x3f00
	s_and_b32 s1, s9, 0x60
	s_waitcnt lgkmcnt(0)
	s_or_b32 s0, s0, s1
	ds_read2_b32 v[12:13], v26 offset0:33 offset1:41
	ds_read2_b32 v[14:15], v26 offset1:8
	ds_read2_b32 v[16:17], v26 offset0:66 offset1:74
	ds_read2_b32 v[18:19], v26 offset0:99 offset1:107
	ds_read2_b32 v[20:21], v26 offset0:132 offset1:140
	ds_read2_b32 v[22:23], v26 offset0:165 offset1:173
	ds_read2_b32 v[38:39], v26 offset0:198 offset1:206
	ds_read2_b32 v[40:41], v26 offset0:231 offset1:239
	s_bitset1_b32 s0, 7
	s_and_b32 s1, 0xffff, s4
	s_lshl_b32 s76, s1, 1
	s_waitcnt lgkmcnt(6)
	v_cvt_pk_bf16_f32 v8, v14, v12
	v_or_b32_e32 v12, s0, v25
	v_lshl_add_u64 v[42:43], v[2:3], 0, s[76:77]
	v_lshlrev_b32_e32 v144, 12, v12
	v_lshl_add_u64 v[44:45], v[42:43], 0, v[144:145]
	s_waitcnt lgkmcnt(4)
	v_cvt_pk_bf16_f32 v9, v16, v18
	s_waitcnt lgkmcnt(2)
	v_cvt_pk_bf16_f32 v10, v20, v22
	s_waitcnt lgkmcnt(0)
	v_cvt_pk_bf16_f32 v11, v38, v40
	global_store_dwordx4 v[44:45], v[8:11], off
	v_or_b32_e32 v12, s0, v27
	v_lshlrev_b32_e32 v144, 12, v12
	v_cvt_pk_bf16_f32 v8, v15, v13
	v_cvt_pk_bf16_f32 v9, v17, v19
	v_cvt_pk_bf16_f32 v10, v21, v23
	v_cvt_pk_bf16_f32 v11, v39, v41
	ds_read2_b32 v[14:15], v26 offset0:16 offset1:24
	ds_read2_b32 v[16:17], v26 offset0:49 offset1:57
	ds_read2_b32 v[18:19], v26 offset0:82 offset1:90
	ds_read2_b32 v[20:21], v26 offset0:115 offset1:123
	ds_read2_b32 v[22:23], v26 offset0:148 offset1:156
	ds_read2_b32 v[38:39], v26 offset0:181 offset1:189
	ds_read2_b32 v[40:41], v26 offset0:214 offset1:222
	ds_read2_b32 v[44:45], v26 offset0:247 offset1:255
	v_lshl_add_u64 v[12:13], v[42:43], 0, v[144:145]
	global_store_dwordx4 v[12:13], v[8:11], off
	v_or_b32_e32 v12, s0, v28
	v_lshlrev_b32_e32 v144, 12, v12
	v_lshl_add_u64 v[12:13], v[42:43], 0, v[144:145]
	s_waitcnt lgkmcnt(6)
	v_cvt_pk_bf16_f32 v8, v14, v16
	s_waitcnt lgkmcnt(4)
	v_cvt_pk_bf16_f32 v9, v18, v20
	s_waitcnt lgkmcnt(2)
	v_cvt_pk_bf16_f32 v10, v22, v38
	s_waitcnt lgkmcnt(0)
	v_cvt_pk_bf16_f32 v11, v40, v44
	global_store_dwordx4 v[12:13], v[8:11], off
	v_or_b32_e32 v12, s0, v29
	v_lshlrev_b32_e32 v144, 12, v12
	v_lshl_add_u64 v[12:13], v[42:43], 0, v[144:145]
	v_cvt_pk_bf16_f32 v8, v15, v17
	v_cvt_pk_bf16_f32 v9, v19, v21
	v_cvt_pk_bf16_f32 v10, v23, v39
	v_cvt_pk_bf16_f32 v11, v41, v45
	global_store_dwordx4 v[12:13], v[8:11], off
	s_waitcnt lgkmcnt(0)
	s_mov_b64 s[0:1], 0

.LBB0_391:
	v_lshl_add_u64 v[40:41], v[22:23], 0, s[0:1]
	global_load_dword v64, v[40:41], off nt
	v_lshl_add_u64 v[42:43], v[20:21], 0, s[0:1]
	global_load_dword v65, v[42:43], off nt
	v_lshl_add_u64 v[40:41], v[18:19], 0, s[0:1]
	global_load_dword v66, v[40:41], off nt
	v_lshl_add_u64 v[42:43], v[16:17], 0, s[0:1]
	global_load_dword v67, v[42:43], off nt
	v_lshl_add_u64 v[40:41], v[14:15], 0, s[0:1]
	global_load_dword v100, v[40:41], off nt
	v_lshl_add_u64 v[42:43], v[12:13], 0, s[0:1]
	global_load_dword v101, v[42:43], off nt
	v_lshl_add_u64 v[40:41], v[10:11], 0, s[0:1]
	global_load_dword v102, v[40:41], off nt
	v_lshl_add_u64 v[42:43], v[8:9], 0, s[0:1]
	global_load_dword v103, v[42:43], off nt
	s_add_u32 s0, s0, 0x58000
	s_addc_u32 s1, s1, 0
	v_lshl_add_u64 v[40:41], v[22:23], 0, s[0:1]
	global_load_dword v104, v[40:41], off nt
	v_lshl_add_u64 v[42:43], v[20:21], 0, s[0:1]
	global_load_dword v105, v[42:43], off nt
	v_lshl_add_u64 v[40:41], v[18:19], 0, s[0:1]
	global_load_dword v106, v[40:41], off nt
	v_lshl_add_u64 v[42:43], v[16:17], 0, s[0:1]
	global_load_dword v107, v[42:43], off nt
	v_lshl_add_u64 v[40:41], v[14:15], 0, s[0:1]
	global_load_dword v108, v[40:41], off nt
	v_lshl_add_u64 v[42:43], v[12:13], 0, s[0:1]
	global_load_dword v109, v[42:43], off nt
	v_lshl_add_u64 v[40:41], v[10:11], 0, s[0:1]
	global_load_dword v110, v[40:41], off nt
	v_lshl_add_u64 v[42:43], v[8:9], 0, s[0:1]
	global_load_dword v111, v[42:43], off nt
	s_add_u32 s0, s0, 0x58000
	s_addc_u32 s1, s1, 0
	v_lshl_add_u64 v[40:41], v[22:23], 0, s[0:1]
	global_load_dword v112, v[40:41], off nt
	v_lshl_add_u64 v[42:43], v[20:21], 0, s[0:1]
	global_load_dword v113, v[42:43], off nt
	v_lshl_add_u64 v[40:41], v[18:19], 0, s[0:1]
	global_load_dword v114, v[40:41], off nt
	v_lshl_add_u64 v[42:43], v[16:17], 0, s[0:1]
	global_load_dword v115, v[42:43], off nt
	v_lshl_add_u64 v[40:41], v[14:15], 0, s[0:1]
	global_load_dword v116, v[40:41], off nt
	v_lshl_add_u64 v[42:43], v[12:13], 0, s[0:1]
	global_load_dword v117, v[42:43], off nt
	v_lshl_add_u64 v[40:41], v[10:11], 0, s[0:1]
	global_load_dword v118, v[40:41], off nt
	v_lshl_add_u64 v[42:43], v[8:9], 0, s[0:1]
	global_load_dword v119, v[42:43], off nt
	s_add_u32 s0, s0, 0x58000
	s_addc_u32 s1, s1, 0
	v_lshl_add_u64 v[40:41], v[22:23], 0, s[0:1]
	global_load_dword v120, v[40:41], off nt
	v_lshl_add_u64 v[42:43], v[20:21], 0, s[0:1]
	global_load_dword v121, v[42:43], off nt
	v_lshl_add_u64 v[40:41], v[18:19], 0, s[0:1]
	global_load_dword v122, v[40:41], off nt
	v_lshl_add_u64 v[42:43], v[16:17], 0, s[0:1]
	global_load_dword v123, v[42:43], off nt
	v_lshl_add_u64 v[40:41], v[14:15], 0, s[0:1]
	global_load_dword v124, v[40:41], off nt
	v_lshl_add_u64 v[42:43], v[12:13], 0, s[0:1]
	global_load_dword v125, v[42:43], off nt
	v_lshl_add_u64 v[40:41], v[10:11], 0, s[0:1]
	global_load_dword v126, v[40:41], off nt
	v_lshl_add_u64 v[42:43], v[8:9], 0, s[0:1]
	global_load_dword v127, v[42:43], off nt
	s_add_u32 s0, s0, 0x58000
	s_addc_u32 s1, s1, 0
	v_add_u32_e32 v47, 0x400, v38
	s_waitcnt vmcnt(30)
	ds_write2_b32 v38, v64, v65 offset1:66
	s_waitcnt vmcnt(28)
	ds_write2_b32 v38, v66, v67 offset0:132 offset1:198
	s_waitcnt vmcnt(26)
	ds_write2_b32 v47, v100, v101 offset0:8 offset1:74
	s_waitcnt vmcnt(24)
	ds_write2_b32 v47, v102, v103 offset0:140 offset1:206
	v_add_u32_e32 v38, 0x840, v38
	v_add_u32_e32 v47, 0x400, v38
	s_waitcnt vmcnt(22)
	ds_write2_b32 v38, v104, v105 offset1:66
	s_waitcnt vmcnt(20)
	ds_write2_b32 v38, v106, v107 offset0:132 offset1:198
	s_waitcnt vmcnt(18)
	ds_write2_b32 v47, v108, v109 offset0:8 offset1:74
	s_waitcnt vmcnt(16)
	ds_write2_b32 v47, v110, v111 offset0:140 offset1:206
	v_add_u32_e32 v38, 0x840, v38
	v_add_u32_e32 v47, 0x400, v38
	s_waitcnt vmcnt(14)
	ds_write2_b32 v38, v112, v113 offset1:66
	s_waitcnt vmcnt(12)
	ds_write2_b32 v38, v114, v115 offset0:132 offset1:198
	s_waitcnt vmcnt(10)
	ds_write2_b32 v47, v116, v117 offset0:8 offset1:74
	s_waitcnt vmcnt(8)
	ds_write2_b32 v47, v118, v119 offset0:140 offset1:206
	v_add_u32_e32 v38, 0x840, v38
	v_add_u32_e32 v47, 0x400, v38
	s_waitcnt vmcnt(6)
	ds_write2_b32 v38, v120, v121 offset1:66
	s_waitcnt vmcnt(4)
	ds_write2_b32 v38, v122, v123 offset0:132 offset1:198
	s_waitcnt vmcnt(2)
	ds_write2_b32 v47, v124, v125 offset0:8 offset1:74
	s_waitcnt vmcnt(0)
	ds_write2_b32 v47, v126, v127 offset0:140 offset1:206
	v_add_u32_e32 v38, 0x840, v38
	s_lshl_b32 s0, s5, 6
	s_waitcnt lgkmcnt(0)
	s_and_b32 s1, s9, 0x60
	s_and_b32 s0, s0, 0x3f00
	ds_read2_b32 v[12:13], v26 offset0:33 offset1:41
	ds_read2_b32 v[14:15], v26 offset1:8
	ds_read2_b32 v[16:17], v26 offset0:66 offset1:74
	ds_read2_b32 v[18:19], v26 offset0:99 offset1:107
	ds_read2_b32 v[20:21], v26 offset0:132 offset1:140
	ds_read2_b32 v[22:23], v26 offset0:165 offset1:173
	ds_read2_b32 v[38:39], v26 offset0:198 offset1:206
	ds_read2_b32 v[40:41], v26 offset0:231 offset1:239
	s_or_b32 s0, s0, s1
	s_and_b32 s1, 0xffff, s4
	s_lshl_b32 s76, s1, 1
	s_waitcnt lgkmcnt(6)
	v_cvt_pk_bf16_f32 v8, v14, v12
	v_or_b32_e32 v12, s0, v25
	v_lshl_add_u64 v[42:43], v[2:3], 0, s[76:77]
	v_lshlrev_b32_e32 v144, 12, v12
	v_lshl_add_u64 v[44:45], v[42:43], 0, v[144:145]
	s_waitcnt lgkmcnt(4)
	v_cvt_pk_bf16_f32 v9, v16, v18
	s_waitcnt lgkmcnt(2)
	v_cvt_pk_bf16_f32 v10, v20, v22
	s_waitcnt lgkmcnt(0)
	v_cvt_pk_bf16_f32 v11, v38, v40
	global_store_dwordx4 v[44:45], v[8:11], off
	v_or_b32_e32 v12, s0, v27
	v_lshlrev_b32_e32 v144, 12, v12
	v_cvt_pk_bf16_f32 v8, v15, v13
	v_cvt_pk_bf16_f32 v9, v17, v19
	v_cvt_pk_bf16_f32 v10, v21, v23
	v_cvt_pk_bf16_f32 v11, v39, v41
	ds_read2_b32 v[14:15], v26 offset0:16 offset1:24
	ds_read2_b32 v[16:17], v26 offset0:49 offset1:57
	ds_read2_b32 v[18:19], v26 offset0:82 offset1:90
	ds_read2_b32 v[20:21], v26 offset0:115 offset1:123
	ds_read2_b32 v[22:23], v26 offset0:148 offset1:156
	ds_read2_b32 v[38:39], v26 offset0:181 offset1:189
	ds_read2_b32 v[40:41], v26 offset0:214 offset1:222
	ds_read2_b32 v[44:45], v26 offset0:247 offset1:255
	v_lshl_add_u64 v[12:13], v[42:43], 0, v[144:145]
	global_store_dwordx4 v[12:13], v[8:11], off
	v_or_b32_e32 v12, s0, v28
	v_lshlrev_b32_e32 v144, 12, v12
	v_lshl_add_u64 v[12:13], v[42:43], 0, v[144:145]
	s_waitcnt lgkmcnt(6)
	v_cvt_pk_bf16_f32 v8, v14, v16
	s_waitcnt lgkmcnt(4)
	v_cvt_pk_bf16_f32 v9, v18, v20
	s_waitcnt lgkmcnt(2)
	v_cvt_pk_bf16_f32 v10, v22, v38
	s_waitcnt lgkmcnt(0)
	v_cvt_pk_bf16_f32 v11, v40, v44
	global_store_dwordx4 v[12:13], v[8:11], off
	v_or_b32_e32 v12, s0, v29
	v_lshlrev_b32_e32 v144, 12, v12
	v_lshl_add_u64 v[12:13], v[42:43], 0, v[144:145]
	v_cvt_pk_bf16_f32 v8, v15, v17
	v_cvt_pk_bf16_f32 v9, v19, v21
	v_cvt_pk_bf16_f32 v10, v23, v39
	v_cvt_pk_bf16_f32 v11, v41, v45
	global_store_dwordx4 v[12:13], v[8:11], off
	s_waitcnt lgkmcnt(0)

.LBB0_396:
	v_lshl_add_u64 v[40:41], v[22:23], 0, s[0:1]
	global_load_dword v64, v[40:41], off nt
	v_lshl_add_u64 v[42:43], v[20:21], 0, s[0:1]
	global_load_dword v65, v[42:43], off nt
	v_lshl_add_u64 v[40:41], v[18:19], 0, s[0:1]
	global_load_dword v66, v[40:41], off nt
	v_lshl_add_u64 v[42:43], v[16:17], 0, s[0:1]
	global_load_dword v67, v[42:43], off nt
	v_lshl_add_u64 v[40:41], v[14:15], 0, s[0:1]
	global_load_dword v100, v[40:41], off nt
	v_lshl_add_u64 v[42:43], v[12:13], 0, s[0:1]
	global_load_dword v101, v[42:43], off nt
	v_lshl_add_u64 v[40:41], v[10:11], 0, s[0:1]
	global_load_dword v102, v[40:41], off nt
	v_lshl_add_u64 v[42:43], v[8:9], 0, s[0:1]
	global_load_dword v103, v[42:43], off nt
	s_add_u32 s0, s0, 0x20000
	s_addc_u32 s1, s1, 0
	v_lshl_add_u64 v[40:41], v[22:23], 0, s[0:1]
	global_load_dword v104, v[40:41], off nt
	v_lshl_add_u64 v[42:43], v[20:21], 0, s[0:1]
	global_load_dword v105, v[42:43], off nt
	v_lshl_add_u64 v[40:41], v[18:19], 0, s[0:1]
	global_load_dword v106, v[40:41], off nt
	v_lshl_add_u64 v[42:43], v[16:17], 0, s[0:1]
	global_load_dword v107, v[42:43], off nt
	v_lshl_add_u64 v[40:41], v[14:15], 0, s[0:1]
	global_load_dword v108, v[40:41], off nt
	v_lshl_add_u64 v[42:43], v[12:13], 0, s[0:1]
	global_load_dword v109, v[42:43], off nt
	v_lshl_add_u64 v[40:41], v[10:11], 0, s[0:1]
	global_load_dword v110, v[40:41], off nt
	v_lshl_add_u64 v[42:43], v[8:9], 0, s[0:1]
	global_load_dword v111, v[42:43], off nt
	s_add_u32 s0, s0, 0x20000
	s_addc_u32 s1, s1, 0
	v_lshl_add_u64 v[40:41], v[22:23], 0, s[0:1]
	global_load_dword v112, v[40:41], off nt
	v_lshl_add_u64 v[42:43], v[20:21], 0, s[0:1]
	global_load_dword v113, v[42:43], off nt
	v_lshl_add_u64 v[40:41], v[18:19], 0, s[0:1]
	global_load_dword v114, v[40:41], off nt
	v_lshl_add_u64 v[42:43], v[16:17], 0, s[0:1]
	global_load_dword v115, v[42:43], off nt
	v_lshl_add_u64 v[40:41], v[14:15], 0, s[0:1]
	global_load_dword v116, v[40:41], off nt
	v_lshl_add_u64 v[42:43], v[12:13], 0, s[0:1]
	global_load_dword v117, v[42:43], off nt
	v_lshl_add_u64 v[40:41], v[10:11], 0, s[0:1]
	global_load_dword v118, v[40:41], off nt
	v_lshl_add_u64 v[42:43], v[8:9], 0, s[0:1]
	global_load_dword v119, v[42:43], off nt
	s_add_u32 s0, s0, 0x20000
	s_addc_u32 s1, s1, 0
	v_lshl_add_u64 v[40:41], v[22:23], 0, s[0:1]
	global_load_dword v120, v[40:41], off nt
	v_lshl_add_u64 v[42:43], v[20:21], 0, s[0:1]
	global_load_dword v121, v[42:43], off nt
	v_lshl_add_u64 v[40:41], v[18:19], 0, s[0:1]
	global_load_dword v122, v[40:41], off nt
	v_lshl_add_u64 v[42:43], v[16:17], 0, s[0:1]
	global_load_dword v123, v[42:43], off nt
	v_lshl_add_u64 v[40:41], v[14:15], 0, s[0:1]
	global_load_dword v124, v[40:41], off nt
	v_lshl_add_u64 v[42:43], v[12:13], 0, s[0:1]
	global_load_dword v125, v[42:43], off nt
	v_lshl_add_u64 v[40:41], v[10:11], 0, s[0:1]
	global_load_dword v126, v[40:41], off nt
	v_lshl_add_u64 v[42:43], v[8:9], 0, s[0:1]
	global_load_dword v127, v[42:43], off nt
	s_add_u32 s0, s0, 0x20000
	s_addc_u32 s1, s1, 0
	v_add_u32_e32 v47, 0x400, v38
	s_waitcnt vmcnt(30)
	ds_write2_b32 v38, v64, v65 offset1:66
	s_waitcnt vmcnt(28)
	ds_write2_b32 v38, v66, v67 offset0:132 offset1:198
	s_waitcnt vmcnt(26)
	ds_write2_b32 v47, v100, v101 offset0:8 offset1:74
	s_waitcnt vmcnt(24)
	ds_write2_b32 v47, v102, v103 offset0:140 offset1:206
	v_add_u32_e32 v38, 0x840, v38
	v_add_u32_e32 v47, 0x400, v38
	s_waitcnt vmcnt(22)
	ds_write2_b32 v38, v104, v105 offset1:66
	s_waitcnt vmcnt(20)
	ds_write2_b32 v38, v106, v107 offset0:132 offset1:198
	s_waitcnt vmcnt(18)
	ds_write2_b32 v47, v108, v109 offset0:8 offset1:74
	s_waitcnt vmcnt(16)
	ds_write2_b32 v47, v110, v111 offset0:140 offset1:206
	v_add_u32_e32 v38, 0x840, v38
	v_add_u32_e32 v47, 0x400, v38
	s_waitcnt vmcnt(14)
	ds_write2_b32 v38, v112, v113 offset1:66
	s_waitcnt vmcnt(12)
	ds_write2_b32 v38, v114, v115 offset0:132 offset1:198
	s_waitcnt vmcnt(10)
	ds_write2_b32 v47, v116, v117 offset0:8 offset1:74
	s_waitcnt vmcnt(8)
	ds_write2_b32 v47, v118, v119 offset0:140 offset1:206
	v_add_u32_e32 v38, 0x840, v38
	v_add_u32_e32 v47, 0x400, v38
	s_waitcnt vmcnt(6)
	ds_write2_b32 v38, v120, v121 offset1:66
	s_waitcnt vmcnt(4)
	ds_write2_b32 v38, v122, v123 offset0:132 offset1:198
	s_waitcnt vmcnt(2)
	ds_write2_b32 v47, v124, v125 offset0:8 offset1:74
	s_waitcnt vmcnt(0)
	ds_write2_b32 v47, v126, v127 offset0:140 offset1:206
	v_add_u32_e32 v38, 0x840, v38
	s_waitcnt lgkmcnt(0)
	s_add_i32 s0, s6, 0xe800
	s_lshl_b32 s1, s6, 5
	ds_read2_b32 v[12:13], v26 offset0:33 offset1:41
	ds_read2_b32 v[14:15], v26 offset1:8
	ds_read2_b32 v[16:17], v26 offset0:66 offset1:74
	ds_read2_b32 v[18:19], v26 offset0:99 offset1:107
	ds_read2_b32 v[20:21], v26 offset0:132 offset1:140
	ds_read2_b32 v[22:23], v26 offset0:165 offset1:173
	ds_read2_b32 v[38:39], v26 offset0:198 offset1:206
	ds_read2_b32 v[40:41], v26 offset0:231 offset1:239
	s_and_b32 s0, s0, 0xffc0
	s_and_b32 s1, s1, 0x7e0
	s_lshl_b32 s76, s0, 1
	s_waitcnt lgkmcnt(6)
	v_cvt_pk_bf16_f32 v8, v14, v12
	v_or_b32_e32 v12, s1, v25
	v_lshl_add_u64 v[42:43], v[4:5], 0, s[76:77]
	v_lshlrev_b32_e32 v144, 12, v12
	v_lshl_add_u64 v[44:45], v[42:43], 0, v[144:145]
	s_waitcnt lgkmcnt(4)
	v_cvt_pk_bf16_f32 v9, v16, v18
	s_waitcnt lgkmcnt(2)
	v_cvt_pk_bf16_f32 v10, v20, v22
	s_waitcnt lgkmcnt(0)
	v_cvt_pk_bf16_f32 v11, v38, v40
	global_store_dwordx4 v[44:45], v[8:11], off
	v_or_b32_e32 v12, s1, v27
	v_lshlrev_b32_e32 v144, 12, v12
	v_cvt_pk_bf16_f32 v8, v15, v13
	v_cvt_pk_bf16_f32 v9, v17, v19
	v_cvt_pk_bf16_f32 v10, v21, v23
	v_cvt_pk_bf16_f32 v11, v39, v41
	ds_read2_b32 v[14:15], v26 offset0:16 offset1:24
	ds_read2_b32 v[16:17], v26 offset0:49 offset1:57
	ds_read2_b32 v[18:19], v26 offset0:82 offset1:90
	ds_read2_b32 v[20:21], v26 offset0:115 offset1:123
	ds_read2_b32 v[22:23], v26 offset0:148 offset1:156
	ds_read2_b32 v[38:39], v26 offset0:181 offset1:189
	ds_read2_b32 v[40:41], v26 offset0:214 offset1:222
	ds_read2_b32 v[44:45], v26 offset0:247 offset1:255
	v_lshl_add_u64 v[12:13], v[42:43], 0, v[144:145]
	global_store_dwordx4 v[12:13], v[8:11], off
	v_or_b32_e32 v12, s1, v28
	v_lshlrev_b32_e32 v144, 12, v12
	v_lshl_add_u64 v[12:13], v[42:43], 0, v[144:145]
	s_waitcnt lgkmcnt(6)
	v_cvt_pk_bf16_f32 v8, v14, v16
	s_waitcnt lgkmcnt(4)
	v_cvt_pk_bf16_f32 v9, v18, v20
	s_waitcnt lgkmcnt(2)
	v_cvt_pk_bf16_f32 v10, v22, v38
	s_waitcnt lgkmcnt(0)
	v_cvt_pk_bf16_f32 v11, v40, v44
	global_store_dwordx4 v[12:13], v[8:11], off
	v_or_b32_e32 v12, s1, v29
	v_lshlrev_b32_e32 v144, 12, v12
	v_lshl_add_u64 v[12:13], v[42:43], 0, v[144:145]
	v_cvt_pk_bf16_f32 v8, v15, v17
	v_cvt_pk_bf16_f32 v9, v19, v21
	v_cvt_pk_bf16_f32 v10, v23, v39
	v_cvt_pk_bf16_f32 v11, v41, v45
	global_store_dwordx4 v[12:13], v[8:11], off
	s_waitcnt lgkmcnt(0)

.LBB0_405:
	v_lshl_add_u64 v[40:41], v[22:23], 0, s[4:5]
	global_load_dword v64, v[40:41], off nt
	v_lshl_add_u64 v[42:43], v[20:21], 0, s[4:5]
	global_load_dword v65, v[42:43], off nt
	v_lshl_add_u64 v[40:41], v[18:19], 0, s[4:5]
	global_load_dword v66, v[40:41], off nt
	v_lshl_add_u64 v[42:43], v[16:17], 0, s[4:5]
	global_load_dword v67, v[42:43], off nt
	v_lshl_add_u64 v[40:41], v[14:15], 0, s[4:5]
	global_load_dword v100, v[40:41], off nt
	v_lshl_add_u64 v[42:43], v[12:13], 0, s[4:5]
	global_load_dword v101, v[42:43], off nt
	v_lshl_add_u64 v[40:41], v[10:11], 0, s[4:5]
	global_load_dword v102, v[40:41], off nt
	v_lshl_add_u64 v[42:43], v[8:9], 0, s[4:5]
	global_load_dword v103, v[42:43], off nt
	s_add_u32 s4, s4, 0x60000
	s_addc_u32 s5, s5, 0
	v_lshl_add_u64 v[40:41], v[22:23], 0, s[4:5]
	global_load_dword v104, v[40:41], off nt
	v_lshl_add_u64 v[42:43], v[20:21], 0, s[4:5]
	global_load_dword v105, v[42:43], off nt
	v_lshl_add_u64 v[40:41], v[18:19], 0, s[4:5]
	global_load_dword v106, v[40:41], off nt
	v_lshl_add_u64 v[42:43], v[16:17], 0, s[4:5]
	global_load_dword v107, v[42:43], off nt
	v_lshl_add_u64 v[40:41], v[14:15], 0, s[4:5]
	global_load_dword v108, v[40:41], off nt
	v_lshl_add_u64 v[42:43], v[12:13], 0, s[4:5]
	global_load_dword v109, v[42:43], off nt
	v_lshl_add_u64 v[40:41], v[10:11], 0, s[4:5]
	global_load_dword v110, v[40:41], off nt
	v_lshl_add_u64 v[42:43], v[8:9], 0, s[4:5]
	global_load_dword v111, v[42:43], off nt
	s_add_u32 s4, s4, 0x60000
	s_addc_u32 s5, s5, 0
	v_lshl_add_u64 v[40:41], v[22:23], 0, s[4:5]
	global_load_dword v112, v[40:41], off nt
	v_lshl_add_u64 v[42:43], v[20:21], 0, s[4:5]
	global_load_dword v113, v[42:43], off nt
	v_lshl_add_u64 v[40:41], v[18:19], 0, s[4:5]
	global_load_dword v114, v[40:41], off nt
	v_lshl_add_u64 v[42:43], v[16:17], 0, s[4:5]
	global_load_dword v115, v[42:43], off nt
	v_lshl_add_u64 v[40:41], v[14:15], 0, s[4:5]
	global_load_dword v116, v[40:41], off nt
	v_lshl_add_u64 v[42:43], v[12:13], 0, s[4:5]
	global_load_dword v117, v[42:43], off nt
	v_lshl_add_u64 v[40:41], v[10:11], 0, s[4:5]
	global_load_dword v118, v[40:41], off nt
	v_lshl_add_u64 v[42:43], v[8:9], 0, s[4:5]
	global_load_dword v119, v[42:43], off nt
	s_add_u32 s4, s4, 0x60000
	s_addc_u32 s5, s5, 0
	v_lshl_add_u64 v[40:41], v[22:23], 0, s[4:5]
	global_load_dword v120, v[40:41], off nt
	v_lshl_add_u64 v[42:43], v[20:21], 0, s[4:5]
	global_load_dword v121, v[42:43], off nt
	v_lshl_add_u64 v[40:41], v[18:19], 0, s[4:5]
	global_load_dword v122, v[40:41], off nt
	v_lshl_add_u64 v[42:43], v[16:17], 0, s[4:5]
	global_load_dword v123, v[42:43], off nt
	v_lshl_add_u64 v[40:41], v[14:15], 0, s[4:5]
	global_load_dword v124, v[40:41], off nt
	v_lshl_add_u64 v[42:43], v[12:13], 0, s[4:5]
	global_load_dword v125, v[42:43], off nt
	v_lshl_add_u64 v[40:41], v[10:11], 0, s[4:5]
	global_load_dword v126, v[40:41], off nt
	v_lshl_add_u64 v[42:43], v[8:9], 0, s[4:5]
	global_load_dword v127, v[42:43], off nt
	s_add_u32 s4, s4, 0x60000
	s_addc_u32 s5, s5, 0
	v_add_u32_e32 v47, 0x400, v38
	s_waitcnt vmcnt(30)
	ds_write2_b32 v38, v64, v65 offset1:66
	s_waitcnt vmcnt(28)
	ds_write2_b32 v38, v66, v67 offset0:132 offset1:198
	s_waitcnt vmcnt(26)
	ds_write2_b32 v47, v100, v101 offset0:8 offset1:74
	s_waitcnt vmcnt(24)
	ds_write2_b32 v47, v102, v103 offset0:140 offset1:206
	v_add_u32_e32 v38, 0x840, v38
	v_add_u32_e32 v47, 0x400, v38
	s_waitcnt vmcnt(22)
	ds_write2_b32 v38, v104, v105 offset1:66
	s_waitcnt vmcnt(20)
	ds_write2_b32 v38, v106, v107 offset0:132 offset1:198
	s_waitcnt vmcnt(18)
	ds_write2_b32 v47, v108, v109 offset0:8 offset1:74
	s_waitcnt vmcnt(16)
	ds_write2_b32 v47, v110, v111 offset0:140 offset1:206
	v_add_u32_e32 v38, 0x840, v38
	v_add_u32_e32 v47, 0x400, v38
	s_waitcnt vmcnt(14)
	ds_write2_b32 v38, v112, v113 offset1:66
	s_waitcnt vmcnt(12)
	ds_write2_b32 v38, v114, v115 offset0:132 offset1:198
	s_waitcnt vmcnt(10)
	ds_write2_b32 v47, v116, v117 offset0:8 offset1:74
	s_waitcnt vmcnt(8)
	ds_write2_b32 v47, v118, v119 offset0:140 offset1:206
	v_add_u32_e32 v38, 0x840, v38
	v_add_u32_e32 v47, 0x400, v38
	s_waitcnt vmcnt(6)
	ds_write2_b32 v38, v120, v121 offset1:66
	s_waitcnt vmcnt(4)
	ds_write2_b32 v38, v122, v123 offset0:132 offset1:198
	s_waitcnt vmcnt(2)
	ds_write2_b32 v47, v124, v125 offset0:8 offset1:74
	s_waitcnt vmcnt(0)
	ds_write2_b32 v47, v126, v127 offset0:140 offset1:206
	v_add_u32_e32 v38, 0x840, v38
	s_waitcnt lgkmcnt(0)
	ds_read2_b32 v[12:13], v26 offset0:33 offset1:41
	ds_read2_b32 v[14:15], v26 offset1:8
	ds_read2_b32 v[16:17], v26 offset0:66 offset1:74
	ds_read2_b32 v[18:19], v26 offset0:99 offset1:107
	ds_read2_b32 v[20:21], v26 offset0:132 offset1:140
	ds_read2_b32 v[22:23], v26 offset0:165 offset1:173
	ds_read2_b32 v[38:39], v26 offset0:198 offset1:206
	ds_read2_b32 v[40:41], v26 offset0:231 offset1:239
	v_add_u32_e32 v44, s9, v25
	s_ashr_i32 s1, s0, 31
	v_ashrrev_i32_e32 v45, 31, v44
	v_lshl_add_u64 v[42:43], s[0:1], 1, v[0:1]
	v_lshlrev_b64 v[44:45], 12, v[44:45]
	s_waitcnt lgkmcnt(6)
	v_cvt_pk_bf16_f32 v8, v14, v12
	v_lshl_add_u64 v[44:45], v[42:43], 0, v[44:45]
	v_add_u32_e32 v12, s9, v27
	s_waitcnt lgkmcnt(4)
	v_cvt_pk_bf16_f32 v9, v16, v18
	s_waitcnt lgkmcnt(2)
	v_cvt_pk_bf16_f32 v10, v20, v22
	s_waitcnt lgkmcnt(0)
	v_cvt_pk_bf16_f32 v11, v38, v40
	global_store_dwordx4 v[44:45], v[8:11], off
	s_nop 1
	v_cvt_pk_bf16_f32 v8, v15, v13
	v_ashrrev_i32_e32 v13, 31, v12
	v_lshlrev_b64 v[12:13], 12, v[12:13]
	v_cvt_pk_bf16_f32 v9, v17, v19
	v_cvt_pk_bf16_f32 v10, v21, v23
	v_cvt_pk_bf16_f32 v11, v39, v41
	v_lshl_add_u64 v[12:13], v[42:43], 0, v[12:13]
	ds_read2_b32 v[14:15], v26 offset0:16 offset1:24
	ds_read2_b32 v[16:17], v26 offset0:49 offset1:57
	ds_read2_b32 v[18:19], v26 offset0:82 offset1:90
	ds_read2_b32 v[20:21], v26 offset0:115 offset1:123
	ds_read2_b32 v[22:23], v26 offset0:148 offset1:156
	ds_read2_b32 v[38:39], v26 offset0:181 offset1:189
	ds_read2_b32 v[40:41], v26 offset0:214 offset1:222
	ds_read2_b32 v[44:45], v26 offset0:247 offset1:255
	global_store_dwordx4 v[12:13], v[8:11], off
	v_add_u32_e32 v12, s9, v28
	v_ashrrev_i32_e32 v13, 31, v12
	v_lshlrev_b64 v[12:13], 12, v[12:13]
	v_lshl_add_u64 v[12:13], v[42:43], 0, v[12:13]
	s_waitcnt lgkmcnt(6)
	v_cvt_pk_bf16_f32 v8, v14, v16
	s_waitcnt lgkmcnt(4)
	v_cvt_pk_bf16_f32 v9, v18, v20
	s_waitcnt lgkmcnt(2)
	v_cvt_pk_bf16_f32 v10, v22, v38
	s_waitcnt lgkmcnt(0)
	v_cvt_pk_bf16_f32 v11, v40, v44
	global_store_dwordx4 v[12:13], v[8:11], off
	v_add_u32_e32 v12, s9, v29
	v_ashrrev_i32_e32 v13, 31, v12
	v_lshlrev_b64 v[12:13], 12, v[12:13]
	v_lshl_add_u64 v[12:13], v[42:43], 0, v[12:13]
	v_cvt_pk_bf16_f32 v8, v15, v17
	v_cvt_pk_bf16_f32 v9, v19, v21
	v_cvt_pk_bf16_f32 v10, v23, v39
	v_cvt_pk_bf16_f32 v11, v41, v45
	global_store_dwordx4 v[12:13], v[8:11], off
	s_waitcnt lgkmcnt(0)
	s_branch .LBB0_382

.LBB0_824:
	v_lshl_add_u64 v[58:59], v[32:33], 0, s[4:5]
	global_load_dword v64, v[58:59], off nt
	v_lshl_add_u64 v[58:59], v[30:31], 0, s[4:5]
	global_load_dword v65, v[58:59], off nt
	v_lshl_add_u64 v[58:59], v[28:29], 0, s[4:5]
	global_load_dword v66, v[58:59], off nt
	v_lshl_add_u64 v[58:59], v[26:27], 0, s[4:5]
	global_load_dword v67, v[58:59], off nt
	v_lshl_add_u64 v[58:59], v[24:25], 0, s[4:5]
	global_load_dword v100, v[58:59], off nt
	v_lshl_add_u64 v[58:59], v[22:23], 0, s[4:5]
	global_load_dword v101, v[58:59], off nt
	v_lshl_add_u64 v[58:59], v[20:21], 0, s[4:5]
	global_load_dword v102, v[58:59], off nt
	v_lshl_add_u64 v[58:59], v[18:19], 0, s[4:5]
	global_load_dword v103, v[58:59], off nt
	s_add_u32 s4, s4, 0x20000
	s_addc_u32 s5, s5, 0
	v_lshl_add_u64 v[58:59], v[32:33], 0, s[4:5]
	global_load_dword v104, v[58:59], off nt
	v_lshl_add_u64 v[58:59], v[30:31], 0, s[4:5]
	global_load_dword v105, v[58:59], off nt
	v_lshl_add_u64 v[58:59], v[28:29], 0, s[4:5]
	global_load_dword v106, v[58:59], off nt
	v_lshl_add_u64 v[58:59], v[26:27], 0, s[4:5]
	global_load_dword v107, v[58:59], off nt
	v_lshl_add_u64 v[58:59], v[24:25], 0, s[4:5]
	global_load_dword v108, v[58:59], off nt
	v_lshl_add_u64 v[58:59], v[22:23], 0, s[4:5]
	global_load_dword v109, v[58:59], off nt
	v_lshl_add_u64 v[58:59], v[20:21], 0, s[4:5]
	global_load_dword v110, v[58:59], off nt
	v_lshl_add_u64 v[58:59], v[18:19], 0, s[4:5]
	global_load_dword v111, v[58:59], off nt
	s_add_u32 s4, s4, 0x20000
	s_addc_u32 s5, s5, 0
	v_lshl_add_u64 v[58:59], v[32:33], 0, s[4:5]
	global_load_dword v112, v[58:59], off nt
	v_lshl_add_u64 v[58:59], v[30:31], 0, s[4:5]
	global_load_dword v113, v[58:59], off nt
	v_lshl_add_u64 v[58:59], v[28:29], 0, s[4:5]
	global_load_dword v114, v[58:59], off nt
	v_lshl_add_u64 v[58:59], v[26:27], 0, s[4:5]
	global_load_dword v115, v[58:59], off nt
	v_lshl_add_u64 v[58:59], v[24:25], 0, s[4:5]
	global_load_dword v116, v[58:59], off nt
	v_lshl_add_u64 v[58:59], v[22:23], 0, s[4:5]
	global_load_dword v117, v[58:59], off nt
	v_lshl_add_u64 v[58:59], v[20:21], 0, s[4:5]
	global_load_dword v118, v[58:59], off nt
	v_lshl_add_u64 v[58:59], v[18:19], 0, s[4:5]
	global_load_dword v119, v[58:59], off nt
	s_add_u32 s4, s4, 0x20000
	s_addc_u32 s5, s5, 0
	v_lshl_add_u64 v[58:59], v[32:33], 0, s[4:5]
	global_load_dword v120, v[58:59], off nt
	v_lshl_add_u64 v[58:59], v[30:31], 0, s[4:5]
	global_load_dword v121, v[58:59], off nt
	v_lshl_add_u64 v[58:59], v[28:29], 0, s[4:5]
	global_load_dword v122, v[58:59], off nt
	v_lshl_add_u64 v[58:59], v[26:27], 0, s[4:5]
	global_load_dword v123, v[58:59], off nt
	v_lshl_add_u64 v[58:59], v[24:25], 0, s[4:5]
	global_load_dword v124, v[58:59], off nt
	v_lshl_add_u64 v[58:59], v[22:23], 0, s[4:5]
	global_load_dword v125, v[58:59], off nt
	v_lshl_add_u64 v[58:59], v[20:21], 0, s[4:5]
	global_load_dword v126, v[58:59], off nt
	v_lshl_add_u64 v[58:59], v[18:19], 0, s[4:5]
	global_load_dword v127, v[58:59], off nt
	s_add_u32 s4, s4, 0x20000
	s_addc_u32 s5, s5, 0
	v_add_u32_e32 v60, 0x400, v56
	s_waitcnt vmcnt(30)
	ds_write2_b32 v56, v64, v65 offset1:66
	s_waitcnt vmcnt(28)
	ds_write2_b32 v56, v66, v67 offset0:132 offset1:198
	s_waitcnt vmcnt(26)
	ds_write2_b32 v60, v100, v101 offset0:8 offset1:74
	s_waitcnt vmcnt(24)
	ds_write2_b32 v60, v102, v103 offset0:140 offset1:206
	v_add_u32_e32 v56, 0x840, v56
	v_add_u32_e32 v60, 0x400, v56
	s_waitcnt vmcnt(22)
	ds_write2_b32 v56, v104, v105 offset1:66
	s_waitcnt vmcnt(20)
	ds_write2_b32 v56, v106, v107 offset0:132 offset1:198
	s_waitcnt vmcnt(18)
	ds_write2_b32 v60, v108, v109 offset0:8 offset1:74
	s_waitcnt vmcnt(16)
	ds_write2_b32 v60, v110, v111 offset0:140 offset1:206
	v_add_u32_e32 v56, 0x840, v56
	v_add_u32_e32 v60, 0x400, v56
	s_waitcnt vmcnt(14)
	ds_write2_b32 v56, v112, v113 offset1:66
	s_waitcnt vmcnt(12)
	ds_write2_b32 v56, v114, v115 offset0:132 offset1:198
	s_waitcnt vmcnt(10)
	ds_write2_b32 v60, v116, v117 offset0:8 offset1:74
	s_waitcnt vmcnt(8)
	ds_write2_b32 v60, v118, v119 offset0:140 offset1:206
	v_add_u32_e32 v56, 0x840, v56
	v_add_u32_e32 v60, 0x400, v56
	s_waitcnt vmcnt(6)
	ds_write2_b32 v56, v120, v121 offset1:66
	s_waitcnt vmcnt(4)
	ds_write2_b32 v56, v122, v123 offset0:132 offset1:198
	s_waitcnt vmcnt(2)
	ds_write2_b32 v60, v124, v125 offset0:8 offset1:74
	s_waitcnt vmcnt(0)
	ds_write2_b32 v60, v126, v127 offset0:140 offset1:206
	v_add_u32_e32 v56, 0x840, v56
	s_waitcnt lgkmcnt(0)
	ds_read2_b32 v[24:25], v36 offset0:33 offset1:41
	ds_read2_b32 v[26:27], v36 offset1:8
	s_lshl_b32 s4, s9, 5
	s_and_b32 s4, s4, 0x7e0
	ds_read2_b32 v[28:29], v36 offset0:66 offset1:74
	ds_read2_b32 v[30:31], v36 offset0:99 offset1:107
	ds_read2_b32 v[32:33], v36 offset0:132 offset1:140
	ds_read2_b32 v[56:57], v36 offset0:165 offset1:173
	s_waitcnt lgkmcnt(4)
	v_cvt_pk_bf16_f32 v18, v26, v24
	ds_read2_b32 v[58:59], v36 offset0:198 offset1:206
	ds_read2_b32 v[60:61], v36 offset0:231 offset1:239
	v_or_b32_e32 v24, s4, v35
	v_mul_u32_u24_e32 v24, 0x1600, v24
	s_add_i32 s76, s7, 0xffff5a00
	v_lshlrev_b32_e32 v144, 1, v24
	v_or_b32_e32 v24, s4, v37
	v_lshl_add_u64 v[22:23], s[76:77], 1, v[2:3]
	v_mul_u32_u24_e32 v24, 0x1600, v24
	v_lshl_add_u64 v[62:63], v[22:23], 0, v[144:145]
	v_lshlrev_b32_e32 v144, 1, v24
	s_waitcnt lgkmcnt(4)
	v_cvt_pk_bf16_f32 v19, v28, v30
	s_waitcnt lgkmcnt(2)
	v_cvt_pk_bf16_f32 v20, v32, v56
	s_waitcnt lgkmcnt(0)
	v_cvt_pk_bf16_f32 v21, v58, v60
	global_store_dwordx4 v[62:63], v[18:21], off
	s_nop 1
	v_cvt_pk_bf16_f32 v18, v27, v25
	v_lshl_add_u64 v[24:25], v[22:23], 0, v[144:145]
	v_cvt_pk_bf16_f32 v19, v29, v31
	v_cvt_pk_bf16_f32 v20, v33, v57
	v_cvt_pk_bf16_f32 v21, v59, v61
	global_store_dwordx4 v[24:25], v[18:21], off
	ds_read2_b32 v[24:25], v36 offset0:16 offset1:24
	ds_read2_b32 v[26:27], v36 offset0:49 offset1:57
	s_waitcnt lgkmcnt(0)
	v_cvt_pk_bf16_f32 v18, v24, v26
	ds_read2_b32 v[28:29], v36 offset0:82 offset1:90
	ds_read2_b32 v[30:31], v36 offset0:115 offset1:123
	ds_read2_b32 v[32:33], v36 offset0:148 offset1:156
	ds_read2_b32 v[56:57], v36 offset0:181 offset1:189
	ds_read2_b32 v[58:59], v36 offset0:214 offset1:222
	ds_read2_b32 v[60:61], v36 offset0:247 offset1:255
	v_or_b32_e32 v24, s4, v38
	v_mul_u32_u24_e32 v24, 0x1600, v24
	v_lshlrev_b32_e32 v144, 1, v24
	v_or_b32_e32 v24, s4, v39
	v_mul_u32_u24_e32 v24, 0x1600, v24
	v_lshl_add_u64 v[62:63], v[22:23], 0, v[144:145]
	v_lshlrev_b32_e32 v144, 1, v24
	s_waitcnt lgkmcnt(4)
	v_cvt_pk_bf16_f32 v19, v28, v30
	s_waitcnt lgkmcnt(2)
	v_cvt_pk_bf16_f32 v20, v32, v56
	s_waitcnt lgkmcnt(0)
	v_cvt_pk_bf16_f32 v21, v58, v60
	v_lshl_add_u64 v[22:23], v[22:23], 0, v[144:145]
	global_store_dwordx4 v[62:63], v[18:21], off
	s_mov_b64 s[4:5], 0
	s_nop 0
	v_cvt_pk_bf16_f32 v18, v25, v27
	v_cvt_pk_bf16_f32 v19, v29, v31
	v_cvt_pk_bf16_f32 v20, v33, v57
	v_cvt_pk_bf16_f32 v21, v59, v61
	global_store_dwordx4 v[22:23], v[18:21], off
	s_waitcnt lgkmcnt(0)

.LBB0_828:
	v_lshl_add_u64 v[58:59], v[32:33], 0, s[4:5]
	global_load_dword v64, v[58:59], off nt
	v_lshl_add_u64 v[58:59], v[30:31], 0, s[4:5]
	global_load_dword v65, v[58:59], off nt
	v_lshl_add_u64 v[58:59], v[28:29], 0, s[4:5]
	global_load_dword v66, v[58:59], off nt
	v_lshl_add_u64 v[58:59], v[26:27], 0, s[4:5]
	global_load_dword v67, v[58:59], off nt
	v_lshl_add_u64 v[58:59], v[24:25], 0, s[4:5]
	global_load_dword v100, v[58:59], off nt
	v_lshl_add_u64 v[58:59], v[22:23], 0, s[4:5]
	global_load_dword v101, v[58:59], off nt
	v_lshl_add_u64 v[58:59], v[20:21], 0, s[4:5]
	global_load_dword v102, v[58:59], off nt
	v_lshl_add_u64 v[58:59], v[18:19], 0, s[4:5]
	global_load_dword v103, v[58:59], off nt
	s_add_u32 s4, s4, 0x58000
	s_addc_u32 s5, s5, 0
	v_lshl_add_u64 v[58:59], v[32:33], 0, s[4:5]
	global_load_dword v104, v[58:59], off nt
	v_lshl_add_u64 v[58:59], v[30:31], 0, s[4:5]
	global_load_dword v105, v[58:59], off nt
	v_lshl_add_u64 v[58:59], v[28:29], 0, s[4:5]
	global_load_dword v106, v[58:59], off nt
	v_lshl_add_u64 v[58:59], v[26:27], 0, s[4:5]
	global_load_dword v107, v[58:59], off nt
	v_lshl_add_u64 v[58:59], v[24:25], 0, s[4:5]
	global_load_dword v108, v[58:59], off nt
	v_lshl_add_u64 v[58:59], v[22:23], 0, s[4:5]
	global_load_dword v109, v[58:59], off nt
	v_lshl_add_u64 v[58:59], v[20:21], 0, s[4:5]
	global_load_dword v110, v[58:59], off nt
	v_lshl_add_u64 v[58:59], v[18:19], 0, s[4:5]
	global_load_dword v111, v[58:59], off nt
	s_add_u32 s4, s4, 0x58000
	s_addc_u32 s5, s5, 0
	v_lshl_add_u64 v[58:59], v[32:33], 0, s[4:5]
	global_load_dword v112, v[58:59], off nt
	v_lshl_add_u64 v[58:59], v[30:31], 0, s[4:5]
	global_load_dword v113, v[58:59], off nt
	v_lshl_add_u64 v[58:59], v[28:29], 0, s[4:5]
	global_load_dword v114, v[58:59], off nt
	v_lshl_add_u64 v[58:59], v[26:27], 0, s[4:5]
	global_load_dword v115, v[58:59], off nt
	v_lshl_add_u64 v[58:59], v[24:25], 0, s[4:5]
	global_load_dword v116, v[58:59], off nt
	v_lshl_add_u64 v[58:59], v[22:23], 0, s[4:5]
	global_load_dword v117, v[58:59], off nt
	v_lshl_add_u64 v[58:59], v[20:21], 0, s[4:5]
	global_load_dword v118, v[58:59], off nt
	v_lshl_add_u64 v[58:59], v[18:19], 0, s[4:5]
	global_load_dword v119, v[58:59], off nt
	s_add_u32 s4, s4, 0x58000
	s_addc_u32 s5, s5, 0
	v_lshl_add_u64 v[58:59], v[32:33], 0, s[4:5]
	global_load_dword v120, v[58:59], off nt
	v_lshl_add_u64 v[58:59], v[30:31], 0, s[4:5]
	global_load_dword v121, v[58:59], off nt
	v_lshl_add_u64 v[58:59], v[28:29], 0, s[4:5]
	global_load_dword v122, v[58:59], off nt
	v_lshl_add_u64 v[58:59], v[26:27], 0, s[4:5]
	global_load_dword v123, v[58:59], off nt
	v_lshl_add_u64 v[58:59], v[24:25], 0, s[4:5]
	global_load_dword v124, v[58:59], off nt
	v_lshl_add_u64 v[58:59], v[22:23], 0, s[4:5]
	global_load_dword v125, v[58:59], off nt
	v_lshl_add_u64 v[58:59], v[20:21], 0, s[4:5]
	global_load_dword v126, v[58:59], off nt
	v_lshl_add_u64 v[58:59], v[18:19], 0, s[4:5]
	global_load_dword v127, v[58:59], off nt
	s_add_u32 s4, s4, 0x58000
	s_addc_u32 s5, s5, 0
	v_add_u32_e32 v60, 0x400, v56
	s_waitcnt vmcnt(30)
	ds_write2_b32 v56, v64, v65 offset1:66
	s_waitcnt vmcnt(28)
	ds_write2_b32 v56, v66, v67 offset0:132 offset1:198
	s_waitcnt vmcnt(26)
	ds_write2_b32 v60, v100, v101 offset0:8 offset1:74
	s_waitcnt vmcnt(24)
	ds_write2_b32 v60, v102, v103 offset0:140 offset1:206
	v_add_u32_e32 v56, 0x840, v56
	v_add_u32_e32 v60, 0x400, v56
	s_waitcnt vmcnt(22)
	ds_write2_b32 v56, v104, v105 offset1:66
	s_waitcnt vmcnt(20)
	ds_write2_b32 v56, v106, v107 offset0:132 offset1:198
	s_waitcnt vmcnt(18)
	ds_write2_b32 v60, v108, v109 offset0:8 offset1:74
	s_waitcnt vmcnt(16)
	ds_write2_b32 v60, v110, v111 offset0:140 offset1:206
	v_add_u32_e32 v56, 0x840, v56
	v_add_u32_e32 v60, 0x400, v56
	s_waitcnt vmcnt(14)
	ds_write2_b32 v56, v112, v113 offset1:66
	s_waitcnt vmcnt(12)
	ds_write2_b32 v56, v114, v115 offset0:132 offset1:198
	s_waitcnt vmcnt(10)
	ds_write2_b32 v60, v116, v117 offset0:8 offset1:74
	s_waitcnt vmcnt(8)
	ds_write2_b32 v60, v118, v119 offset0:140 offset1:206
	v_add_u32_e32 v56, 0x840, v56
	v_add_u32_e32 v60, 0x400, v56
	s_waitcnt vmcnt(6)
	ds_write2_b32 v56, v120, v121 offset1:66
	s_waitcnt vmcnt(4)
	ds_write2_b32 v56, v122, v123 offset0:132 offset1:198
	s_waitcnt vmcnt(2)
	ds_write2_b32 v60, v124, v125 offset0:8 offset1:74
	s_waitcnt vmcnt(0)
	ds_write2_b32 v60, v126, v127 offset0:140 offset1:206
	v_add_u32_e32 v56, 0x840, v56
	s_waitcnt lgkmcnt(0)
	ds_read2_b32 v[24:25], v36 offset0:33 offset1:41
	ds_read2_b32 v[26:27], v36 offset1:8
	s_lshl_b32 s4, s12, 6
	s_and_b32 s4, s4, 0x3f00
	s_and_b32 s5, s13, 0x60
	s_or_b32 s4, s4, s5
	ds_read2_b32 v[28:29], v36 offset0:66 offset1:74
	ds_read2_b32 v[30:31], v36 offset0:99 offset1:107
	ds_read2_b32 v[32:33], v36 offset0:132 offset1:140
	ds_read2_b32 v[56:57], v36 offset0:165 offset1:173
	ds_read2_b32 v[58:59], v36 offset0:198 offset1:206
	ds_read2_b32 v[60:61], v36 offset0:231 offset1:239
	s_bitset1_b32 s4, 7
	s_and_b32 s5, 0xffff, s7
	s_lshl_b32 s76, s5, 1
	s_waitcnt lgkmcnt(6)
	v_cvt_pk_bf16_f32 v18, v26, v24
	v_or_b32_e32 v24, s4, v35
	v_lshl_add_u64 v[22:23], v[4:5], 0, s[76:77]
	v_lshlrev_b32_e32 v144, 12, v24
	v_or_b32_e32 v24, s4, v37
	v_lshl_add_u64 v[62:63], v[22:23], 0, v[144:145]
	v_lshlrev_b32_e32 v144, 12, v24
	s_waitcnt lgkmcnt(4)
	v_cvt_pk_bf16_f32 v19, v28, v30
	s_waitcnt lgkmcnt(2)
	v_cvt_pk_bf16_f32 v20, v32, v56
	s_waitcnt lgkmcnt(0)
	v_cvt_pk_bf16_f32 v21, v58, v60
	global_store_dwordx4 v[62:63], v[18:21], off
	s_nop 1
	v_cvt_pk_bf16_f32 v18, v27, v25
	v_lshl_add_u64 v[24:25], v[22:23], 0, v[144:145]
	v_cvt_pk_bf16_f32 v19, v29, v31
	v_cvt_pk_bf16_f32 v20, v33, v57
	v_cvt_pk_bf16_f32 v21, v59, v61
	global_store_dwordx4 v[24:25], v[18:21], off
	ds_read2_b32 v[24:25], v36 offset0:16 offset1:24
	ds_read2_b32 v[26:27], v36 offset0:49 offset1:57
	ds_read2_b32 v[28:29], v36 offset0:82 offset1:90
	ds_read2_b32 v[30:31], v36 offset0:115 offset1:123
	ds_read2_b32 v[32:33], v36 offset0:148 offset1:156
	ds_read2_b32 v[56:57], v36 offset0:181 offset1:189
	ds_read2_b32 v[58:59], v36 offset0:214 offset1:222
	ds_read2_b32 v[60:61], v36 offset0:247 offset1:255
	s_waitcnt lgkmcnt(6)
	v_cvt_pk_bf16_f32 v18, v24, v26
	v_or_b32_e32 v24, s4, v38
	v_lshlrev_b32_e32 v144, 12, v24
	v_or_b32_e32 v24, s4, v39
	v_lshl_add_u64 v[62:63], v[22:23], 0, v[144:145]
	v_lshlrev_b32_e32 v144, 12, v24
	s_waitcnt lgkmcnt(4)
	v_cvt_pk_bf16_f32 v19, v28, v30
	s_waitcnt lgkmcnt(2)
	v_cvt_pk_bf16_f32 v20, v32, v56
	s_waitcnt lgkmcnt(0)
	v_cvt_pk_bf16_f32 v21, v58, v60
	v_lshl_add_u64 v[22:23], v[22:23], 0, v[144:145]
	global_store_dwordx4 v[62:63], v[18:21], off
	s_nop 1
	v_cvt_pk_bf16_f32 v18, v25, v27
	v_cvt_pk_bf16_f32 v19, v29, v31
	v_cvt_pk_bf16_f32 v20, v33, v57
	v_cvt_pk_bf16_f32 v21, v59, v61
	global_store_dwordx4 v[22:23], v[18:21], off
	s_waitcnt lgkmcnt(0)

.LBB0_833:
	v_lshl_add_u64 v[58:59], v[32:33], 0, s[4:5]
	global_load_dword v64, v[58:59], off nt
	v_lshl_add_u64 v[58:59], v[30:31], 0, s[4:5]
	global_load_dword v65, v[58:59], off nt
	v_lshl_add_u64 v[58:59], v[28:29], 0, s[4:5]
	global_load_dword v66, v[58:59], off nt
	v_lshl_add_u64 v[58:59], v[26:27], 0, s[4:5]
	global_load_dword v67, v[58:59], off nt
	v_lshl_add_u64 v[58:59], v[24:25], 0, s[4:5]
	global_load_dword v100, v[58:59], off nt
	v_lshl_add_u64 v[58:59], v[22:23], 0, s[4:5]
	global_load_dword v101, v[58:59], off nt
	v_lshl_add_u64 v[58:59], v[20:21], 0, s[4:5]
	global_load_dword v102, v[58:59], off nt
	v_lshl_add_u64 v[58:59], v[18:19], 0, s[4:5]
	global_load_dword v103, v[58:59], off nt
	s_add_u32 s4, s4, 0x58000
	s_addc_u32 s5, s5, 0
	v_lshl_add_u64 v[58:59], v[32:33], 0, s[4:5]
	global_load_dword v104, v[58:59], off nt
	v_lshl_add_u64 v[58:59], v[30:31], 0, s[4:5]
	global_load_dword v105, v[58:59], off nt
	v_lshl_add_u64 v[58:59], v[28:29], 0, s[4:5]
	global_load_dword v106, v[58:59], off nt
	v_lshl_add_u64 v[58:59], v[26:27], 0, s[4:5]
	global_load_dword v107, v[58:59], off nt
	v_lshl_add_u64 v[58:59], v[24:25], 0, s[4:5]
	global_load_dword v108, v[58:59], off nt
	v_lshl_add_u64 v[58:59], v[22:23], 0, s[4:5]
	global_load_dword v109, v[58:59], off nt
	v_lshl_add_u64 v[58:59], v[20:21], 0, s[4:5]
	global_load_dword v110, v[58:59], off nt
	v_lshl_add_u64 v[58:59], v[18:19], 0, s[4:5]
	global_load_dword v111, v[58:59], off nt
	s_add_u32 s4, s4, 0x58000
	s_addc_u32 s5, s5, 0
	v_lshl_add_u64 v[58:59], v[32:33], 0, s[4:5]
	global_load_dword v112, v[58:59], off nt
	v_lshl_add_u64 v[58:59], v[30:31], 0, s[4:5]
	global_load_dword v113, v[58:59], off nt
	v_lshl_add_u64 v[58:59], v[28:29], 0, s[4:5]
	global_load_dword v114, v[58:59], off nt
	v_lshl_add_u64 v[58:59], v[26:27], 0, s[4:5]
	global_load_dword v115, v[58:59], off nt
	v_lshl_add_u64 v[58:59], v[24:25], 0, s[4:5]
	global_load_dword v116, v[58:59], off nt
	v_lshl_add_u64 v[58:59], v[22:23], 0, s[4:5]
	global_load_dword v117, v[58:59], off nt
	v_lshl_add_u64 v[58:59], v[20:21], 0, s[4:5]
	global_load_dword v118, v[58:59], off nt
	v_lshl_add_u64 v[58:59], v[18:19], 0, s[4:5]
	global_load_dword v119, v[58:59], off nt
	s_add_u32 s4, s4, 0x58000
	s_addc_u32 s5, s5, 0
	v_lshl_add_u64 v[58:59], v[32:33], 0, s[4:5]
	global_load_dword v120, v[58:59], off nt
	v_lshl_add_u64 v[58:59], v[30:31], 0, s[4:5]
	global_load_dword v121, v[58:59], off nt
	v_lshl_add_u64 v[58:59], v[28:29], 0, s[4:5]
	global_load_dword v122, v[58:59], off nt
	v_lshl_add_u64 v[58:59], v[26:27], 0, s[4:5]
	global_load_dword v123, v[58:59], off nt
	v_lshl_add_u64 v[58:59], v[24:25], 0, s[4:5]
	global_load_dword v124, v[58:59], off nt
	v_lshl_add_u64 v[58:59], v[22:23], 0, s[4:5]
	global_load_dword v125, v[58:59], off nt
	v_lshl_add_u64 v[58:59], v[20:21], 0, s[4:5]
	global_load_dword v126, v[58:59], off nt
	v_lshl_add_u64 v[58:59], v[18:19], 0, s[4:5]
	global_load_dword v127, v[58:59], off nt
	s_add_u32 s4, s4, 0x58000
	s_addc_u32 s5, s5, 0
	v_add_u32_e32 v60, 0x400, v56
	s_waitcnt vmcnt(30)
	ds_write2_b32 v56, v64, v65 offset1:66
	s_waitcnt vmcnt(28)
	ds_write2_b32 v56, v66, v67 offset0:132 offset1:198
	s_waitcnt vmcnt(26)
	ds_write2_b32 v60, v100, v101 offset0:8 offset1:74
	s_waitcnt vmcnt(24)
	ds_write2_b32 v60, v102, v103 offset0:140 offset1:206
	v_add_u32_e32 v56, 0x840, v56
	v_add_u32_e32 v60, 0x400, v56
	s_waitcnt vmcnt(22)
	ds_write2_b32 v56, v104, v105 offset1:66
	s_waitcnt vmcnt(20)
	ds_write2_b32 v56, v106, v107 offset0:132 offset1:198
	s_waitcnt vmcnt(18)
	ds_write2_b32 v60, v108, v109 offset0:8 offset1:74
	s_waitcnt vmcnt(16)
	ds_write2_b32 v60, v110, v111 offset0:140 offset1:206
	v_add_u32_e32 v56, 0x840, v56
	v_add_u32_e32 v60, 0x400, v56
	s_waitcnt vmcnt(14)
	ds_write2_b32 v56, v112, v113 offset1:66
	s_waitcnt vmcnt(12)
	ds_write2_b32 v56, v114, v115 offset0:132 offset1:198
	s_waitcnt vmcnt(10)
	ds_write2_b32 v60, v116, v117 offset0:8 offset1:74
	s_waitcnt vmcnt(8)
	ds_write2_b32 v60, v118, v119 offset0:140 offset1:206
	v_add_u32_e32 v56, 0x840, v56
	v_add_u32_e32 v60, 0x400, v56
	s_waitcnt vmcnt(6)
	ds_write2_b32 v56, v120, v121 offset1:66
	s_waitcnt vmcnt(4)
	ds_write2_b32 v56, v122, v123 offset0:132 offset1:198
	s_waitcnt vmcnt(2)
	ds_write2_b32 v60, v124, v125 offset0:8 offset1:74
	s_waitcnt vmcnt(0)
	ds_write2_b32 v60, v126, v127 offset0:140 offset1:206
	v_add_u32_e32 v56, 0x840, v56
	s_waitcnt lgkmcnt(0)
	ds_read2_b32 v[24:25], v36 offset0:33 offset1:41
	ds_read2_b32 v[26:27], v36 offset1:8
	s_lshl_b32 s4, s12, 6
	s_and_b32 s5, s13, 0x60
	s_and_b32 s4, s4, 0x3f00
	ds_read2_b32 v[28:29], v36 offset0:66 offset1:74
	ds_read2_b32 v[30:31], v36 offset0:99 offset1:107
	ds_read2_b32 v[32:33], v36 offset0:132 offset1:140
	ds_read2_b32 v[56:57], v36 offset0:165 offset1:173
	ds_read2_b32 v[58:59], v36 offset0:198 offset1:206
	ds_read2_b32 v[60:61], v36 offset0:231 offset1:239
	s_or_b32 s4, s4, s5
	s_and_b32 s5, 0xffff, s7
	s_lshl_b32 s76, s5, 1
	s_waitcnt lgkmcnt(6)
	v_cvt_pk_bf16_f32 v18, v26, v24
	v_or_b32_e32 v24, s4, v35
	v_lshl_add_u64 v[22:23], v[4:5], 0, s[76:77]
	v_lshlrev_b32_e32 v144, 12, v24
	v_or_b32_e32 v24, s4, v37
	v_lshl_add_u64 v[62:63], v[22:23], 0, v[144:145]
	v_lshlrev_b32_e32 v144, 12, v24
	s_waitcnt lgkmcnt(4)
	v_cvt_pk_bf16_f32 v19, v28, v30
	s_waitcnt lgkmcnt(2)
	v_cvt_pk_bf16_f32 v20, v32, v56
	s_waitcnt lgkmcnt(0)
	v_cvt_pk_bf16_f32 v21, v58, v60
	global_store_dwordx4 v[62:63], v[18:21], off
	s_nop 1
	v_cvt_pk_bf16_f32 v18, v27, v25
	v_lshl_add_u64 v[24:25], v[22:23], 0, v[144:145]
	v_cvt_pk_bf16_f32 v19, v29, v31
	v_cvt_pk_bf16_f32 v20, v33, v57
	v_cvt_pk_bf16_f32 v21, v59, v61
	global_store_dwordx4 v[24:25], v[18:21], off
	ds_read2_b32 v[24:25], v36 offset0:16 offset1:24
	ds_read2_b32 v[26:27], v36 offset0:49 offset1:57
	ds_read2_b32 v[28:29], v36 offset0:82 offset1:90
	ds_read2_b32 v[30:31], v36 offset0:115 offset1:123
	ds_read2_b32 v[32:33], v36 offset0:148 offset1:156
	ds_read2_b32 v[56:57], v36 offset0:181 offset1:189
	ds_read2_b32 v[58:59], v36 offset0:214 offset1:222
	ds_read2_b32 v[60:61], v36 offset0:247 offset1:255
	s_waitcnt lgkmcnt(6)
	v_cvt_pk_bf16_f32 v18, v24, v26
	v_or_b32_e32 v24, s4, v38
	v_lshlrev_b32_e32 v144, 12, v24
	v_or_b32_e32 v24, s4, v39
	v_lshl_add_u64 v[62:63], v[22:23], 0, v[144:145]
	v_lshlrev_b32_e32 v144, 12, v24
	s_waitcnt lgkmcnt(4)
	v_cvt_pk_bf16_f32 v19, v28, v30
	s_waitcnt lgkmcnt(2)
	v_cvt_pk_bf16_f32 v20, v32, v56
	s_waitcnt lgkmcnt(0)
	v_cvt_pk_bf16_f32 v21, v58, v60
	v_lshl_add_u64 v[22:23], v[22:23], 0, v[144:145]
	global_store_dwordx4 v[62:63], v[18:21], off
	s_nop 1
	v_cvt_pk_bf16_f32 v18, v25, v27
	v_cvt_pk_bf16_f32 v19, v29, v31
	v_cvt_pk_bf16_f32 v20, v33, v57
	v_cvt_pk_bf16_f32 v21, v59, v61
	global_store_dwordx4 v[22:23], v[18:21], off
	s_waitcnt lgkmcnt(0)

.LBB0_838:
	v_lshl_add_u64 v[58:59], v[32:33], 0, s[4:5]
	global_load_dword v64, v[58:59], off nt
	v_lshl_add_u64 v[58:59], v[30:31], 0, s[4:5]
	global_load_dword v65, v[58:59], off nt
	v_lshl_add_u64 v[58:59], v[28:29], 0, s[4:5]
	global_load_dword v66, v[58:59], off nt
	v_lshl_add_u64 v[58:59], v[26:27], 0, s[4:5]
	global_load_dword v67, v[58:59], off nt
	v_lshl_add_u64 v[58:59], v[24:25], 0, s[4:5]
	global_load_dword v100, v[58:59], off nt
	v_lshl_add_u64 v[58:59], v[22:23], 0, s[4:5]
	global_load_dword v101, v[58:59], off nt
	v_lshl_add_u64 v[58:59], v[20:21], 0, s[4:5]
	global_load_dword v102, v[58:59], off nt
	v_lshl_add_u64 v[58:59], v[18:19], 0, s[4:5]
	global_load_dword v103, v[58:59], off nt
	s_add_u32 s4, s4, 0x20000
	s_addc_u32 s5, s5, 0
	v_lshl_add_u64 v[58:59], v[32:33], 0, s[4:5]
	global_load_dword v104, v[58:59], off nt
	v_lshl_add_u64 v[58:59], v[30:31], 0, s[4:5]
	global_load_dword v105, v[58:59], off nt
	v_lshl_add_u64 v[58:59], v[28:29], 0, s[4:5]
	global_load_dword v106, v[58:59], off nt
	v_lshl_add_u64 v[58:59], v[26:27], 0, s[4:5]
	global_load_dword v107, v[58:59], off nt
	v_lshl_add_u64 v[58:59], v[24:25], 0, s[4:5]
	global_load_dword v108, v[58:59], off nt
	v_lshl_add_u64 v[58:59], v[22:23], 0, s[4:5]
	global_load_dword v109, v[58:59], off nt
	v_lshl_add_u64 v[58:59], v[20:21], 0, s[4:5]
	global_load_dword v110, v[58:59], off nt
	v_lshl_add_u64 v[58:59], v[18:19], 0, s[4:5]
	global_load_dword v111, v[58:59], off nt
	s_add_u32 s4, s4, 0x20000
	s_addc_u32 s5, s5, 0
	v_lshl_add_u64 v[58:59], v[32:33], 0, s[4:5]
	global_load_dword v112, v[58:59], off nt
	v_lshl_add_u64 v[58:59], v[30:31], 0, s[4:5]
	global_load_dword v113, v[58:59], off nt
	v_lshl_add_u64 v[58:59], v[28:29], 0, s[4:5]
	global_load_dword v114, v[58:59], off nt
	v_lshl_add_u64 v[58:59], v[26:27], 0, s[4:5]
	global_load_dword v115, v[58:59], off nt
	v_lshl_add_u64 v[58:59], v[24:25], 0, s[4:5]
	global_load_dword v116, v[58:59], off nt
	v_lshl_add_u64 v[58:59], v[22:23], 0, s[4:5]
	global_load_dword v117, v[58:59], off nt
	v_lshl_add_u64 v[58:59], v[20:21], 0, s[4:5]
	global_load_dword v118, v[58:59], off nt
	v_lshl_add_u64 v[58:59], v[18:19], 0, s[4:5]
	global_load_dword v119, v[58:59], off nt
	s_add_u32 s4, s4, 0x20000
	s_addc_u32 s5, s5, 0
	v_lshl_add_u64 v[58:59], v[32:33], 0, s[4:5]
	global_load_dword v120, v[58:59], off nt
	v_lshl_add_u64 v[58:59], v[30:31], 0, s[4:5]
	global_load_dword v121, v[58:59], off nt
	v_lshl_add_u64 v[58:59], v[28:29], 0, s[4:5]
	global_load_dword v122, v[58:59], off nt
	v_lshl_add_u64 v[58:59], v[26:27], 0, s[4:5]
	global_load_dword v123, v[58:59], off nt
	v_lshl_add_u64 v[58:59], v[24:25], 0, s[4:5]
	global_load_dword v124, v[58:59], off nt
	v_lshl_add_u64 v[58:59], v[22:23], 0, s[4:5]
	global_load_dword v125, v[58:59], off nt
	v_lshl_add_u64 v[58:59], v[20:21], 0, s[4:5]
	global_load_dword v126, v[58:59], off nt
	v_lshl_add_u64 v[58:59], v[18:19], 0, s[4:5]
	global_load_dword v127, v[58:59], off nt
	s_add_u32 s4, s4, 0x20000
	s_addc_u32 s5, s5, 0
	v_add_u32_e32 v60, 0x400, v56
	s_waitcnt vmcnt(30)
	ds_write2_b32 v56, v64, v65 offset1:66
	s_waitcnt vmcnt(28)
	ds_write2_b32 v56, v66, v67 offset0:132 offset1:198
	s_waitcnt vmcnt(26)
	ds_write2_b32 v60, v100, v101 offset0:8 offset1:74
	s_waitcnt vmcnt(24)
	ds_write2_b32 v60, v102, v103 offset0:140 offset1:206
	v_add_u32_e32 v56, 0x840, v56
	v_add_u32_e32 v60, 0x400, v56
	s_waitcnt vmcnt(22)
	ds_write2_b32 v56, v104, v105 offset1:66
	s_waitcnt vmcnt(20)
	ds_write2_b32 v56, v106, v107 offset0:132 offset1:198
	s_waitcnt vmcnt(18)
	ds_write2_b32 v60, v108, v109 offset0:8 offset1:74
	s_waitcnt vmcnt(16)
	ds_write2_b32 v60, v110, v111 offset0:140 offset1:206
	v_add_u32_e32 v56, 0x840, v56
	v_add_u32_e32 v60, 0x400, v56
	s_waitcnt vmcnt(14)
	ds_write2_b32 v56, v112, v113 offset1:66
	s_waitcnt vmcnt(12)
	ds_write2_b32 v56, v114, v115 offset0:132 offset1:198
	s_waitcnt vmcnt(10)
	ds_write2_b32 v60, v116, v117 offset0:8 offset1:74
	s_waitcnt vmcnt(8)
	ds_write2_b32 v60, v118, v119 offset0:140 offset1:206
	v_add_u32_e32 v56, 0x840, v56
	v_add_u32_e32 v60, 0x400, v56
	s_waitcnt vmcnt(6)
	ds_write2_b32 v56, v120, v121 offset1:66
	s_waitcnt vmcnt(4)
	ds_write2_b32 v56, v122, v123 offset0:132 offset1:198
	s_waitcnt vmcnt(2)
	ds_write2_b32 v60, v124, v125 offset0:8 offset1:74
	s_waitcnt vmcnt(0)
	ds_write2_b32 v60, v126, v127 offset0:140 offset1:206
	v_add_u32_e32 v56, 0x840, v56
	s_waitcnt lgkmcnt(0)
	ds_read2_b32 v[24:25], v36 offset0:33 offset1:41
	ds_read2_b32 v[26:27], v36 offset1:8
	s_add_i32 s4, s9, 0x8e00
	s_lshl_b32 s5, s9, 5
	ds_read2_b32 v[28:29], v36 offset0:66 offset1:74
	ds_read2_b32 v[30:31], v36 offset0:99 offset1:107
	ds_read2_b32 v[32:33], v36 offset0:132 offset1:140
	ds_read2_b32 v[56:57], v36 offset0:165 offset1:173
	ds_read2_b32 v[58:59], v36 offset0:198 offset1:206
	ds_read2_b32 v[60:61], v36 offset0:231 offset1:239
	s_and_b32 s4, s4, 0xffc0
	s_and_b32 s5, s5, 0x7e0
	s_lshl_b32 s76, s4, 1
	s_waitcnt lgkmcnt(6)
	v_cvt_pk_bf16_f32 v18, v26, v24
	v_or_b32_e32 v24, s5, v35
	v_lshl_add_u64 v[22:23], v[6:7], 0, s[76:77]
	v_lshlrev_b32_e32 v144, 12, v24
	v_or_b32_e32 v24, s5, v37
	v_lshl_add_u64 v[62:63], v[22:23], 0, v[144:145]
	v_lshlrev_b32_e32 v144, 12, v24
	s_waitcnt lgkmcnt(4)
	v_cvt_pk_bf16_f32 v19, v28, v30
	s_waitcnt lgkmcnt(2)
	v_cvt_pk_bf16_f32 v20, v32, v56
	s_waitcnt lgkmcnt(0)
	v_cvt_pk_bf16_f32 v21, v58, v60
	global_store_dwordx4 v[62:63], v[18:21], off
	s_nop 1
	v_cvt_pk_bf16_f32 v18, v27, v25
	v_lshl_add_u64 v[24:25], v[22:23], 0, v[144:145]
	v_cvt_pk_bf16_f32 v19, v29, v31
	v_cvt_pk_bf16_f32 v20, v33, v57
	v_cvt_pk_bf16_f32 v21, v59, v61
	global_store_dwordx4 v[24:25], v[18:21], off
	ds_read2_b32 v[24:25], v36 offset0:16 offset1:24
	ds_read2_b32 v[26:27], v36 offset0:49 offset1:57
	ds_read2_b32 v[28:29], v36 offset0:82 offset1:90
	ds_read2_b32 v[30:31], v36 offset0:115 offset1:123
	ds_read2_b32 v[32:33], v36 offset0:148 offset1:156
	ds_read2_b32 v[56:57], v36 offset0:181 offset1:189
	ds_read2_b32 v[58:59], v36 offset0:214 offset1:222
	ds_read2_b32 v[60:61], v36 offset0:247 offset1:255
	s_waitcnt lgkmcnt(6)
	v_cvt_pk_bf16_f32 v18, v24, v26
	v_or_b32_e32 v24, s5, v38
	v_lshlrev_b32_e32 v144, 12, v24
	v_or_b32_e32 v24, s5, v39
	v_lshl_add_u64 v[62:63], v[22:23], 0, v[144:145]
	v_lshlrev_b32_e32 v144, 12, v24
	s_waitcnt lgkmcnt(4)
	v_cvt_pk_bf16_f32 v19, v28, v30
	s_waitcnt lgkmcnt(2)
	v_cvt_pk_bf16_f32 v20, v32, v56
	s_waitcnt lgkmcnt(0)
	v_cvt_pk_bf16_f32 v21, v58, v60
	v_lshl_add_u64 v[22:23], v[22:23], 0, v[144:145]
	global_store_dwordx4 v[62:63], v[18:21], off
	s_nop 1
	v_cvt_pk_bf16_f32 v18, v25, v27
	v_cvt_pk_bf16_f32 v19, v29, v31
	v_cvt_pk_bf16_f32 v20, v33, v57
	v_cvt_pk_bf16_f32 v21, v59, v61
	global_store_dwordx4 v[22:23], v[18:21], off
	s_waitcnt lgkmcnt(0)

.LBB0_843:
	v_lshl_add_u64 v[58:59], v[32:33], 0, s[4:5]
	global_load_dword v64, v[58:59], off nt
	v_lshl_add_u64 v[58:59], v[30:31], 0, s[4:5]
	global_load_dword v65, v[58:59], off nt
	v_lshl_add_u64 v[58:59], v[28:29], 0, s[4:5]
	global_load_dword v66, v[58:59], off nt
	v_lshl_add_u64 v[58:59], v[26:27], 0, s[4:5]
	global_load_dword v67, v[58:59], off nt
	v_lshl_add_u64 v[58:59], v[24:25], 0, s[4:5]
	global_load_dword v100, v[58:59], off nt
	v_lshl_add_u64 v[58:59], v[22:23], 0, s[4:5]
	global_load_dword v101, v[58:59], off nt
	v_lshl_add_u64 v[58:59], v[20:21], 0, s[4:5]
	global_load_dword v102, v[58:59], off nt
	v_lshl_add_u64 v[58:59], v[18:19], 0, s[4:5]
	global_load_dword v103, v[58:59], off nt
	s_add_u32 s4, s4, 0x40000
	s_addc_u32 s5, s5, 0
	v_lshl_add_u64 v[58:59], v[32:33], 0, s[4:5]
	global_load_dword v104, v[58:59], off nt
	v_lshl_add_u64 v[58:59], v[30:31], 0, s[4:5]
	global_load_dword v105, v[58:59], off nt
	v_lshl_add_u64 v[58:59], v[28:29], 0, s[4:5]
	global_load_dword v106, v[58:59], off nt
	v_lshl_add_u64 v[58:59], v[26:27], 0, s[4:5]
	global_load_dword v107, v[58:59], off nt
	v_lshl_add_u64 v[58:59], v[24:25], 0, s[4:5]
	global_load_dword v108, v[58:59], off nt
	v_lshl_add_u64 v[58:59], v[22:23], 0, s[4:5]
	global_load_dword v109, v[58:59], off nt
	v_lshl_add_u64 v[58:59], v[20:21], 0, s[4:5]
	global_load_dword v110, v[58:59], off nt
	v_lshl_add_u64 v[58:59], v[18:19], 0, s[4:5]
	global_load_dword v111, v[58:59], off nt
	s_add_u32 s4, s4, 0x40000
	s_addc_u32 s5, s5, 0
	v_lshl_add_u64 v[58:59], v[32:33], 0, s[4:5]
	global_load_dword v112, v[58:59], off nt
	v_lshl_add_u64 v[58:59], v[30:31], 0, s[4:5]
	global_load_dword v113, v[58:59], off nt
	v_lshl_add_u64 v[58:59], v[28:29], 0, s[4:5]
	global_load_dword v114, v[58:59], off nt
	v_lshl_add_u64 v[58:59], v[26:27], 0, s[4:5]
	global_load_dword v115, v[58:59], off nt
	v_lshl_add_u64 v[58:59], v[24:25], 0, s[4:5]
	global_load_dword v116, v[58:59], off nt
	v_lshl_add_u64 v[58:59], v[22:23], 0, s[4:5]
	global_load_dword v117, v[58:59], off nt
	v_lshl_add_u64 v[58:59], v[20:21], 0, s[4:5]
	global_load_dword v118, v[58:59], off nt
	v_lshl_add_u64 v[58:59], v[18:19], 0, s[4:5]
	global_load_dword v119, v[58:59], off nt
	s_add_u32 s4, s4, 0x40000
	s_addc_u32 s5, s5, 0
	v_lshl_add_u64 v[58:59], v[32:33], 0, s[4:5]
	global_load_dword v120, v[58:59], off nt
	v_lshl_add_u64 v[58:59], v[30:31], 0, s[4:5]
	global_load_dword v121, v[58:59], off nt
	v_lshl_add_u64 v[58:59], v[28:29], 0, s[4:5]
	global_load_dword v122, v[58:59], off nt
	v_lshl_add_u64 v[58:59], v[26:27], 0, s[4:5]
	global_load_dword v123, v[58:59], off nt
	v_lshl_add_u64 v[58:59], v[24:25], 0, s[4:5]
	global_load_dword v124, v[58:59], off nt
	v_lshl_add_u64 v[58:59], v[22:23], 0, s[4:5]
	global_load_dword v125, v[58:59], off nt
	v_lshl_add_u64 v[58:59], v[20:21], 0, s[4:5]
	global_load_dword v126, v[58:59], off nt
	v_lshl_add_u64 v[58:59], v[18:19], 0, s[4:5]
	global_load_dword v127, v[58:59], off nt
	s_add_u32 s4, s4, 0x40000
	s_addc_u32 s5, s5, 0
	v_add_u32_e32 v60, 0x400, v56
	s_waitcnt vmcnt(30)
	ds_write2_b32 v56, v64, v65 offset1:66
	s_waitcnt vmcnt(28)
	ds_write2_b32 v56, v66, v67 offset0:132 offset1:198
	s_waitcnt vmcnt(26)
	ds_write2_b32 v60, v100, v101 offset0:8 offset1:74
	s_waitcnt vmcnt(24)
	ds_write2_b32 v60, v102, v103 offset0:140 offset1:206
	v_add_u32_e32 v56, 0x840, v56
	v_add_u32_e32 v60, 0x400, v56
	s_waitcnt vmcnt(22)
	ds_write2_b32 v56, v104, v105 offset1:66
	s_waitcnt vmcnt(20)
	ds_write2_b32 v56, v106, v107 offset0:132 offset1:198
	s_waitcnt vmcnt(18)
	ds_write2_b32 v60, v108, v109 offset0:8 offset1:74
	s_waitcnt vmcnt(16)
	ds_write2_b32 v60, v110, v111 offset0:140 offset1:206
	v_add_u32_e32 v56, 0x840, v56
	v_add_u32_e32 v60, 0x400, v56
	s_waitcnt vmcnt(14)
	ds_write2_b32 v56, v112, v113 offset1:66
	s_waitcnt vmcnt(12)
	ds_write2_b32 v56, v114, v115 offset0:132 offset1:198
	s_waitcnt vmcnt(10)
	ds_write2_b32 v60, v116, v117 offset0:8 offset1:74
	s_waitcnt vmcnt(8)
	ds_write2_b32 v60, v118, v119 offset0:140 offset1:206
	v_add_u32_e32 v56, 0x840, v56
	v_add_u32_e32 v60, 0x400, v56
	s_waitcnt vmcnt(6)
	ds_write2_b32 v56, v120, v121 offset1:66
	s_waitcnt vmcnt(4)
	ds_write2_b32 v56, v122, v123 offset0:132 offset1:198
	s_waitcnt vmcnt(2)
	ds_write2_b32 v60, v124, v125 offset0:8 offset1:74
	s_waitcnt vmcnt(0)
	ds_write2_b32 v60, v126, v127 offset0:140 offset1:206
	v_add_u32_e32 v56, 0x840, v56
	s_waitcnt lgkmcnt(0)
	ds_read2_b32 v[24:25], v36 offset0:33 offset1:41
	ds_read2_b32 v[26:27], v36 offset1:8
	s_lshl_b32 s5, s9, 5
	ds_read2_b32 v[28:29], v36 offset0:66 offset1:74
	ds_read2_b32 v[30:31], v36 offset0:99 offset1:107
	ds_read2_b32 v[32:33], v36 offset0:132 offset1:140
	ds_read2_b32 v[56:57], v36 offset0:165 offset1:173
	ds_read2_b32 v[58:59], v36 offset0:198 offset1:206
	ds_read2_b32 v[60:61], v36 offset0:231 offset1:239
	s_add_i32 s4, s9, 0x9e00
	s_and_b32 s5, s5, 0xfe0
	s_and_b32 s76, s4, 0xff80
	s_waitcnt lgkmcnt(6)
	v_cvt_pk_bf16_f32 v18, v26, v24
	v_or_b32_e32 v24, s5, v35
	v_lshl_add_u64 v[22:23], v[8:9], 0, s[76:77]
	v_lshlrev_b32_e32 v144, 12, v24
	v_or_b32_e32 v24, s5, v37
	v_lshl_add_u64 v[62:63], v[22:23], 0, v[144:145]
	v_lshlrev_b32_e32 v144, 12, v24
	s_waitcnt lgkmcnt(4)
	v_cvt_pk_bf16_f32 v19, v28, v30
	s_waitcnt lgkmcnt(2)
	v_cvt_pk_bf16_f32 v20, v32, v56
	s_waitcnt lgkmcnt(0)
	v_cvt_pk_bf16_f32 v21, v58, v60
	global_store_dwordx4 v[62:63], v[18:21], off
	s_nop 1
	v_cvt_pk_bf16_f32 v18, v27, v25
	v_lshl_add_u64 v[24:25], v[22:23], 0, v[144:145]
	v_cvt_pk_bf16_f32 v19, v29, v31
	v_cvt_pk_bf16_f32 v20, v33, v57
	v_cvt_pk_bf16_f32 v21, v59, v61
	global_store_dwordx4 v[24:25], v[18:21], off
	ds_read2_b32 v[24:25], v36 offset0:16 offset1:24
	ds_read2_b32 v[26:27], v36 offset0:49 offset1:57
	ds_read2_b32 v[28:29], v36 offset0:82 offset1:90
	ds_read2_b32 v[30:31], v36 offset0:115 offset1:123
	ds_read2_b32 v[32:33], v36 offset0:148 offset1:156
	ds_read2_b32 v[56:57], v36 offset0:181 offset1:189
	ds_read2_b32 v[58:59], v36 offset0:214 offset1:222
	ds_read2_b32 v[60:61], v36 offset0:247 offset1:255
	s_waitcnt lgkmcnt(6)
	v_cvt_pk_bf16_f32 v18, v24, v26
	v_or_b32_e32 v24, s5, v38
	v_lshlrev_b32_e32 v144, 12, v24
	v_or_b32_e32 v24, s5, v39
	v_lshl_add_u64 v[62:63], v[22:23], 0, v[144:145]
	v_lshlrev_b32_e32 v144, 12, v24
	s_waitcnt lgkmcnt(4)
	v_cvt_pk_bf16_f32 v19, v28, v30
	s_waitcnt lgkmcnt(2)
	v_cvt_pk_bf16_f32 v20, v32, v56
	s_waitcnt lgkmcnt(0)
	v_cvt_pk_bf16_f32 v21, v58, v60
	v_lshl_add_u64 v[22:23], v[22:23], 0, v[144:145]
	global_store_dwordx4 v[62:63], v[18:21], off
	s_nop 1
	v_cvt_pk_bf16_f32 v18, v25, v27
	v_cvt_pk_bf16_f32 v19, v29, v31
	v_cvt_pk_bf16_f32 v20, v33, v57
	v_cvt_pk_bf16_f32 v21, v59, v61
	global_store_dwordx4 v[22:23], v[18:21], off
	s_waitcnt lgkmcnt(0)

.LBB0_848:
	v_lshl_add_u64 v[58:59], v[32:33], 0, s[4:5]
	global_load_dword v64, v[58:59], off nt
	v_lshl_add_u64 v[58:59], v[30:31], 0, s[4:5]
	global_load_dword v65, v[58:59], off nt
	v_lshl_add_u64 v[58:59], v[28:29], 0, s[4:5]
	global_load_dword v66, v[58:59], off nt
	v_lshl_add_u64 v[58:59], v[26:27], 0, s[4:5]
	global_load_dword v67, v[58:59], off nt
	v_lshl_add_u64 v[58:59], v[24:25], 0, s[4:5]
	global_load_dword v100, v[58:59], off nt
	v_lshl_add_u64 v[58:59], v[22:23], 0, s[4:5]
	global_load_dword v101, v[58:59], off nt
	v_lshl_add_u64 v[58:59], v[20:21], 0, s[4:5]
	global_load_dword v102, v[58:59], off nt
	v_lshl_add_u64 v[58:59], v[18:19], 0, s[4:5]
	global_load_dword v103, v[58:59], off nt
	s_add_u32 s4, s4, 0x20000
	s_addc_u32 s5, s5, 0
	v_lshl_add_u64 v[58:59], v[32:33], 0, s[4:5]
	global_load_dword v104, v[58:59], off nt
	v_lshl_add_u64 v[58:59], v[30:31], 0, s[4:5]
	global_load_dword v105, v[58:59], off nt
	v_lshl_add_u64 v[58:59], v[28:29], 0, s[4:5]
	global_load_dword v106, v[58:59], off nt
	v_lshl_add_u64 v[58:59], v[26:27], 0, s[4:5]
	global_load_dword v107, v[58:59], off nt
	v_lshl_add_u64 v[58:59], v[24:25], 0, s[4:5]
	global_load_dword v108, v[58:59], off nt
	v_lshl_add_u64 v[58:59], v[22:23], 0, s[4:5]
	global_load_dword v109, v[58:59], off nt
	v_lshl_add_u64 v[58:59], v[20:21], 0, s[4:5]
	global_load_dword v110, v[58:59], off nt
	v_lshl_add_u64 v[58:59], v[18:19], 0, s[4:5]
	global_load_dword v111, v[58:59], off nt
	s_add_u32 s4, s4, 0x20000
	s_addc_u32 s5, s5, 0
	v_lshl_add_u64 v[58:59], v[32:33], 0, s[4:5]
	global_load_dword v112, v[58:59], off nt
	v_lshl_add_u64 v[58:59], v[30:31], 0, s[4:5]
	global_load_dword v113, v[58:59], off nt
	v_lshl_add_u64 v[58:59], v[28:29], 0, s[4:5]
	global_load_dword v114, v[58:59], off nt
	v_lshl_add_u64 v[58:59], v[26:27], 0, s[4:5]
	global_load_dword v115, v[58:59], off nt
	v_lshl_add_u64 v[58:59], v[24:25], 0, s[4:5]
	global_load_dword v116, v[58:59], off nt
	v_lshl_add_u64 v[58:59], v[22:23], 0, s[4:5]
	global_load_dword v117, v[58:59], off nt
	v_lshl_add_u64 v[58:59], v[20:21], 0, s[4:5]
	global_load_dword v118, v[58:59], off nt
	v_lshl_add_u64 v[58:59], v[18:19], 0, s[4:5]
	global_load_dword v119, v[58:59], off nt
	s_add_u32 s4, s4, 0x20000
	s_addc_u32 s5, s5, 0
	v_lshl_add_u64 v[58:59], v[32:33], 0, s[4:5]
	global_load_dword v120, v[58:59], off nt
	v_lshl_add_u64 v[58:59], v[30:31], 0, s[4:5]
	global_load_dword v121, v[58:59], off nt
	v_lshl_add_u64 v[58:59], v[28:29], 0, s[4:5]
	global_load_dword v122, v[58:59], off nt
	v_lshl_add_u64 v[58:59], v[26:27], 0, s[4:5]
	global_load_dword v123, v[58:59], off nt
	v_lshl_add_u64 v[58:59], v[24:25], 0, s[4:5]
	global_load_dword v124, v[58:59], off nt
	v_lshl_add_u64 v[58:59], v[22:23], 0, s[4:5]
	global_load_dword v125, v[58:59], off nt
	v_lshl_add_u64 v[58:59], v[20:21], 0, s[4:5]
	global_load_dword v126, v[58:59], off nt
	v_lshl_add_u64 v[58:59], v[18:19], 0, s[4:5]
	global_load_dword v127, v[58:59], off nt
	s_add_u32 s4, s4, 0x20000
	s_addc_u32 s5, s5, 0
	v_add_u32_e32 v60, 0x400, v56
	s_waitcnt vmcnt(30)
	ds_write2_b32 v56, v64, v65 offset1:66
	s_waitcnt vmcnt(28)
	ds_write2_b32 v56, v66, v67 offset0:132 offset1:198
	s_waitcnt vmcnt(26)
	ds_write2_b32 v60, v100, v101 offset0:8 offset1:74
	s_waitcnt vmcnt(24)
	ds_write2_b32 v60, v102, v103 offset0:140 offset1:206
	v_add_u32_e32 v56, 0x840, v56
	v_add_u32_e32 v60, 0x400, v56
	s_waitcnt vmcnt(22)
	ds_write2_b32 v56, v104, v105 offset1:66
	s_waitcnt vmcnt(20)
	ds_write2_b32 v56, v106, v107 offset0:132 offset1:198
	s_waitcnt vmcnt(18)
	ds_write2_b32 v60, v108, v109 offset0:8 offset1:74
	s_waitcnt vmcnt(16)
	ds_write2_b32 v60, v110, v111 offset0:140 offset1:206
	v_add_u32_e32 v56, 0x840, v56
	v_add_u32_e32 v60, 0x400, v56
	s_waitcnt vmcnt(14)
	ds_write2_b32 v56, v112, v113 offset1:66
	s_waitcnt vmcnt(12)
	ds_write2_b32 v56, v114, v115 offset0:132 offset1:198
	s_waitcnt vmcnt(10)
	ds_write2_b32 v60, v116, v117 offset0:8 offset1:74
	s_waitcnt vmcnt(8)
	ds_write2_b32 v60, v118, v119 offset0:140 offset1:206
	v_add_u32_e32 v56, 0x840, v56
	v_add_u32_e32 v60, 0x400, v56
	s_waitcnt vmcnt(6)
	ds_write2_b32 v56, v120, v121 offset1:66
	s_waitcnt vmcnt(4)
	ds_write2_b32 v56, v122, v123 offset0:132 offset1:198
	s_waitcnt vmcnt(2)
	ds_write2_b32 v60, v124, v125 offset0:8 offset1:74
	s_waitcnt vmcnt(0)
	ds_write2_b32 v60, v126, v127 offset0:140 offset1:206
	v_add_u32_e32 v56, 0x840, v56
	s_waitcnt lgkmcnt(0)
	ds_read2_b32 v[24:25], v36 offset0:33 offset1:41
	ds_read2_b32 v[26:27], v36 offset1:8
	s_lshl_b32 s5, s9, 5
	s_and_b32 s5, s5, 0x7e0
	s_add_i32 s4, s9, 0xb400
	ds_read2_b32 v[28:29], v36 offset0:66 offset1:74
	ds_read2_b32 v[30:31], v36 offset0:99 offset1:107
	s_waitcnt lgkmcnt(2)
	v_cvt_pk_bf16_f32 v18, v26, v24
	ds_read2_b32 v[32:33], v36 offset0:132 offset1:140
	ds_read2_b32 v[56:57], v36 offset0:165 offset1:173
	ds_read2_b32 v[58:59], v36 offset0:198 offset1:206
	ds_read2_b32 v[60:61], v36 offset0:231 offset1:239
	v_or_b32_e32 v24, s5, v35
	s_and_b32 s4, s4, 0xffc0
	v_mul_u32_u24_e32 v24, 0x1600, v24
	s_lshl_b32 s76, s4, 1
	v_lshlrev_b32_e32 v144, 1, v24
	v_or_b32_e32 v24, s5, v37
	v_lshl_add_u64 v[22:23], v[10:11], 0, s[76:77]
	v_mul_u32_u24_e32 v24, 0x1600, v24
	v_lshl_add_u64 v[62:63], v[22:23], 0, v[144:145]
	v_lshlrev_b32_e32 v144, 1, v24
	s_waitcnt lgkmcnt(4)
	v_cvt_pk_bf16_f32 v19, v28, v30
	s_waitcnt lgkmcnt(2)
	v_cvt_pk_bf16_f32 v20, v32, v56
	s_waitcnt lgkmcnt(0)
	v_cvt_pk_bf16_f32 v21, v58, v60
	global_store_dwordx4 v[62:63], v[18:21], off
	s_nop 1
	v_cvt_pk_bf16_f32 v18, v27, v25
	v_lshl_add_u64 v[24:25], v[22:23], 0, v[144:145]
	v_cvt_pk_bf16_f32 v19, v29, v31
	v_cvt_pk_bf16_f32 v20, v33, v57
	v_cvt_pk_bf16_f32 v21, v59, v61
	global_store_dwordx4 v[24:25], v[18:21], off
	ds_read2_b32 v[24:25], v36 offset0:16 offset1:24
	ds_read2_b32 v[26:27], v36 offset0:49 offset1:57
	s_waitcnt lgkmcnt(0)
	v_cvt_pk_bf16_f32 v18, v24, v26
	ds_read2_b32 v[28:29], v36 offset0:82 offset1:90
	ds_read2_b32 v[30:31], v36 offset0:115 offset1:123
	ds_read2_b32 v[32:33], v36 offset0:148 offset1:156
	ds_read2_b32 v[56:57], v36 offset0:181 offset1:189
	ds_read2_b32 v[58:59], v36 offset0:214 offset1:222
	ds_read2_b32 v[60:61], v36 offset0:247 offset1:255
	v_or_b32_e32 v24, s5, v38
	v_mul_u32_u24_e32 v24, 0x1600, v24
	v_lshlrev_b32_e32 v144, 1, v24
	v_or_b32_e32 v24, s5, v39
	v_mul_u32_u24_e32 v24, 0x1600, v24
	v_lshl_add_u64 v[62:63], v[22:23], 0, v[144:145]
	v_lshlrev_b32_e32 v144, 1, v24
	s_waitcnt lgkmcnt(4)
	v_cvt_pk_bf16_f32 v19, v28, v30
	s_waitcnt lgkmcnt(2)
	v_cvt_pk_bf16_f32 v20, v32, v56
	s_waitcnt lgkmcnt(0)
	v_cvt_pk_bf16_f32 v21, v58, v60
	v_lshl_add_u64 v[22:23], v[22:23], 0, v[144:145]
	global_store_dwordx4 v[62:63], v[18:21], off
	s_nop 1
	v_cvt_pk_bf16_f32 v18, v25, v27
	v_cvt_pk_bf16_f32 v19, v29, v31
	v_cvt_pk_bf16_f32 v20, v33, v57
	v_cvt_pk_bf16_f32 v21, v59, v61
	global_store_dwordx4 v[22:23], v[18:21], off
	s_waitcnt lgkmcnt(0)

.LBB0_853:
	v_lshl_add_u64 v[58:59], v[32:33], 0, s[4:5]
	global_load_dword v64, v[58:59], off nt
	v_lshl_add_u64 v[58:59], v[30:31], 0, s[4:5]
	global_load_dword v65, v[58:59], off nt
	v_lshl_add_u64 v[58:59], v[28:29], 0, s[4:5]
	global_load_dword v66, v[58:59], off nt
	v_lshl_add_u64 v[58:59], v[26:27], 0, s[4:5]
	global_load_dword v67, v[58:59], off nt
	v_lshl_add_u64 v[58:59], v[24:25], 0, s[4:5]
	global_load_dword v100, v[58:59], off nt
	v_lshl_add_u64 v[58:59], v[22:23], 0, s[4:5]
	global_load_dword v101, v[58:59], off nt
	v_lshl_add_u64 v[58:59], v[20:21], 0, s[4:5]
	global_load_dword v102, v[58:59], off nt
	v_lshl_add_u64 v[58:59], v[18:19], 0, s[4:5]
	global_load_dword v103, v[58:59], off nt
	s_add_u32 s4, s4, 0x58000
	s_addc_u32 s5, s5, 0
	v_lshl_add_u64 v[58:59], v[32:33], 0, s[4:5]
	global_load_dword v104, v[58:59], off nt
	v_lshl_add_u64 v[58:59], v[30:31], 0, s[4:5]
	global_load_dword v105, v[58:59], off nt
	v_lshl_add_u64 v[58:59], v[28:29], 0, s[4:5]
	global_load_dword v106, v[58:59], off nt
	v_lshl_add_u64 v[58:59], v[26:27], 0, s[4:5]
	global_load_dword v107, v[58:59], off nt
	v_lshl_add_u64 v[58:59], v[24:25], 0, s[4:5]
	global_load_dword v108, v[58:59], off nt
	v_lshl_add_u64 v[58:59], v[22:23], 0, s[4:5]
	global_load_dword v109, v[58:59], off nt
	v_lshl_add_u64 v[58:59], v[20:21], 0, s[4:5]
	global_load_dword v110, v[58:59], off nt
	v_lshl_add_u64 v[58:59], v[18:19], 0, s[4:5]
	global_load_dword v111, v[58:59], off nt
	s_add_u32 s4, s4, 0x58000
	s_addc_u32 s5, s5, 0
	v_lshl_add_u64 v[58:59], v[32:33], 0, s[4:5]
	global_load_dword v112, v[58:59], off nt
	v_lshl_add_u64 v[58:59], v[30:31], 0, s[4:5]
	global_load_dword v113, v[58:59], off nt
	v_lshl_add_u64 v[58:59], v[28:29], 0, s[4:5]
	global_load_dword v114, v[58:59], off nt
	v_lshl_add_u64 v[58:59], v[26:27], 0, s[4:5]
	global_load_dword v115, v[58:59], off nt
	v_lshl_add_u64 v[58:59], v[24:25], 0, s[4:5]
	global_load_dword v116, v[58:59], off nt
	v_lshl_add_u64 v[58:59], v[22:23], 0, s[4:5]
	global_load_dword v117, v[58:59], off nt
	v_lshl_add_u64 v[58:59], v[20:21], 0, s[4:5]
	global_load_dword v118, v[58:59], off nt
	v_lshl_add_u64 v[58:59], v[18:19], 0, s[4:5]
	global_load_dword v119, v[58:59], off nt
	s_add_u32 s4, s4, 0x58000
	s_addc_u32 s5, s5, 0
	v_lshl_add_u64 v[58:59], v[32:33], 0, s[4:5]
	global_load_dword v120, v[58:59], off nt
	v_lshl_add_u64 v[58:59], v[30:31], 0, s[4:5]
	global_load_dword v121, v[58:59], off nt
	v_lshl_add_u64 v[58:59], v[28:29], 0, s[4:5]
	global_load_dword v122, v[58:59], off nt
	v_lshl_add_u64 v[58:59], v[26:27], 0, s[4:5]
	global_load_dword v123, v[58:59], off nt
	v_lshl_add_u64 v[58:59], v[24:25], 0, s[4:5]
	global_load_dword v124, v[58:59], off nt
	v_lshl_add_u64 v[58:59], v[22:23], 0, s[4:5]
	global_load_dword v125, v[58:59], off nt
	v_lshl_add_u64 v[58:59], v[20:21], 0, s[4:5]
	global_load_dword v126, v[58:59], off nt
	v_lshl_add_u64 v[58:59], v[18:19], 0, s[4:5]
	global_load_dword v127, v[58:59], off nt
	s_add_u32 s4, s4, 0x58000
	s_addc_u32 s5, s5, 0
	v_add_u32_e32 v60, 0x400, v56
	s_waitcnt vmcnt(30)
	ds_write2_b32 v56, v64, v65 offset1:66
	s_waitcnt vmcnt(28)
	ds_write2_b32 v56, v66, v67 offset0:132 offset1:198
	s_waitcnt vmcnt(26)
	ds_write2_b32 v60, v100, v101 offset0:8 offset1:74
	s_waitcnt vmcnt(24)
	ds_write2_b32 v60, v102, v103 offset0:140 offset1:206
	v_add_u32_e32 v56, 0x840, v56
	v_add_u32_e32 v60, 0x400, v56
	s_waitcnt vmcnt(22)
	ds_write2_b32 v56, v104, v105 offset1:66
	s_waitcnt vmcnt(20)
	ds_write2_b32 v56, v106, v107 offset0:132 offset1:198
	s_waitcnt vmcnt(18)
	ds_write2_b32 v60, v108, v109 offset0:8 offset1:74
	s_waitcnt vmcnt(16)
	ds_write2_b32 v60, v110, v111 offset0:140 offset1:206
	v_add_u32_e32 v56, 0x840, v56
	v_add_u32_e32 v60, 0x400, v56
	s_waitcnt vmcnt(14)
	ds_write2_b32 v56, v112, v113 offset1:66
	s_waitcnt vmcnt(12)
	ds_write2_b32 v56, v114, v115 offset0:132 offset1:198
	s_waitcnt vmcnt(10)
	ds_write2_b32 v60, v116, v117 offset0:8 offset1:74
	s_waitcnt vmcnt(8)
	ds_write2_b32 v60, v118, v119 offset0:140 offset1:206
	v_add_u32_e32 v56, 0x840, v56
	v_add_u32_e32 v60, 0x400, v56
	s_waitcnt vmcnt(6)
	ds_write2_b32 v56, v120, v121 offset1:66
	s_waitcnt vmcnt(4)
	ds_write2_b32 v56, v122, v123 offset0:132 offset1:198
	s_waitcnt vmcnt(2)
	ds_write2_b32 v60, v124, v125 offset0:8 offset1:74
	s_waitcnt vmcnt(0)
	ds_write2_b32 v60, v126, v127 offset0:140 offset1:206
	v_add_u32_e32 v56, 0x840, v56
	s_waitcnt lgkmcnt(0)
	ds_read2_b32 v[24:25], v36 offset0:33 offset1:41
	ds_read2_b32 v[26:27], v36 offset1:8
	s_lshl_b32 s4, s12, 6
	s_and_b32 s4, s4, 0x3f00
	s_and_b32 s5, s13, 0x60
	s_or_b32 s4, s4, s5
	ds_read2_b32 v[28:29], v36 offset0:66 offset1:74
	ds_read2_b32 v[30:31], v36 offset0:99 offset1:107
	ds_read2_b32 v[32:33], v36 offset0:132 offset1:140
	ds_read2_b32 v[56:57], v36 offset0:165 offset1:173
	ds_read2_b32 v[58:59], v36 offset0:198 offset1:206
	ds_read2_b32 v[60:61], v36 offset0:231 offset1:239
	s_bitset1_b32 s4, 7
	s_and_b32 s5, 0xffff, s7
	s_lshl_b32 s76, s5, 1
	s_waitcnt lgkmcnt(6)
	v_cvt_pk_bf16_f32 v18, v26, v24
	v_or_b32_e32 v24, s4, v35
	v_lshl_add_u64 v[22:23], v[12:13], 0, s[76:77]
	v_lshlrev_b32_e32 v144, 12, v24
	v_or_b32_e32 v24, s4, v37
	v_lshl_add_u64 v[62:63], v[22:23], 0, v[144:145]
	v_lshlrev_b32_e32 v144, 12, v24
	s_waitcnt lgkmcnt(4)
	v_cvt_pk_bf16_f32 v19, v28, v30
	s_waitcnt lgkmcnt(2)
	v_cvt_pk_bf16_f32 v20, v32, v56
	s_waitcnt lgkmcnt(0)
	v_cvt_pk_bf16_f32 v21, v58, v60
	global_store_dwordx4 v[62:63], v[18:21], off
	s_nop 1
	v_cvt_pk_bf16_f32 v18, v27, v25
	v_lshl_add_u64 v[24:25], v[22:23], 0, v[144:145]
	v_cvt_pk_bf16_f32 v19, v29, v31
	v_cvt_pk_bf16_f32 v20, v33, v57
	v_cvt_pk_bf16_f32 v21, v59, v61
	global_store_dwordx4 v[24:25], v[18:21], off
	ds_read2_b32 v[24:25], v36 offset0:16 offset1:24
	ds_read2_b32 v[26:27], v36 offset0:49 offset1:57
	ds_read2_b32 v[28:29], v36 offset0:82 offset1:90
	ds_read2_b32 v[30:31], v36 offset0:115 offset1:123
	ds_read2_b32 v[32:33], v36 offset0:148 offset1:156
	ds_read2_b32 v[56:57], v36 offset0:181 offset1:189
	ds_read2_b32 v[58:59], v36 offset0:214 offset1:222
	ds_read2_b32 v[60:61], v36 offset0:247 offset1:255
	s_waitcnt lgkmcnt(6)
	v_cvt_pk_bf16_f32 v18, v24, v26
	v_or_b32_e32 v24, s4, v38
	v_lshlrev_b32_e32 v144, 12, v24
	v_or_b32_e32 v24, s4, v39
	v_lshl_add_u64 v[62:63], v[22:23], 0, v[144:145]
	v_lshlrev_b32_e32 v144, 12, v24
	s_waitcnt lgkmcnt(4)
	v_cvt_pk_bf16_f32 v19, v28, v30
	s_waitcnt lgkmcnt(2)
	v_cvt_pk_bf16_f32 v20, v32, v56
	s_waitcnt lgkmcnt(0)
	v_cvt_pk_bf16_f32 v21, v58, v60
	v_lshl_add_u64 v[22:23], v[22:23], 0, v[144:145]
	global_store_dwordx4 v[62:63], v[18:21], off
	s_nop 1
	v_cvt_pk_bf16_f32 v18, v25, v27
	v_cvt_pk_bf16_f32 v19, v29, v31
	v_cvt_pk_bf16_f32 v20, v33, v57
	v_cvt_pk_bf16_f32 v21, v59, v61
	global_store_dwordx4 v[22:23], v[18:21], off
	s_waitcnt lgkmcnt(0)

.LBB0_858:
	v_lshl_add_u64 v[58:59], v[32:33], 0, s[4:5]
	global_load_dword v64, v[58:59], off nt
	v_lshl_add_u64 v[58:59], v[30:31], 0, s[4:5]
	global_load_dword v65, v[58:59], off nt
	v_lshl_add_u64 v[58:59], v[28:29], 0, s[4:5]
	global_load_dword v66, v[58:59], off nt
	v_lshl_add_u64 v[58:59], v[26:27], 0, s[4:5]
	global_load_dword v67, v[58:59], off nt
	v_lshl_add_u64 v[58:59], v[24:25], 0, s[4:5]
	global_load_dword v100, v[58:59], off nt
	v_lshl_add_u64 v[58:59], v[22:23], 0, s[4:5]
	global_load_dword v101, v[58:59], off nt
	v_lshl_add_u64 v[58:59], v[20:21], 0, s[4:5]
	global_load_dword v102, v[58:59], off nt
	v_lshl_add_u64 v[58:59], v[18:19], 0, s[4:5]
	global_load_dword v103, v[58:59], off nt
	s_add_u32 s4, s4, 0x58000
	s_addc_u32 s5, s5, 0
	v_lshl_add_u64 v[58:59], v[32:33], 0, s[4:5]
	global_load_dword v104, v[58:59], off nt
	v_lshl_add_u64 v[58:59], v[30:31], 0, s[4:5]
	global_load_dword v105, v[58:59], off nt
	v_lshl_add_u64 v[58:59], v[28:29], 0, s[4:5]
	global_load_dword v106, v[58:59], off nt
	v_lshl_add_u64 v[58:59], v[26:27], 0, s[4:5]
	global_load_dword v107, v[58:59], off nt
	v_lshl_add_u64 v[58:59], v[24:25], 0, s[4:5]
	global_load_dword v108, v[58:59], off nt
	v_lshl_add_u64 v[58:59], v[22:23], 0, s[4:5]
	global_load_dword v109, v[58:59], off nt
	v_lshl_add_u64 v[58:59], v[20:21], 0, s[4:5]
	global_load_dword v110, v[58:59], off nt
	v_lshl_add_u64 v[58:59], v[18:19], 0, s[4:5]
	global_load_dword v111, v[58:59], off nt
	s_add_u32 s4, s4, 0x58000
	s_addc_u32 s5, s5, 0
	v_lshl_add_u64 v[58:59], v[32:33], 0, s[4:5]
	global_load_dword v112, v[58:59], off nt
	v_lshl_add_u64 v[58:59], v[30:31], 0, s[4:5]
	global_load_dword v113, v[58:59], off nt
	v_lshl_add_u64 v[58:59], v[28:29], 0, s[4:5]
	global_load_dword v114, v[58:59], off nt
	v_lshl_add_u64 v[58:59], v[26:27], 0, s[4:5]
	global_load_dword v115, v[58:59], off nt
	v_lshl_add_u64 v[58:59], v[24:25], 0, s[4:5]
	global_load_dword v116, v[58:59], off nt
	v_lshl_add_u64 v[58:59], v[22:23], 0, s[4:5]
	global_load_dword v117, v[58:59], off nt
	v_lshl_add_u64 v[58:59], v[20:21], 0, s[4:5]
	global_load_dword v118, v[58:59], off nt
	v_lshl_add_u64 v[58:59], v[18:19], 0, s[4:5]
	global_load_dword v119, v[58:59], off nt
	s_add_u32 s4, s4, 0x58000
	s_addc_u32 s5, s5, 0
	v_lshl_add_u64 v[58:59], v[32:33], 0, s[4:5]
	global_load_dword v120, v[58:59], off nt
	v_lshl_add_u64 v[58:59], v[30:31], 0, s[4:5]
	global_load_dword v121, v[58:59], off nt
	v_lshl_add_u64 v[58:59], v[28:29], 0, s[4:5]
	global_load_dword v122, v[58:59], off nt
	v_lshl_add_u64 v[58:59], v[26:27], 0, s[4:5]
	global_load_dword v123, v[58:59], off nt
	v_lshl_add_u64 v[58:59], v[24:25], 0, s[4:5]
	global_load_dword v124, v[58:59], off nt
	v_lshl_add_u64 v[58:59], v[22:23], 0, s[4:5]
	global_load_dword v125, v[58:59], off nt
	v_lshl_add_u64 v[58:59], v[20:21], 0, s[4:5]
	global_load_dword v126, v[58:59], off nt
	v_lshl_add_u64 v[58:59], v[18:19], 0, s[4:5]
	global_load_dword v127, v[58:59], off nt
	s_add_u32 s4, s4, 0x58000
	s_addc_u32 s5, s5, 0
	v_add_u32_e32 v60, 0x400, v56
	s_waitcnt vmcnt(30)
	ds_write2_b32 v56, v64, v65 offset1:66
	s_waitcnt vmcnt(28)
	ds_write2_b32 v56, v66, v67 offset0:132 offset1:198
	s_waitcnt vmcnt(26)
	ds_write2_b32 v60, v100, v101 offset0:8 offset1:74
	s_waitcnt vmcnt(24)
	ds_write2_b32 v60, v102, v103 offset0:140 offset1:206
	v_add_u32_e32 v56, 0x840, v56
	v_add_u32_e32 v60, 0x400, v56
	s_waitcnt vmcnt(22)
	ds_write2_b32 v56, v104, v105 offset1:66
	s_waitcnt vmcnt(20)
	ds_write2_b32 v56, v106, v107 offset0:132 offset1:198
	s_waitcnt vmcnt(18)
	ds_write2_b32 v60, v108, v109 offset0:8 offset1:74
	s_waitcnt vmcnt(16)
	ds_write2_b32 v60, v110, v111 offset0:140 offset1:206
	v_add_u32_e32 v56, 0x840, v56
	v_add_u32_e32 v60, 0x400, v56
	s_waitcnt vmcnt(14)
	ds_write2_b32 v56, v112, v113 offset1:66
	s_waitcnt vmcnt(12)
	ds_write2_b32 v56, v114, v115 offset0:132 offset1:198
	s_waitcnt vmcnt(10)
	ds_write2_b32 v60, v116, v117 offset0:8 offset1:74
	s_waitcnt vmcnt(8)
	ds_write2_b32 v60, v118, v119 offset0:140 offset1:206
	v_add_u32_e32 v56, 0x840, v56
	v_add_u32_e32 v60, 0x400, v56
	s_waitcnt vmcnt(6)
	ds_write2_b32 v56, v120, v121 offset1:66
	s_waitcnt vmcnt(4)
	ds_write2_b32 v56, v122, v123 offset0:132 offset1:198
	s_waitcnt vmcnt(2)
	ds_write2_b32 v60, v124, v125 offset0:8 offset1:74
	s_waitcnt vmcnt(0)
	ds_write2_b32 v60, v126, v127 offset0:140 offset1:206
	v_add_u32_e32 v56, 0x840, v56
	s_waitcnt lgkmcnt(0)
	ds_read2_b32 v[24:25], v36 offset0:33 offset1:41
	ds_read2_b32 v[26:27], v36 offset1:8
	s_lshl_b32 s4, s12, 6
	s_and_b32 s5, s13, 0x60
	s_and_b32 s4, s4, 0x3f00
	ds_read2_b32 v[28:29], v36 offset0:66 offset1:74
	ds_read2_b32 v[30:31], v36 offset0:99 offset1:107
	ds_read2_b32 v[32:33], v36 offset0:132 offset1:140
	ds_read2_b32 v[56:57], v36 offset0:165 offset1:173
	ds_read2_b32 v[58:59], v36 offset0:198 offset1:206
	ds_read2_b32 v[60:61], v36 offset0:231 offset1:239
	s_or_b32 s4, s4, s5
	s_and_b32 s5, 0xffff, s7
	s_lshl_b32 s76, s5, 1
	s_waitcnt lgkmcnt(6)
	v_cvt_pk_bf16_f32 v18, v26, v24
	v_or_b32_e32 v24, s4, v35
	v_lshl_add_u64 v[22:23], v[12:13], 0, s[76:77]
	v_lshlrev_b32_e32 v144, 12, v24
	v_or_b32_e32 v24, s4, v37
	v_lshl_add_u64 v[62:63], v[22:23], 0, v[144:145]
	v_lshlrev_b32_e32 v144, 12, v24
	s_waitcnt lgkmcnt(4)
	v_cvt_pk_bf16_f32 v19, v28, v30
	s_waitcnt lgkmcnt(2)
	v_cvt_pk_bf16_f32 v20, v32, v56
	s_waitcnt lgkmcnt(0)
	v_cvt_pk_bf16_f32 v21, v58, v60
	global_store_dwordx4 v[62:63], v[18:21], off
	s_nop 1
	v_cvt_pk_bf16_f32 v18, v27, v25
	v_lshl_add_u64 v[24:25], v[22:23], 0, v[144:145]
	v_cvt_pk_bf16_f32 v19, v29, v31
	v_cvt_pk_bf16_f32 v20, v33, v57
	v_cvt_pk_bf16_f32 v21, v59, v61
	global_store_dwordx4 v[24:25], v[18:21], off
	ds_read2_b32 v[24:25], v36 offset0:16 offset1:24
	ds_read2_b32 v[26:27], v36 offset0:49 offset1:57
	ds_read2_b32 v[28:29], v36 offset0:82 offset1:90
	ds_read2_b32 v[30:31], v36 offset0:115 offset1:123
	ds_read2_b32 v[32:33], v36 offset0:148 offset1:156
	ds_read2_b32 v[56:57], v36 offset0:181 offset1:189
	ds_read2_b32 v[58:59], v36 offset0:214 offset1:222
	ds_read2_b32 v[60:61], v36 offset0:247 offset1:255
	s_waitcnt lgkmcnt(6)
	v_cvt_pk_bf16_f32 v18, v24, v26
	v_or_b32_e32 v24, s4, v38
	v_lshlrev_b32_e32 v144, 12, v24
	v_or_b32_e32 v24, s4, v39
	v_lshl_add_u64 v[62:63], v[22:23], 0, v[144:145]
	v_lshlrev_b32_e32 v144, 12, v24
	s_waitcnt lgkmcnt(4)
	v_cvt_pk_bf16_f32 v19, v28, v30
	s_waitcnt lgkmcnt(2)
	v_cvt_pk_bf16_f32 v20, v32, v56
	s_waitcnt lgkmcnt(0)
	v_cvt_pk_bf16_f32 v21, v58, v60
	v_lshl_add_u64 v[22:23], v[22:23], 0, v[144:145]
	global_store_dwordx4 v[62:63], v[18:21], off
	s_nop 1
	v_cvt_pk_bf16_f32 v18, v25, v27
	v_cvt_pk_bf16_f32 v19, v29, v31
	v_cvt_pk_bf16_f32 v20, v33, v57
	v_cvt_pk_bf16_f32 v21, v59, v61
	global_store_dwordx4 v[22:23], v[18:21], off
	s_waitcnt lgkmcnt(0)

.LBB0_863:
	v_lshl_add_u64 v[58:59], v[32:33], 0, s[4:5]
	global_load_dword v64, v[58:59], off nt
	v_lshl_add_u64 v[58:59], v[30:31], 0, s[4:5]
	global_load_dword v65, v[58:59], off nt
	v_lshl_add_u64 v[58:59], v[28:29], 0, s[4:5]
	global_load_dword v66, v[58:59], off nt
	v_lshl_add_u64 v[58:59], v[26:27], 0, s[4:5]
	global_load_dword v67, v[58:59], off nt
	v_lshl_add_u64 v[58:59], v[24:25], 0, s[4:5]
	global_load_dword v100, v[58:59], off nt
	v_lshl_add_u64 v[58:59], v[22:23], 0, s[4:5]
	global_load_dword v101, v[58:59], off nt
	v_lshl_add_u64 v[58:59], v[20:21], 0, s[4:5]
	global_load_dword v102, v[58:59], off nt
	v_lshl_add_u64 v[58:59], v[18:19], 0, s[4:5]
	global_load_dword v103, v[58:59], off nt
	s_add_u32 s4, s4, 0x20000
	s_addc_u32 s5, s5, 0
	v_lshl_add_u64 v[58:59], v[32:33], 0, s[4:5]
	global_load_dword v104, v[58:59], off nt
	v_lshl_add_u64 v[58:59], v[30:31], 0, s[4:5]
	global_load_dword v105, v[58:59], off nt
	v_lshl_add_u64 v[58:59], v[28:29], 0, s[4:5]
	global_load_dword v106, v[58:59], off nt
	v_lshl_add_u64 v[58:59], v[26:27], 0, s[4:5]
	global_load_dword v107, v[58:59], off nt
	v_lshl_add_u64 v[58:59], v[24:25], 0, s[4:5]
	global_load_dword v108, v[58:59], off nt
	v_lshl_add_u64 v[58:59], v[22:23], 0, s[4:5]
	global_load_dword v109, v[58:59], off nt
	v_lshl_add_u64 v[58:59], v[20:21], 0, s[4:5]
	global_load_dword v110, v[58:59], off nt
	v_lshl_add_u64 v[58:59], v[18:19], 0, s[4:5]
	global_load_dword v111, v[58:59], off nt
	s_add_u32 s4, s4, 0x20000
	s_addc_u32 s5, s5, 0
	v_lshl_add_u64 v[58:59], v[32:33], 0, s[4:5]
	global_load_dword v112, v[58:59], off nt
	v_lshl_add_u64 v[58:59], v[30:31], 0, s[4:5]
	global_load_dword v113, v[58:59], off nt
	v_lshl_add_u64 v[58:59], v[28:29], 0, s[4:5]
	global_load_dword v114, v[58:59], off nt
	v_lshl_add_u64 v[58:59], v[26:27], 0, s[4:5]
	global_load_dword v115, v[58:59], off nt
	v_lshl_add_u64 v[58:59], v[24:25], 0, s[4:5]
	global_load_dword v116, v[58:59], off nt
	v_lshl_add_u64 v[58:59], v[22:23], 0, s[4:5]
	global_load_dword v117, v[58:59], off nt
	v_lshl_add_u64 v[58:59], v[20:21], 0, s[4:5]
	global_load_dword v118, v[58:59], off nt
	v_lshl_add_u64 v[58:59], v[18:19], 0, s[4:5]
	global_load_dword v119, v[58:59], off nt
	s_add_u32 s4, s4, 0x20000
	s_addc_u32 s5, s5, 0
	v_lshl_add_u64 v[58:59], v[32:33], 0, s[4:5]
	global_load_dword v120, v[58:59], off nt
	v_lshl_add_u64 v[58:59], v[30:31], 0, s[4:5]
	global_load_dword v121, v[58:59], off nt
	v_lshl_add_u64 v[58:59], v[28:29], 0, s[4:5]
	global_load_dword v122, v[58:59], off nt
	v_lshl_add_u64 v[58:59], v[26:27], 0, s[4:5]
	global_load_dword v123, v[58:59], off nt
	v_lshl_add_u64 v[58:59], v[24:25], 0, s[4:5]
	global_load_dword v124, v[58:59], off nt
	v_lshl_add_u64 v[58:59], v[22:23], 0, s[4:5]
	global_load_dword v125, v[58:59], off nt
	v_lshl_add_u64 v[58:59], v[20:21], 0, s[4:5]
	global_load_dword v126, v[58:59], off nt
	v_lshl_add_u64 v[58:59], v[18:19], 0, s[4:5]
	global_load_dword v127, v[58:59], off nt
	s_add_u32 s4, s4, 0x20000
	s_addc_u32 s5, s5, 0
	v_add_u32_e32 v60, 0x400, v56
	s_waitcnt vmcnt(30)
	ds_write2_b32 v56, v64, v65 offset1:66
	s_waitcnt vmcnt(28)
	ds_write2_b32 v56, v66, v67 offset0:132 offset1:198
	s_waitcnt vmcnt(26)
	ds_write2_b32 v60, v100, v101 offset0:8 offset1:74
	s_waitcnt vmcnt(24)
	ds_write2_b32 v60, v102, v103 offset0:140 offset1:206
	v_add_u32_e32 v56, 0x840, v56
	v_add_u32_e32 v60, 0x400, v56
	s_waitcnt vmcnt(22)
	ds_write2_b32 v56, v104, v105 offset1:66
	s_waitcnt vmcnt(20)
	ds_write2_b32 v56, v106, v107 offset0:132 offset1:198
	s_waitcnt vmcnt(18)
	ds_write2_b32 v60, v108, v109 offset0:8 offset1:74
	s_waitcnt vmcnt(16)
	ds_write2_b32 v60, v110, v111 offset0:140 offset1:206
	v_add_u32_e32 v56, 0x840, v56
	v_add_u32_e32 v60, 0x400, v56
	s_waitcnt vmcnt(14)
	ds_write2_b32 v56, v112, v113 offset1:66
	s_waitcnt vmcnt(12)
	ds_write2_b32 v56, v114, v115 offset0:132 offset1:198
	s_waitcnt vmcnt(10)
	ds_write2_b32 v60, v116, v117 offset0:8 offset1:74
	s_waitcnt vmcnt(8)
	ds_write2_b32 v60, v118, v119 offset0:140 offset1:206
	v_add_u32_e32 v56, 0x840, v56
	v_add_u32_e32 v60, 0x400, v56
	s_waitcnt vmcnt(6)
	ds_write2_b32 v56, v120, v121 offset1:66
	s_waitcnt vmcnt(4)
	ds_write2_b32 v56, v122, v123 offset0:132 offset1:198
	s_waitcnt vmcnt(2)
	ds_write2_b32 v60, v124, v125 offset0:8 offset1:74
	s_waitcnt vmcnt(0)
	ds_write2_b32 v60, v126, v127 offset0:140 offset1:206
	v_add_u32_e32 v56, 0x840, v56
	s_waitcnt lgkmcnt(0)
	ds_read2_b32 v[24:25], v36 offset0:33 offset1:41
	ds_read2_b32 v[26:27], v36 offset1:8
	s_add_i32 s4, s9, 0xe800
	s_lshl_b32 s5, s9, 5
	ds_read2_b32 v[28:29], v36 offset0:66 offset1:74
	ds_read2_b32 v[30:31], v36 offset0:99 offset1:107
	ds_read2_b32 v[32:33], v36 offset0:132 offset1:140
	ds_read2_b32 v[56:57], v36 offset0:165 offset1:173
	ds_read2_b32 v[58:59], v36 offset0:198 offset1:206
	ds_read2_b32 v[60:61], v36 offset0:231 offset1:239
	s_and_b32 s4, s4, 0xffc0
	s_and_b32 s5, s5, 0x7e0
	s_lshl_b32 s76, s4, 1
	s_waitcnt lgkmcnt(6)
	v_cvt_pk_bf16_f32 v18, v26, v24
	v_or_b32_e32 v24, s5, v35
	v_lshl_add_u64 v[22:23], v[14:15], 0, s[76:77]
	v_lshlrev_b32_e32 v144, 12, v24
	v_or_b32_e32 v24, s5, v37
	v_lshl_add_u64 v[62:63], v[22:23], 0, v[144:145]
	v_lshlrev_b32_e32 v144, 12, v24
	s_waitcnt lgkmcnt(4)
	v_cvt_pk_bf16_f32 v19, v28, v30
	s_waitcnt lgkmcnt(2)
	v_cvt_pk_bf16_f32 v20, v32, v56
	s_waitcnt lgkmcnt(0)
	v_cvt_pk_bf16_f32 v21, v58, v60
	global_store_dwordx4 v[62:63], v[18:21], off
	s_nop 1
	v_cvt_pk_bf16_f32 v18, v27, v25
	v_lshl_add_u64 v[24:25], v[22:23], 0, v[144:145]
	v_cvt_pk_bf16_f32 v19, v29, v31
	v_cvt_pk_bf16_f32 v20, v33, v57
	v_cvt_pk_bf16_f32 v21, v59, v61
	global_store_dwordx4 v[24:25], v[18:21], off
	ds_read2_b32 v[24:25], v36 offset0:16 offset1:24
	ds_read2_b32 v[26:27], v36 offset0:49 offset1:57
	ds_read2_b32 v[28:29], v36 offset0:82 offset1:90
	ds_read2_b32 v[30:31], v36 offset0:115 offset1:123
	ds_read2_b32 v[32:33], v36 offset0:148 offset1:156
	ds_read2_b32 v[56:57], v36 offset0:181 offset1:189
	ds_read2_b32 v[58:59], v36 offset0:214 offset1:222
	ds_read2_b32 v[60:61], v36 offset0:247 offset1:255
	s_waitcnt lgkmcnt(6)
	v_cvt_pk_bf16_f32 v18, v24, v26
	v_or_b32_e32 v24, s5, v38
	v_lshlrev_b32_e32 v144, 12, v24
	v_or_b32_e32 v24, s5, v39
	v_lshl_add_u64 v[62:63], v[22:23], 0, v[144:145]
	v_lshlrev_b32_e32 v144, 12, v24
	s_waitcnt lgkmcnt(4)
	v_cvt_pk_bf16_f32 v19, v28, v30
	s_waitcnt lgkmcnt(2)
	v_cvt_pk_bf16_f32 v20, v32, v56
	s_waitcnt lgkmcnt(0)
	v_cvt_pk_bf16_f32 v21, v58, v60
	v_lshl_add_u64 v[22:23], v[22:23], 0, v[144:145]
	global_store_dwordx4 v[62:63], v[18:21], off
	s_nop 1
	v_cvt_pk_bf16_f32 v18, v25, v27
	v_cvt_pk_bf16_f32 v19, v29, v31
	v_cvt_pk_bf16_f32 v20, v33, v57
	v_cvt_pk_bf16_f32 v21, v59, v61
	global_store_dwordx4 v[22:23], v[18:21], off
	s_waitcnt lgkmcnt(0)

.LBB0_872:
	v_lshl_add_u64 v[58:59], v[32:33], 0, s[6:7]
	global_load_dword v64, v[58:59], off nt
	v_lshl_add_u64 v[58:59], v[30:31], 0, s[6:7]
	global_load_dword v65, v[58:59], off nt
	v_lshl_add_u64 v[58:59], v[28:29], 0, s[6:7]
	global_load_dword v66, v[58:59], off nt
	v_lshl_add_u64 v[58:59], v[26:27], 0, s[6:7]
	global_load_dword v67, v[58:59], off nt
	v_lshl_add_u64 v[58:59], v[24:25], 0, s[6:7]
	global_load_dword v100, v[58:59], off nt
	v_lshl_add_u64 v[58:59], v[22:23], 0, s[6:7]
	global_load_dword v101, v[58:59], off nt
	v_lshl_add_u64 v[58:59], v[20:21], 0, s[6:7]
	global_load_dword v102, v[58:59], off nt
	v_lshl_add_u64 v[58:59], v[18:19], 0, s[6:7]
	global_load_dword v103, v[58:59], off nt
	s_add_u32 s6, s6, 0x60000
	s_addc_u32 s7, s7, 0
	v_lshl_add_u64 v[58:59], v[32:33], 0, s[6:7]
	global_load_dword v104, v[58:59], off nt
	v_lshl_add_u64 v[58:59], v[30:31], 0, s[6:7]
	global_load_dword v105, v[58:59], off nt
	v_lshl_add_u64 v[58:59], v[28:29], 0, s[6:7]
	global_load_dword v106, v[58:59], off nt
	v_lshl_add_u64 v[58:59], v[26:27], 0, s[6:7]
	global_load_dword v107, v[58:59], off nt
	v_lshl_add_u64 v[58:59], v[24:25], 0, s[6:7]
	global_load_dword v108, v[58:59], off nt
	v_lshl_add_u64 v[58:59], v[22:23], 0, s[6:7]
	global_load_dword v109, v[58:59], off nt
	v_lshl_add_u64 v[58:59], v[20:21], 0, s[6:7]
	global_load_dword v110, v[58:59], off nt
	v_lshl_add_u64 v[58:59], v[18:19], 0, s[6:7]
	global_load_dword v111, v[58:59], off nt
	s_add_u32 s6, s6, 0x60000
	s_addc_u32 s7, s7, 0
	v_lshl_add_u64 v[58:59], v[32:33], 0, s[6:7]
	global_load_dword v112, v[58:59], off nt
	v_lshl_add_u64 v[58:59], v[30:31], 0, s[6:7]
	global_load_dword v113, v[58:59], off nt
	v_lshl_add_u64 v[58:59], v[28:29], 0, s[6:7]
	global_load_dword v114, v[58:59], off nt
	v_lshl_add_u64 v[58:59], v[26:27], 0, s[6:7]
	global_load_dword v115, v[58:59], off nt
	v_lshl_add_u64 v[58:59], v[24:25], 0, s[6:7]
	global_load_dword v116, v[58:59], off nt
	v_lshl_add_u64 v[58:59], v[22:23], 0, s[6:7]
	global_load_dword v117, v[58:59], off nt
	v_lshl_add_u64 v[58:59], v[20:21], 0, s[6:7]
	global_load_dword v118, v[58:59], off nt
	v_lshl_add_u64 v[58:59], v[18:19], 0, s[6:7]
	global_load_dword v119, v[58:59], off nt
	s_add_u32 s6, s6, 0x60000
	s_addc_u32 s7, s7, 0
	v_lshl_add_u64 v[58:59], v[32:33], 0, s[6:7]
	global_load_dword v120, v[58:59], off nt
	v_lshl_add_u64 v[58:59], v[30:31], 0, s[6:7]
	global_load_dword v121, v[58:59], off nt
	v_lshl_add_u64 v[58:59], v[28:29], 0, s[6:7]
	global_load_dword v122, v[58:59], off nt
	v_lshl_add_u64 v[58:59], v[26:27], 0, s[6:7]
	global_load_dword v123, v[58:59], off nt
	v_lshl_add_u64 v[58:59], v[24:25], 0, s[6:7]
	global_load_dword v124, v[58:59], off nt
	v_lshl_add_u64 v[58:59], v[22:23], 0, s[6:7]
	global_load_dword v125, v[58:59], off nt
	v_lshl_add_u64 v[58:59], v[20:21], 0, s[6:7]
	global_load_dword v126, v[58:59], off nt
	v_lshl_add_u64 v[58:59], v[18:19], 0, s[6:7]
	global_load_dword v127, v[58:59], off nt
	s_add_u32 s6, s6, 0x60000
	s_addc_u32 s7, s7, 0
	v_add_u32_e32 v60, 0x400, v56
	s_waitcnt vmcnt(30)
	ds_write2_b32 v56, v64, v65 offset1:66
	s_waitcnt vmcnt(28)
	ds_write2_b32 v56, v66, v67 offset0:132 offset1:198
	s_waitcnt vmcnt(26)
	ds_write2_b32 v60, v100, v101 offset0:8 offset1:74
	s_waitcnt vmcnt(24)
	ds_write2_b32 v60, v102, v103 offset0:140 offset1:206
	v_add_u32_e32 v56, 0x840, v56
	v_add_u32_e32 v60, 0x400, v56
	s_waitcnt vmcnt(22)
	ds_write2_b32 v56, v104, v105 offset1:66
	s_waitcnt vmcnt(20)
	ds_write2_b32 v56, v106, v107 offset0:132 offset1:198
	s_waitcnt vmcnt(18)
	ds_write2_b32 v60, v108, v109 offset0:8 offset1:74
	s_waitcnt vmcnt(16)
	ds_write2_b32 v60, v110, v111 offset0:140 offset1:206
	v_add_u32_e32 v56, 0x840, v56
	v_add_u32_e32 v60, 0x400, v56
	s_waitcnt vmcnt(14)
	ds_write2_b32 v56, v112, v113 offset1:66
	s_waitcnt vmcnt(12)
	ds_write2_b32 v56, v114, v115 offset0:132 offset1:198
	s_waitcnt vmcnt(10)
	ds_write2_b32 v60, v116, v117 offset0:8 offset1:74
	s_waitcnt vmcnt(8)
	ds_write2_b32 v60, v118, v119 offset0:140 offset1:206
	v_add_u32_e32 v56, 0x840, v56
	v_add_u32_e32 v60, 0x400, v56
	s_waitcnt vmcnt(6)
	ds_write2_b32 v56, v120, v121 offset1:66
	s_waitcnt vmcnt(4)
	ds_write2_b32 v56, v122, v123 offset0:132 offset1:198
	s_waitcnt vmcnt(2)
	ds_write2_b32 v60, v124, v125 offset0:8 offset1:74
	s_waitcnt vmcnt(0)
	ds_write2_b32 v60, v126, v127 offset0:140 offset1:206
	v_add_u32_e32 v56, 0x840, v56
	s_waitcnt lgkmcnt(0)
	ds_read2_b32 v[24:25], v36 offset0:33 offset1:41
	ds_read2_b32 v[26:27], v36 offset1:8
	ds_read2_b32 v[28:29], v36 offset0:66 offset1:74
	ds_read2_b32 v[30:31], v36 offset0:99 offset1:107
	ds_read2_b32 v[32:33], v36 offset0:132 offset1:140
	ds_read2_b32 v[56:57], v36 offset0:165 offset1:173
	ds_read2_b32 v[58:59], v36 offset0:198 offset1:206
	ds_read2_b32 v[60:61], v36 offset0:231 offset1:239
	v_add_u32_e32 v62, s12, v35
	s_ashr_i32 s5, s4, 31
	v_ashrrev_i32_e32 v63, 31, v62
	v_lshl_add_u64 v[22:23], s[4:5], 1, v[0:1]
	v_lshlrev_b64 v[62:63], 12, v[62:63]
	s_waitcnt lgkmcnt(6)
	v_cvt_pk_bf16_f32 v18, v26, v24
	v_lshl_add_u64 v[62:63], v[22:23], 0, v[62:63]
	v_add_u32_e32 v24, s12, v37
	s_waitcnt lgkmcnt(4)
	v_cvt_pk_bf16_f32 v19, v28, v30
	s_waitcnt lgkmcnt(2)
	v_cvt_pk_bf16_f32 v20, v32, v56
	s_waitcnt lgkmcnt(0)
	v_cvt_pk_bf16_f32 v21, v58, v60
	global_store_dwordx4 v[62:63], v[18:21], off
	v_add_u32_e32 v62, s12, v38
	v_ashrrev_i32_e32 v63, 31, v62
	v_cvt_pk_bf16_f32 v18, v27, v25
	v_ashrrev_i32_e32 v25, 31, v24
	v_lshlrev_b64 v[24:25], 12, v[24:25]
	v_lshl_add_u64 v[24:25], v[22:23], 0, v[24:25]
	v_cvt_pk_bf16_f32 v19, v29, v31
	v_cvt_pk_bf16_f32 v20, v33, v57
	v_cvt_pk_bf16_f32 v21, v59, v61
	global_store_dwordx4 v[24:25], v[18:21], off
	ds_read2_b32 v[24:25], v36 offset0:16 offset1:24
	ds_read2_b32 v[26:27], v36 offset0:49 offset1:57
	ds_read2_b32 v[28:29], v36 offset0:82 offset1:90
	ds_read2_b32 v[30:31], v36 offset0:115 offset1:123
	ds_read2_b32 v[32:33], v36 offset0:148 offset1:156
	ds_read2_b32 v[56:57], v36 offset0:181 offset1:189
	ds_read2_b32 v[58:59], v36 offset0:214 offset1:222
	ds_read2_b32 v[60:61], v36 offset0:247 offset1:255
	v_lshlrev_b64 v[62:63], 12, v[62:63]
	s_waitcnt lgkmcnt(6)
	v_cvt_pk_bf16_f32 v18, v24, v26
	v_lshl_add_u64 v[62:63], v[22:23], 0, v[62:63]
	v_add_u32_e32 v24, s12, v39
	s_waitcnt lgkmcnt(4)
	v_cvt_pk_bf16_f32 v19, v28, v30
	s_waitcnt lgkmcnt(2)
	v_cvt_pk_bf16_f32 v20, v32, v56
	s_waitcnt lgkmcnt(0)
	v_cvt_pk_bf16_f32 v21, v58, v60
	global_store_dwordx4 v[62:63], v[18:21], off
	s_nop 1
	v_cvt_pk_bf16_f32 v18, v25, v27
	v_ashrrev_i32_e32 v25, 31, v24
	v_lshlrev_b64 v[24:25], 12, v[24:25]
	v_lshl_add_u64 v[22:23], v[22:23], 0, v[24:25]
	v_cvt_pk_bf16_f32 v19, v29, v31
	v_cvt_pk_bf16_f32 v20, v33, v57
	v_cvt_pk_bf16_f32 v21, v59, v61
	global_store_dwordx4 v[22:23], v[18:21], off
	s_waitcnt lgkmcnt(0)
	s_branch .LBB0_813
